# attention: coalesced LDS-DMA layout + half-tile stagger + V reads early; P7 epilogue rstd precompute; G2 exp(g_last) load ahead of DMA; G1 conv weights loaded once
# speedup vs baseline: 1.0668x; 1.0141x over previous
.LBB0_19:
	s_load_dwordx16 s[52:67], s[0:1], 0x40
	s_waitcnt lgkmcnt(0)
	v_mbcnt_lo_u32_b32 v252, -1, 0
	v_mbcnt_hi_u32_b32 v252, -1, v252
	v_lshlrev_b32_e32 v252, 2, v252
	global_load_dword v253, v252, s[90:91]
	global_load_dword v254, v252, s[52:53]
	s_waitcnt vmcnt(0)
	v_mul_f32_e32 v253, v253, v254
	v_and_b32_e32 v253, 0x7fffffff, v253
	v_xor_b32_e32 v254, 4, v252
	ds_bpermute_b32 v255, v254, v253
	s_waitcnt lgkmcnt(0)
	v_max_f32_e32 v253, v253, v255
	v_xor_b32_e32 v254, 8, v252
	ds_bpermute_b32 v255, v254, v253
	s_waitcnt lgkmcnt(0)
	v_max_f32_e32 v253, v253, v255
	v_xor_b32_e32 v254, 16, v252
	ds_bpermute_b32 v255, v254, v253
	s_waitcnt lgkmcnt(0)
	v_max_f32_e32 v253, v253, v255
	v_xor_b32_e32 v254, 32, v252
	ds_bpermute_b32 v255, v254, v253
	s_waitcnt lgkmcnt(0)
	v_max_f32_e32 v253, v253, v255
	v_xor_b32_e32 v254, 64, v252
	ds_bpermute_b32 v255, v254, v253
	s_waitcnt lgkmcnt(0)
	v_max_f32_e32 v253, v253, v255
	v_xor_b32_e32 v254, 128, v252
	ds_bpermute_b32 v255, v254, v253
	s_waitcnt lgkmcnt(0)
	v_max_f32_e32 v253, v253, v255
	v_mul_f32_e32 v253, 0x4138aa3b, v253
	v_add_f32_e32 v253, 1.0, v253
	v_xor_b32_e32 v247, 0x80000000, v253
	s_and_b32 s0, s14, 0xffffffc0
	s_add_u32 s16, s92, 0x800000
	s_addc_u32 s17, s93, 0
	s_cmp_lt_i32 s94, 1
	s_cselect_b64 s[18:19], -1, 0
	s_cmp_gt_i32 s95, 0
	v_writelane_b32 v245, s0, 0
	s_cselect_b64 s[0:1], -1, 0
	s_and_b64 s[0:1], s[18:19], s[0:1]
	s_lshl_b32 s28, s22, 3
	s_add_u32 s4, s92, 0x2700000
	s_addc_u32 s5, s93, 0
	v_writelane_b32 v245, s4, 1
	v_mbcnt_lo_u32_b32 v192, -1, 0
	s_nop 0
	v_writelane_b32 v245, s5, 2
	s_add_u32 s4, s92, 0x1c00000
	s_addc_u32 s5, s93, 0
	v_writelane_b32 v245, s4, 3
	s_nop 1
	v_writelane_b32 v245, s5, 4
	s_add_u32 s4, s92, 0x1a00000
	s_addc_u32 s5, s93, 0
	v_writelane_b32 v245, s4, 5
	s_andn2_b64 vcc, exec, s[0:1]
	s_nop 0
	v_writelane_b32 v245, s5, 6
	v_writelane_b32 v245, s22, 7
	s_nop 1
	v_writelane_b32 v245, s23, 8
	s_cbranch_vccnz .LBB0_95
	v_mbcnt_hi_u32_b32 v36, -1, v192
	v_readlane_b32 s0, v245, 0
	s_lshl_b32 s3, s3, 3
	s_mov_b32 s5, 0
	v_add_u32_e32 v33, s0, v36
	s_nop 0
	v_readfirstlane_b32 s0, v33
	s_ashr_i32 s15, s0, 6
	v_and_b32_e32 v37, 63, v33
	s_add_i32 s24, s15, s3
	s_cmpk_gt_i32 s24, 0x247f
	v_lshlrev_b32_e32 v32, 3, v37
	s_cbranch_scc1 .LBB0_79
	s_waitcnt lgkmcnt(0)
	s_cmp_lg_u64 s[66:67], 0
	s_mul_i32 s0, s15, 0x2200
	s_cselect_b64 s[6:7], -1, 0
	s_add_i32 s0, s0, 0
	v_lshrrev_b32_e32 v38, 5, v37
	v_and_b32_e32 v16, 31, v33
	s_add_i32 s0, s0, 0x10000
	v_mul_u32_u24_e32 v0, 0x84, v38
	v_lshlrev_b32_e32 v14, 2, v16
	v_add3_u32 v39, s0, v0, v14
	v_lshrrev_b32_e32 v40, 3, v37
	v_and_b32_e32 v0, 56, v32
	v_mul_u32_u24_e32 v4, 0x84, v0
	v_lshlrev_b32_e32 v5, 2, v40
	v_add3_u32 v41, s0, v4, v5
	v_or_b32_e32 v4, 2, v38
	v_mul_u32_u24_e32 v4, 0x84, v4
	v_add3_u32 v45, s0, v4, v14
	v_readlane_b32 s0, v245, 3
	v_mov_b32_e32 v1, 0
	v_lshlrev_b32_e32 v0, 1, v0
	v_readlane_b32 s1, v245, 4
	v_readlane_b32 s8, v245, 1
	v_readlane_b32 s9, v245, 2
	v_lshl_add_u64 v[4:5], s[0:1], 0, v[0:1]
	v_readlane_b32 s0, v245, 5
	v_readlane_b32 s1, v245, 6
	v_mov_b32_e32 v15, v1
	v_lshl_add_u64 v[2:3], s[8:9], 0, v[0:1]
	v_lshl_add_u64 v[6:7], s[0:1], 0, v[0:1]
	s_lshl_b32 s0, s24, 5
	v_or_b32_e32 v42, 8, v40
	v_or_b32_e32 v43, 16, v40
	v_or_b32_e32 v44, 24, v40
	v_add_u32_e32 v46, 0x108, v45
	v_add_u32_e32 v47, 0x210, v45
	v_add_u32_e32 v48, 0x318, v45
	v_add_u32_e32 v49, 0x420, v45
	v_add_u32_e32 v50, 0x528, v45
	v_add_u32_e32 v51, 0x630, v45
	v_add_u32_e32 v52, 0x738, v45
	v_add_u32_e32 v53, 0x840, v45
	v_add_u32_e32 v54, 0x948, v45
	v_add_u32_e32 v55, 0xa50, v45
	v_add_u32_e32 v56, 0xb58, v45
	v_add_u32_e32 v57, 0xc60, v45
	v_add_u32_e32 v58, 0xd68, v45
	v_add_u32_e32 v59, 0xe70, v45
	v_add_u32_e32 v60, 0xf78, v45
	v_add_u32_e32 v61, 0x1080, v45
	v_add_u32_e32 v62, 0x1188, v45
	v_add_u32_e32 v63, 0x1290, v45
	v_add_u32_e32 v64, 0x1398, v45
	v_add_u32_e32 v65, 0x14a0, v45
	v_add_u32_e32 v66, 0x15a8, v45
	v_add_u32_e32 v67, 0x16b0, v45
	v_add_u32_e32 v68, 0x17b8, v45
	v_add_u32_e32 v69, 0x18c0, v45
	v_add_u32_e32 v70, 0x19c8, v45
	v_add_u32_e32 v71, 0x1ad0, v45
	v_add_u32_e32 v72, 0x1bd8, v45
	v_add_u32_e32 v73, 0x1ce0, v45
	v_add_u32_e32 v74, 0x1de8, v45
	v_add_u32_e32 v75, 0x1ef0, v45
	v_lshl_add_u64 v[8:9], s[16:17], 0, v[0:1]
	v_lshl_add_u64 v[10:11], s[72:73], 0, v[14:15]
	v_lshl_add_u64 v[12:13], s[64:65], 0, v[14:15]
	v_lshl_add_u64 v[14:15], s[80:81], 0, v[14:15]
	s_add_i32 s10, s0, 0xfffff810
	s_lshl_b32 s11, s28, 5
	s_lshl_b32 s12, s24, 6
	s_lshl_b32 s13, s28, 6
	s_lshl_b32 s20, s24, 1
	s_lshl_b32 s21, s28, 1
	v_lshlrev_b32_e32 v0, 2, v16
	s_mov_b32 s22, 0x2c000
	s_mov_b32 s23, 0x31000
	s_mov_b32 s25, 0x37000
	s_mov_b32 s26, 0x3c000
	s_mov_b32 s27, 0x42000
	s_mov_b32 s29, 0x47000
	s_mov_b32 s30, 0x4d000
	s_mov_b32 s31, 0x52000
	s_mov_b32 s34, 0x58000
	s_mov_b32 s35, 0x5d000
	s_mov_b32 s36, 0x63000
	s_mov_b32 s37, 0x68000
	s_mov_b32 s38, 0x6e000
	s_mov_b32 s39, 0x73000
	s_mov_b32 s40, 0x79000
	s_mov_b32 s41, 0x7e000
	s_mov_b32 s42, 0x84000
	s_mov_b32 s43, 0x89000
	s_mov_b32 s44, 0x8f000
	s_mov_b32 s45, 0x94000
	s_mov_b32 s46, 0x9a000
	s_movk_i32 s47, 0x1010
	s_mov_b32 s48, 0x9040
	s_mov_b32 s49, s24
	s_branch .LBB0_25

.LBB0_282:
	s_andn2_b64 vcc, exec, s[0:1]
	s_cbranch_vccnz .LBB0_495
	s_ashr_i32 s0, s14, 6
	v_writelane_b32 v244, s36, 2
	s_add_u32 s4, s92, 0x180000
	s_addc_u32 s5, s93, 0
	v_writelane_b32 v244, s37, 3
	v_writelane_b32 v244, s4, 4
	v_and_b32_e32 v44, 64, v46
	v_add_u32_e32 v45, -1, v46
	v_writelane_b32 v244, s5, 5
	s_add_u32 s4, s92, 0x100000
	s_addc_u32 s5, s93, 0
	v_writelane_b32 v244, s4, 6
	s_cmp_eq_u32 s0, 7
	v_cmp_lt_i32_e32 vcc, v45, v44
	v_writelane_b32 v244, s5, 7
	s_cselect_b64 s[4:5], -1, 0
	s_and_b32 s1, s0, 3
	v_writelane_b32 v244, s4, 8
	s_cmp_gt_u32 s0, 3
	v_cndmask_b32_e32 v45, v45, v46, vcc
	v_writelane_b32 v244, s5, 9
	s_cselect_b64 s[64:65], -1, 0
	s_add_i32 s4, 0, 0x4000
	v_lshlrev_b32_e32 v194, 2, v45
	v_add_u32_e32 v45, -2, v46
	s_cmp_lt_u32 s0, 4
	v_cmp_lt_i32_e32 vcc, v45, v44
	v_writelane_b32 v244, s4, 10
	s_cselect_b32 s29, s4, 0
	s_lshl_b32 s4, s1, 8
	v_cndmask_b32_e32 v45, v45, v46, vcc
	s_cmp_eq_u32 s1, 0
	v_lshlrev_b32_e32 v195, 2, v45
	v_add_u32_e32 v45, -4, v46
	s_cselect_b64 s[68:69], -1, 0
	s_cmp_lg_u32 s1, 0
	v_cmp_lt_i32_e32 vcc, v45, v44
	s_cselect_b64 s[70:71], -1, 0
	s_cmp_lt_u32 s1, 2
	v_cndmask_b32_e32 v45, v45, v46, vcc
	s_cselect_b64 s[72:73], -1, 0
	s_cmp_gt_u32 s1, 1
	v_lshlrev_b32_e32 v196, 2, v45
	v_add_u32_e32 v45, -8, v46
	s_cselect_b64 s[86:87], -1, 0
	s_cmp_lg_u32 s1, 3
	v_cmp_lt_i32_e32 vcc, v45, v44
	s_cselect_b64 s[6:7], -1, 0
	s_cmp_eq_u32 s1, 3
	v_cndmask_b32_e32 v45, v45, v46, vcc
	v_writelane_b32 v244, s4, 11
	s_cselect_b64 s[4:5], -1, 0
	s_lshl_b32 s8, s1, 4
	v_lshlrev_b32_e32 v197, 2, v45
	v_add_u32_e32 v45, -16, v46
	v_writelane_b32 v244, s8, 13
	s_lshl_b32 s8, s1, 6
	v_cmp_lt_i32_e32 vcc, v45, v44
	s_add_i32 s8, s8, 0
	s_add_i32 s9, s8, 0x1f400
	v_cndmask_b32_e32 v45, v45, v46, vcc
	s_add_i32 s8, s8, 0x1f600
	v_lshlrev_b32_e32 v198, 2, v45
	v_subrev_u32_e32 v45, 32, v46
	v_writelane_b32 v244, s9, 15
	s_cmp_eq_u32 s1, 1
	v_cmp_lt_i32_e32 vcc, v45, v44
	v_writelane_b32 v244, s8, 16
	s_cselect_b64 s[8:9], -1, 0
	v_cndmask_b32_e32 v45, v45, v46, vcc
	v_writelane_b32 v244, s8, 17
	s_cmp_eq_u32 s1, 2
	v_lshlrev_b32_e32 v199, 2, v45
	v_bfrev_b32_e32 v45, 0.5
	v_writelane_b32 v244, s9, 18
	s_cselect_b64 s[8:9], -1, 0
	s_cmp_lt_i32 s0, 4
	v_lshl_or_b32 v200, v46, 2, v45
	v_xor_b32_e32 v45, 1, v46
	v_add_u32_e32 v44, 64, v44
	s_cselect_b64 s[12:13], -1, 0
	s_lshl_b32 s1, s0, 12
	v_cmp_lt_i32_e32 vcc, v45, v44
	s_add_i32 s1, s1, 0
	s_andn2_b32 s14, s14, 63
	v_cndmask_b32_e32 v45, v46, v45, vcc
	v_writelane_b32 v244, s8, 19
	s_add_i32 s1, s1, s14
	v_lshlrev_b32_e32 v201, 2, v45
	v_xor_b32_e32 v45, 2, v46
	v_writelane_b32 v244, s9, 20
	s_add_i32 s1, s1, 0x19000
	v_cmp_lt_i32_e32 vcc, v45, v44
	v_writelane_b32 v244, s1, 21
	s_lshl_b32 s1, s0, 9
	v_cndmask_b32_e32 v45, v46, v45, vcc
	s_add_i32 s1, s1, 0
	v_lshlrev_b32_e32 v202, 2, v45
	v_xor_b32_e32 v45, 4, v46
	s_add_i32 s1, s1, 0x21c00
	v_cmp_lt_i32_e32 vcc, v45, v44
	v_writelane_b32 v244, s1, 22
	s_lshl_b32 s1, s0, 5
	v_cndmask_b32_e32 v45, v46, v45, vcc
	s_add_i32 s21, s1, 0
	s_lshl_b32 s23, s0, 8
	s_lshl_b64 s[0:1], s[2:3], 2
	v_lshlrev_b32_e32 v203, 2, v45
	v_xor_b32_e32 v45, 8, v46
	s_add_u32 s34, s0, 0x80000
	v_cmp_lt_i32_e32 vcc, v45, v44
	s_addc_u32 s35, s1, 0
	s_lshl_b64 s[78:79], s[84:85], 2
	s_lshl_b64 s[0:1], s[2:3], 13
	v_cndmask_b32_e32 v44, v46, v45, vcc
	s_add_u32 s36, s0, 0xcd00000
	v_lshlrev_b32_e32 v204, 2, v44
	s_mov_b32 s67, 0
	s_addc_u32 s37, s1, 0
	s_lshl_b64 s[16:17], s[84:85], 13
	s_lshl_b64 s[18:19], s[84:85], 14
	s_lshl_b32 s22, s2, 3
	v_mov_b32_e32 v45, 0
	s_movk_i32 s50, 0x210
	s_add_i32 s51, 0, 0x10400
	s_movk_i32 s33, 0x110
	s_add_i32 s14, 0, 0x14800
	s_add_i32 s15, 0, 0x1d000
	s_add_i32 s20, 0, 0x1f800
	s_movk_i32 s0, 0x90
	s_mov_b32 s1, 0xdd00000
	s_mov_b32 s96, 0xffffff0
	v_mov_b32_e32 v205, 0x3db504f3
	v_mov_b32_e32 v206, 0x100
	v_mov_b32_e32 v207, 0xad00000
	v_mov_b32_e32 v208, 0x8d00000
	v_mov_b32_e32 v209, 0x6d00000
	s_mov_b32 s97, s2
	v_ashrrev_i32_e32 v217, 7, v193
	v_and_b32_e32 v242, 15, v193
	s_and_b32 s38, s2, 7
	s_lshl_b32 s38, s38, 9
	v_cmp_gt_i32_e32 vcc, 3, v217
	s_and_saveexec_b64 s[40:41], vcc
	v_lshlrev_b32_e32 v217, 12, v217
	v_lshl_add_u32 v217, v242, 5, v217
	v_add_u32_e32 v217, s38, v217
	global_load_dwordx4 v[218:221], v217, s[82:83]
	global_load_dwordx4 v[222:225], v217, s[82:83] offset:16
	v_add_u32_e32 v242, 0x3000, v217
	global_load_dwordx4 v[226:229], v242, s[82:83]
	global_load_dwordx4 v[230:233], v242, s[82:83] offset:16
	v_add_u32_e32 v242, 0x6000, v217
	global_load_dwordx4 v[234:237], v242, s[82:83]
	global_load_dwordx4 v[238:241], v242, s[82:83] offset:16
	v_add_u32_e32 v242, 0x9000, v217
	global_load_dwordx4 v[248:251], v242, s[82:83]
	global_load_dwordx4 v[252:255], v242, s[82:83] offset:16
	s_or_b64 exec, exec, s[40:41]
	s_waitcnt vmcnt(0)
	s_branch .LBB0_286

.LBB0_290:
	v_ashrrev_i32_e32 v188, 7, v210
	v_and_b32_e32 v211, 15, v210
	v_cmp_lt_i32_e32 vcc, 2, v188
	v_cmp_gt_i32_e64 s[38:39], 3, v188
	s_and_saveexec_b64 s[44:45], s[38:39]
	s_cbranch_execz .LBB0_308
	v_mov_b64_e32 v[58:59], v[218:219]
	v_mov_b64_e32 v[60:61], v[220:221]
	v_mov_b64_e32 v[46:47], v[222:223]
	v_mov_b64_e32 v[48:49], v[224:225]
	v_mov_b64_e32 v[62:63], v[226:227]
	v_mov_b64_e32 v[64:65], v[228:229]
	v_mov_b64_e32 v[50:51], v[230:231]
	v_mov_b64_e32 v[52:53], v[232:233]
	v_mov_b64_e32 v[70:71], v[234:235]
	v_mov_b64_e32 v[72:73], v[236:237]
	v_mov_b64_e32 v[54:55], v[238:239]
	v_mov_b64_e32 v[56:57], v[240:241]
	v_mov_b64_e32 v[74:75], v[248:249]
	v_mov_b64_e32 v[76:77], v[250:251]
	v_mov_b64_e32 v[66:67], v[252:253]
	v_mov_b64_e32 v[68:69], v[254:255]
	s_waitcnt vmcnt(11)
	v_lshlrev_b32_e32 v78, 16, v0
	v_and_b32_e32 v79, 0xffff0000, v0
	v_lshlrev_b32_e32 v102, 16, v4
	v_and_b32_e32 v103, 0xffff0000, v4
	v_lshlrev_b32_e32 v90, 16, v8
	v_and_b32_e32 v91, 0xffff0000, v8
	v_lshlrev_b32_e32 v100, 16, v12
	v_and_b32_e32 v101, 0xffff0000, v12
	v_lshlrev_b32_e32 v104, 16, v5
	v_and_b32_e32 v105, 0xffff0000, v5
	v_lshlrev_b32_e32 v86, 16, v9
	v_and_b32_e32 v87, 0xffff0000, v9
	v_lshlrev_b32_e32 v98, 16, v13
	v_and_b32_e32 v99, 0xffff0000, v13
	v_lshlrev_b32_e32 v106, 16, v6
	v_and_b32_e32 v107, 0xffff0000, v6
	v_lshlrev_b32_e32 v88, 16, v10
	v_and_b32_e32 v89, 0xffff0000, v10
	v_lshlrev_b32_e32 v96, 16, v14
	v_and_b32_e32 v97, 0xffff0000, v14
	v_lshlrev_b32_e32 v108, 16, v7
	v_and_b32_e32 v109, 0xffff0000, v7
	v_lshlrev_b32_e32 v92, 16, v11
	v_and_b32_e32 v93, 0xffff0000, v11
	v_lshlrev_b32_e32 v94, 16, v15
	v_and_b32_e32 v95, 0xffff0000, v15
	s_movk_i32 s8, 0x80
	v_cmp_gt_u32_e64 s[42:43], s8, v210
	v_cmp_ne_u32_e64 s[40:41], 2, v188
	v_pk_fma_f32 v[78:79], v[58:59], v[78:79], 0 op_sel_hi:[1,1,0]
	v_cndmask_b32_e64 v44, 1.0, v205, s[42:43]
	v_pk_fma_f32 v[78:79], v[62:63], v[102:103], v[78:79]
	s_nop 0
	v_pk_fma_f32 v[78:79], v[70:71], v[90:91], v[78:79]
	s_nop 0
	v_pk_fma_f32 v[78:79], v[74:75], v[100:101], v[78:79]
	s_nop 0
	v_mul_f32_e32 v80, 0xbfb8aa3b, v78
	v_mul_f32_e32 v81, 0xbfb8aa3b, v79
	v_exp_f32_e32 v80, v80
	v_exp_f32_e32 v81, v81
	v_add_f32_e32 v80, 1.0, v80
	v_add_f32_e32 v81, 1.0, v81
	v_rcp_f32_e32 v80, v80
	v_rcp_f32_e32 v81, v81
	s_nop 0
	v_pk_mul_f32 v[78:79], v[78:79], v[80:81]
	v_lshlrev_b32_e32 v80, 16, v1
	v_and_b32_e32 v81, 0xffff0000, v1
	v_pk_fma_f32 v[80:81], v[60:61], v[80:81], 0 op_sel_hi:[1,1,0]
	s_nop 0
	v_pk_fma_f32 v[80:81], v[64:65], v[104:105], v[80:81]
	s_nop 0
	v_pk_fma_f32 v[80:81], v[72:73], v[86:87], v[80:81]
	s_nop 0
	v_pk_fma_f32 v[80:81], v[76:77], v[98:99], v[80:81]
	s_nop 0
	v_mul_f32_e32 v82, 0xbfb8aa3b, v80
	v_mul_f32_e32 v83, 0xbfb8aa3b, v81
	v_exp_f32_e32 v82, v82
	v_exp_f32_e32 v83, v83
	v_add_f32_e32 v82, 1.0, v82
	v_add_f32_e32 v83, 1.0, v83
	v_rcp_f32_e32 v82, v82
	v_rcp_f32_e32 v83, v83
	s_nop 0
	v_pk_mul_f32 v[80:81], v[80:81], v[82:83]
	v_lshlrev_b32_e32 v82, 16, v2
	v_and_b32_e32 v83, 0xffff0000, v2
	v_pk_fma_f32 v[82:83], v[46:47], v[82:83], 0 op_sel_hi:[1,1,0]
	s_nop 0
	v_pk_fma_f32 v[82:83], v[50:51], v[106:107], v[82:83]
	s_nop 0
	v_pk_fma_f32 v[82:83], v[54:55], v[88:89], v[82:83]
	s_nop 0
	v_pk_fma_f32 v[82:83], v[66:67], v[96:97], v[82:83]
	s_nop 0
	v_mul_f32_e32 v84, 0xbfb8aa3b, v82
	v_mul_f32_e32 v85, 0xbfb8aa3b, v83
	v_exp_f32_e32 v84, v84
	v_exp_f32_e32 v85, v85
	v_add_f32_e32 v84, 1.0, v84
	v_add_f32_e32 v85, 1.0, v85
	v_rcp_f32_e32 v84, v84
	v_rcp_f32_e32 v85, v85
	s_nop 0
	v_pk_mul_f32 v[82:83], v[82:83], v[84:85]
	v_lshlrev_b32_e32 v84, 16, v3
	v_and_b32_e32 v85, 0xffff0000, v3
	v_pk_fma_f32 v[84:85], v[48:49], v[84:85], 0 op_sel_hi:[1,1,0]
	s_nop 0
	v_pk_fma_f32 v[84:85], v[52:53], v[108:109], v[84:85]
	s_nop 0
	v_pk_fma_f32 v[84:85], v[56:57], v[92:93], v[84:85]
	s_nop 0
	v_pk_fma_f32 v[84:85], v[68:69], v[94:95], v[84:85]
	s_nop 0
	v_mul_f32_e32 v110, 0xbfb8aa3b, v84
	v_mul_f32_e32 v111, 0xbfb8aa3b, v85
	v_exp_f32_e32 v110, v110
	v_exp_f32_e32 v111, v111
	v_add_f32_e32 v110, 1.0, v110
	v_add_f32_e32 v111, 1.0, v111
	v_rcp_f32_e32 v110, v110
	v_rcp_f32_e32 v111, v111
	s_nop 0
	v_pk_mul_f32 v[84:85], v[84:85], v[110:111]
	s_and_saveexec_b64 s[8:9], s[40:41]
	s_cbranch_execz .LBB0_293
	v_pk_mul_f32 v[110:111], v[78:79], v[78:79]
	v_pk_mul_f32 v[112:113], v[80:81], v[80:81]
	v_add_f32_e32 v110, v110, v111
	v_add_f32_e32 v110, v112, v110
	v_pk_mul_f32 v[114:115], v[82:83], v[82:83]
	v_add_f32_e32 v110, v113, v110
	v_add_f32_e32 v110, v114, v110
	v_pk_mul_f32 v[116:117], v[84:85], v[84:85]
	v_add_f32_e32 v110, v115, v110
	v_add_f32_e32 v110, v116, v110
	v_add_f32_e32 v110, v117, v110
	ds_bpermute_b32 v111, v201, v110
	s_waitcnt lgkmcnt(0)
	v_add_f32_e32 v110, v110, v111
	ds_bpermute_b32 v111, v202, v110
	s_waitcnt lgkmcnt(0)
	v_add_f32_e32 v110, v110, v111
	ds_bpermute_b32 v111, v203, v110
	s_waitcnt lgkmcnt(0)
	v_add_f32_e32 v110, v110, v111
	ds_bpermute_b32 v111, v204, v110
	s_waitcnt lgkmcnt(0)
	v_add_f32_e32 v110, v110, v111
	v_add_f32_e32 v110, 0x358637bd, v110
	v_rsq_f32_e32 v110, v110
	s_nop 0
	v_mul_f32_e32 v110, v44, v110
	v_pk_mul_f32 v[78:79], v[78:79], v[110:111] op_sel_hi:[1,0]
	v_pk_mul_f32 v[80:81], v[80:81], v[110:111] op_sel_hi:[1,0]
	v_pk_mul_f32 v[82:83], v[82:83], v[110:111] op_sel_hi:[1,0]
	v_pk_mul_f32 v[84:85], v[84:85], v[110:111] op_sel_hi:[1,0]

.LBB0_563:
	s_add_u32 s48, s92, s36
	s_addc_u32 s49, s93, s37
	global_load_dword v0, v60, s[48:49]
	v_lshl_add_u64 v[62:63], s[92:93], 0, v[46:47]
	s_mov_b32 m0, s71
	v_lshl_add_u64 v[64:65], v[62:63], 0, s[8:9]
	global_load_lds_dwordx4 v[64:65], off
	v_lshl_add_u64 v[64:65], s[92:93], 0, v[48:49]
	v_lshl_add_u64 v[66:67], v[64:65], 0, s[8:9]
	s_mov_b32 m0, s22
	v_lshl_add_u64 v[2:3], s[92:93], 0, v[44:45]
	global_load_lds_dwordx4 v[66:67], off
	v_lshl_add_u64 v[66:67], v[62:63], 0, s[10:11]
	s_mov_b32 m0, s23
	v_lshl_add_u64 v[62:63], v[62:63], 0, s[12:13]
	global_load_lds_dwordx4 v[66:67], off
	v_lshl_add_u64 v[66:67], v[64:65], 0, s[10:11]
	s_mov_b32 m0, s33
	v_cmp_ne_u32_e64 s[42:43], 1, v59
	global_load_lds_dwordx4 v[66:67], off
	s_mov_b32 m0, s50
	s_andn2_b64 vcc, exec, s[6:7]
	global_load_lds_dwordx4 v[62:63], off
	v_lshl_add_u64 v[62:63], v[64:65], 0, s[12:13]
	s_mov_b32 m0, s51
	s_nop 0
	global_load_lds_dwordx4 v[62:63], off
	s_mov_b32 m0, s64
	s_nop 0
	global_load_lds_dwordx4 v[2:3], off
	s_cbranch_vccnz .LBB0_565
	v_mov_b32_e32 v61, v58
	v_cvt_pk_bf16_f32 v62, v32, v33
	v_lshl_add_u32 v170, v61, 4, 0
	ds_read_b128 v[78:81], v170
	ds_read_b128 v[82:85], v170 offset:4096
	ds_read_b128 v[86:89], v170 offset:16384
	ds_read_b128 v[90:93], v170 offset:20480
	ds_read_b128 v[94:97], v170 offset:8192
	ds_read_b128 v[98:101], v170 offset:12288
	ds_read_b128 v[102:105], v170 offset:24576
	ds_read_b128 v[106:109], v170 offset:28672
	v_cvt_pk_bf16_f32 v63, v34, v35
	v_cvt_pk_bf16_f32 v64, v28, v29
	v_cvt_pk_bf16_f32 v65, v30, v31
	v_cvt_pk_bf16_f32 v66, v24, v25
	v_cvt_pk_bf16_f32 v67, v26, v27
	v_cvt_pk_bf16_f32 v68, v20, v21
	v_cvt_pk_bf16_f32 v69, v22, v23
	v_cvt_pk_bf16_f32 v70, v16, v17
	v_cvt_pk_bf16_f32 v71, v18, v19
	v_cvt_pk_bf16_f32 v72, v12, v13
	v_cvt_pk_bf16_f32 v73, v14, v15
	v_cvt_pk_bf16_f32 v74, v8, v9
	v_cvt_pk_bf16_f32 v75, v10, v11
	v_cvt_pk_bf16_f32 v76, v4, v5
	v_cvt_pk_bf16_f32 v77, v6, v7
	v_and_b32_e32 v171, 15, v61
	ds_read_b128 v[110:113], v170 offset:1024
	ds_read_b128 v[114:117], v170 offset:5120
	ds_read_b128 v[118:121], v170 offset:17408
	ds_read_b128 v[122:125], v170 offset:21504
	ds_read_b128 v[126:129], v170 offset:9216
	ds_read_b128 v[130:133], v170 offset:13312
	ds_read_b128 v[134:137], v170 offset:25600
	ds_read_b128 v[138:141], v170 offset:29696
	s_waitcnt lgkmcnt(0)
	v_mfma_f32_16x16x32_bf16 v[78:81], v[78:81], v[62:65], 0
	v_mfma_f32_16x16x32_bf16 v[86:89], v[86:89], v[62:65], 0
	v_mfma_f32_16x16x32_bf16 v[82:85], v[82:85], v[62:65], 0
	v_mfma_f32_16x16x32_bf16 v[90:93], v[90:93], v[62:65], 0
	v_mfma_f32_16x16x32_bf16 v[94:97], v[94:97], v[62:65], 0
	v_mfma_f32_16x16x32_bf16 v[102:105], v[102:105], v[62:65], 0
	v_mfma_f32_16x16x32_bf16 v[98:101], v[98:101], v[62:65], 0
	v_mfma_f32_16x16x32_bf16 v[62:65], v[106:109], v[62:65], 0
	ds_read_b128 v[106:109], v170 offset:2048
	ds_read_b128 v[142:145], v170 offset:6144
	ds_read_b128 v[146:149], v170 offset:18432
	ds_read_b128 v[150:153], v170 offset:22528
	ds_read_b128 v[154:157], v170 offset:10240
	ds_read_b128 v[158:161], v170 offset:14336
	ds_read_b128 v[162:165], v170 offset:26624
	ds_read_b128 v[166:169], v170 offset:30720
	v_mfma_f32_16x16x32_bf16 v[78:81], v[110:113], v[66:69], v[78:81]
	v_mfma_f32_16x16x32_bf16 v[86:89], v[118:121], v[66:69], v[86:89]
	v_mfma_f32_16x16x32_bf16 v[82:85], v[114:117], v[66:69], v[82:85]
	v_mfma_f32_16x16x32_bf16 v[90:93], v[122:125], v[66:69], v[90:93]
	v_mfma_f32_16x16x32_bf16 v[94:97], v[126:129], v[66:69], v[94:97]
	v_mfma_f32_16x16x32_bf16 v[102:105], v[134:137], v[66:69], v[102:105]
	v_mfma_f32_16x16x32_bf16 v[98:101], v[130:133], v[66:69], v[98:101]
	v_mfma_f32_16x16x32_bf16 v[62:65], v[138:141], v[66:69], v[62:65]
	ds_read_b128 v[66:69], v170 offset:3072
	ds_read_b128 v[110:113], v170 offset:7168
	ds_read_b128 v[114:117], v170 offset:19456
	ds_read_b128 v[118:121], v170 offset:23552
	ds_read_b128 v[122:125], v170 offset:11264
	ds_read_b128 v[126:129], v170 offset:15360
	ds_read_b128 v[130:133], v170 offset:27648
	ds_read_b128 v[134:137], v170 offset:31744
	s_waitcnt lgkmcnt(0)
	v_mfma_f32_16x16x32_bf16 v[78:81], v[106:109], v[70:73], v[78:81]
	v_mfma_f32_16x16x32_bf16 v[86:89], v[146:149], v[70:73], v[86:89]
	v_mfma_f32_16x16x32_bf16 v[82:85], v[142:145], v[70:73], v[82:85]
	v_mfma_f32_16x16x32_bf16 v[90:93], v[150:153], v[70:73], v[90:93]
	v_mfma_f32_16x16x32_bf16 v[94:97], v[154:157], v[70:73], v[94:97]
	v_mfma_f32_16x16x32_bf16 v[102:105], v[162:165], v[70:73], v[102:105]
	v_mfma_f32_16x16x32_bf16 v[98:101], v[158:161], v[70:73], v[98:101]
	v_mfma_f32_16x16x32_bf16 v[62:65], v[166:169], v[70:73], v[62:65]
	ds_read_b128 v[70:73], v170 offset:32768
	ds_read_b128 v[106:109], v170 offset:34816
	ds_read_b128 v[138:141], v170 offset:36864
	ds_read_b128 v[142:145], v170 offset:38912
	ds_read_b128 v[146:149], v170 offset:40960
	ds_read_b128 v[150:153], v170 offset:43008
	ds_read_b128 v[154:157], v170 offset:45056
	ds_read_b128 v[158:161], v170 offset:47104
	v_mfma_f32_16x16x32_bf16 v[66:69], v[66:69], v[74:77], v[78:81]
	v_mfma_f32_16x16x32_bf16 v[78:81], v[114:117], v[74:77], v[86:89]
	v_mfma_f32_16x16x32_bf16 v[82:85], v[110:113], v[74:77], v[82:85]
	v_mfma_f32_16x16x32_bf16 v[86:89], v[118:121], v[74:77], v[90:93]
	v_mfma_f32_16x16x32_bf16 v[90:93], v[122:125], v[74:77], v[94:97]
	v_mfma_f32_16x16x32_bf16 v[94:97], v[130:133], v[74:77], v[102:105]
	v_mfma_f32_16x16x32_bf16 v[98:101], v[126:129], v[74:77], v[98:101]
	v_mfma_f32_16x16x32_bf16 v[62:65], v[134:137], v[74:77], v[62:65]
	v_lshlrev_b32_e32 v2, 16, v50
	v_and_b32_e32 v3, 0xffff0000, v50
	v_lshlrev_b32_e32 v74, 16, v51
	v_and_b32_e32 v75, 0xffff0000, v51
	v_sub_f32_e32 v3, v3, v67
	v_sub_f32_e32 v2, v2, v66
	v_lshlrev_b32_e32 v66, 16, v52
	v_and_b32_e32 v67, 0xffff0000, v52
	v_sub_f32_e32 v69, v75, v69
	v_sub_f32_e32 v68, v74, v68
	v_lshlrev_b32_e32 v74, 16, v53
	v_and_b32_e32 v75, 0xffff0000, v53
	v_sub_f32_e32 v76, v67, v83
	v_sub_f32_e32 v77, v66, v82
	v_lshlrev_b32_e32 v66, 16, v54
	v_and_b32_e32 v67, 0xffff0000, v54
	v_sub_f32_e32 v75, v75, v85
	v_sub_f32_e32 v74, v74, v84
	v_lshlrev_b32_e32 v82, 16, v55
	v_and_b32_e32 v83, 0xffff0000, v55
	v_sub_f32_e32 v84, v67, v91
	v_sub_f32_e32 v85, v66, v90
	v_lshlrev_b32_e32 v66, 16, v56
	v_and_b32_e32 v67, 0xffff0000, v56
	v_lshlrev_b32_e32 v90, 16, v57
	v_and_b32_e32 v91, 0xffff0000, v57
	v_sub_f32_e32 v83, v83, v93
	v_sub_f32_e32 v82, v82, v92
	v_sub_f32_e32 v91, v91, v101
	v_sub_f32_e32 v90, v90, v100
	v_sub_f32_e32 v92, v67, v99
	v_sub_f32_e32 v93, v66, v98
	s_waitcnt vmcnt(7)
	v_pk_mul_f32 v[34:35], v[34:35], v[0:1] op_sel_hi:[1,0]
	v_pk_mul_f32 v[32:33], v[32:33], v[0:1] op_sel_hi:[1,0]
	v_pk_mul_f32 v[30:31], v[30:31], v[0:1] op_sel_hi:[1,0]
	v_pk_mul_f32 v[28:29], v[28:29], v[0:1] op_sel_hi:[1,0]
	v_pk_mul_f32 v[26:27], v[26:27], v[0:1] op_sel_hi:[1,0]
	v_pk_mul_f32 v[24:25], v[24:25], v[0:1] op_sel_hi:[1,0]
	v_pk_mul_f32 v[22:23], v[22:23], v[0:1] op_sel_hi:[1,0]
	v_pk_mul_f32 v[20:21], v[20:21], v[0:1] op_sel_hi:[1,0]
	v_pk_mul_f32 v[18:19], v[18:19], v[0:1] op_sel_hi:[1,0]
	v_pk_mul_f32 v[16:17], v[16:17], v[0:1] op_sel_hi:[1,0]
	v_pk_mul_f32 v[14:15], v[14:15], v[0:1] op_sel_hi:[1,0]
	v_pk_mul_f32 v[12:13], v[12:13], v[0:1] op_sel_hi:[1,0]
	v_pk_mul_f32 v[10:11], v[10:11], v[0:1] op_sel_hi:[1,0]
	v_pk_mul_f32 v[8:9], v[8:9], v[0:1] op_sel_hi:[1,0]
	v_pk_mul_f32 v[6:7], v[6:7], v[0:1] op_sel_hi:[1,0]
	v_pk_mul_f32 v[4:5], v[4:5], v[0:1] op_sel_hi:[1,0]
	v_cvt_pk_bf16_f32 v66, v2, v3
	v_cvt_pk_bf16_f32 v67, v68, v69
	v_cvt_pk_bf16_f32 v68, v77, v76
	v_cvt_pk_bf16_f32 v69, v74, v75
	v_cvt_pk_bf16_f32 v74, v85, v84
	v_cvt_pk_bf16_f32 v75, v82, v83
	v_cvt_pk_bf16_f32 v76, v93, v92
	v_cvt_pk_bf16_f32 v77, v90, v91
	ds_read_b128 v[82:85], v170 offset:33792
	ds_read_b128 v[90:93], v170 offset:35840
	ds_read_b128 v[98:101], v170 offset:37888
	ds_read_b128 v[102:105], v170 offset:39936
	ds_read_b128 v[110:113], v170 offset:41984
	ds_read_b128 v[114:117], v170 offset:44032
	ds_read_b128 v[118:121], v170 offset:46080
	ds_read_b128 v[122:125], v170 offset:48128
	s_waitcnt lgkmcnt(14)
	v_mfma_f32_16x16x32_bf16 v[32:35], v[70:73], v[66:69], v[32:35]
	v_mfma_f32_16x16x32_bf16 v[28:31], v[106:109], v[66:69], v[28:31]
	s_waitcnt lgkmcnt(13)
	v_mfma_f32_16x16x32_bf16 v[24:27], v[138:141], v[66:69], v[24:27]
	s_waitcnt lgkmcnt(12)
	v_mfma_f32_16x16x32_bf16 v[20:23], v[142:145], v[66:69], v[20:23]
	s_waitcnt lgkmcnt(11)
	v_mfma_f32_16x16x32_bf16 v[16:19], v[146:149], v[66:69], v[16:19]
	s_waitcnt lgkmcnt(10)
	v_mfma_f32_16x16x32_bf16 v[12:15], v[150:153], v[66:69], v[12:15]
	s_waitcnt lgkmcnt(9)
	v_mfma_f32_16x16x32_bf16 v[8:11], v[154:157], v[66:69], v[8:11]
	s_waitcnt lgkmcnt(8)
	v_mfma_f32_16x16x32_bf16 v[2:5], v[158:161], v[66:69], v[4:7]
	ds_read_b128 v[70:73], v170 offset:49152
	ds_read_b128 v[106:109], v170 offset:50176
	ds_read_b128 v[126:129], v170 offset:51200
	ds_read_b128 v[130:133], v170 offset:52224
	ds_read_b128 v[134:137], v170 offset:53248
	ds_read_b128 v[138:141], v170 offset:54272
	ds_read_b128 v[142:145], v170 offset:55296
	ds_read_b128 v[146:149], v170 offset:56320
	s_waitcnt lgkmcnt(14)
	v_mfma_f32_16x16x32_bf16 v[32:35], v[82:85], v[74:77], v[32:35]
	v_mfma_f32_16x16x32_bf16 v[28:31], v[90:93], v[74:77], v[28:31]
	s_waitcnt lgkmcnt(13)
	v_mfma_f32_16x16x32_bf16 v[24:27], v[98:101], v[74:77], v[24:27]
	s_waitcnt lgkmcnt(12)
	v_mfma_f32_16x16x32_bf16 v[20:23], v[102:105], v[74:77], v[20:23]
	s_waitcnt lgkmcnt(11)
	v_mfma_f32_16x16x32_bf16 v[16:19], v[110:113], v[74:77], v[16:19]
	s_waitcnt lgkmcnt(10)
	v_mfma_f32_16x16x32_bf16 v[12:15], v[114:117], v[74:77], v[12:15]
	s_waitcnt lgkmcnt(9)
	v_mfma_f32_16x16x32_bf16 v[8:11], v[118:121], v[74:77], v[8:11]
	s_waitcnt lgkmcnt(8)
	v_mfma_f32_16x16x32_bf16 v[4:7], v[122:125], v[74:77], v[2:5]
	s_waitcnt lgkmcnt(7)
	v_mfma_f32_16x16x32_bf16 v[70:73], v[70:73], v[66:69], v[78:81]
	s_waitcnt lgkmcnt(5)
	v_mfma_f32_16x16x32_bf16 v[78:81], v[126:129], v[66:69], v[86:89]
	s_waitcnt lgkmcnt(3)
	v_mfma_f32_16x16x32_bf16 v[82:85], v[134:137], v[66:69], v[94:97]
	s_waitcnt lgkmcnt(1)
	v_mfma_f32_16x16x32_bf16 v[62:65], v[142:145], v[66:69], v[62:65]
	v_mfma_f32_16x16x32_bf16 v[66:69], v[106:109], v[74:77], v[70:73]
	v_mfma_f32_16x16x32_bf16 v[70:73], v[130:133], v[74:77], v[78:81]
	v_mfma_f32_16x16x32_bf16 v[78:81], v[138:141], v[74:77], v[82:85]
	s_waitcnt lgkmcnt(0)
	v_mfma_f32_16x16x32_bf16 v[62:65], v[146:149], v[74:77], v[62:65]
	v_ashrrev_i32_e32 v0, 2, v61
	v_and_b32_e32 v0, -4, v0
	v_add_u32_e32 v2, s83, v0
	v_lshlrev_b32_e32 v0, 1, v171
	v_ashrrev_i32_e32 v3, 31, v2
	v_lshl_add_u64 v[74:75], s[28:29], 0, v[0:1]
	v_cvt_pk_bf16_f32 v0, v66, v67
	v_lshlrev_b64 v[66:67], 11, v[2:3]
	v_lshl_add_u64 v[66:67], v[74:75], 0, v[66:67]
	global_store_short v[66:67], v0, off
	global_store_short_d16_hi v[66:67], v0, off offset:2048
	v_add_co_u32_e32 v66, vcc, s72, v66
	v_cvt_pk_bf16_f32 v61, v68, v69
	s_nop 0
	v_addc_co_u32_e32 v67, vcc, 0, v67, vcc
	global_store_short v[66:67], v61, off
	global_store_short_d16_hi v[66:67], v61, off offset:2048
	v_add_u32_e32 v66, 16, v2
	v_ashrrev_i32_e32 v67, 31, v66
	v_lshlrev_b64 v[66:67], 11, v[66:67]
	v_cvt_pk_bf16_f32 v0, v70, v71
	v_lshl_add_u64 v[66:67], v[74:75], 0, v[66:67]
	global_store_short v[66:67], v0, off
	global_store_short_d16_hi v[66:67], v0, off offset:2048
	v_add_co_u32_e32 v66, vcc, s72, v66
	v_cvt_pk_bf16_f32 v3, v72, v73
	s_nop 0
	v_addc_co_u32_e32 v67, vcc, 0, v67, vcc
	global_store_short v[66:67], v3, off
	global_store_short_d16_hi v[66:67], v3, off offset:2048
	v_add_u32_e32 v66, 32, v2
	v_ashrrev_i32_e32 v67, 31, v66
	v_lshlrev_b64 v[66:67], 11, v[66:67]
	v_cvt_pk_bf16_f32 v0, v78, v79
	v_lshl_add_u64 v[66:67], v[74:75], 0, v[66:67]
	global_store_short v[66:67], v0, off
	global_store_short_d16_hi v[66:67], v0, off offset:2048
	v_add_co_u32_e32 v66, vcc, s72, v66
	v_cvt_pk_bf16_f32 v3, v80, v81
	s_nop 0
	v_addc_co_u32_e32 v67, vcc, 0, v67, vcc
	v_add_u32_e32 v2, 48, v2
	global_store_short v[66:67], v3, off
	global_store_short_d16_hi v[66:67], v3, off offset:2048
	v_ashrrev_i32_e32 v3, 31, v2
	v_lshlrev_b64 v[2:3], 11, v[2:3]
	v_cvt_pk_bf16_f32 v0, v62, v63
	v_lshl_add_u64 v[2:3], v[74:75], 0, v[2:3]
	global_store_short v[2:3], v0, off
	global_store_short_d16_hi v[2:3], v0, off offset:2048
	v_add_co_u32_e32 v2, vcc, 0x1000, v2
	v_cvt_pk_bf16_f32 v61, v64, v65
	s_nop 0
	v_addc_co_u32_e32 v3, vcc, 0, v3, vcc
	global_store_short v[2:3], v61, off
	global_store_short_d16_hi v[2:3], v61, off offset:2048

.LBB0_567:
	s_add_i32 s86, s19, 3
	s_waitcnt vmcnt(0)
	s_cmp_lt_u32 s86, 31
	s_cselect_b64 s[48:49], -1, 0
	s_add_u32 s96, s92, s36
	s_addc_u32 s97, s93, s37
	s_cmp_gt_u32 s86, 30
	s_waitcnt vmcnt(0) lgkmcnt(0)
	s_barrier
	global_load_dword v0, v60, s[96:97] offset:32
	s_cbranch_scc1 .LBB0_570
	s_add_i32 s86, s18, s19
	s_add_i32 s86, s86, 4
	s_ashr_i32 s87, s86, 31
	s_lshl_b64 s[86:87], s[86:87], 3
	s_or_b64 s[86:87], s[86:87], s[4:5]
	s_lshl_b64 s[96:97], s[86:87], 14
	s_add_u32 vcc_lo, s26, s96
	s_addc_u32 vcc_hi, s27, s97
	s_lshl_b64 s[86:87], s[86:87], 13
	v_lshl_add_u64 v[2:3], v[38:39], 0, s[86:87]
	s_add_u32 s86, s24, s96
	s_addc_u32 s87, s25, s97
	s_add_u32 s96, s80, s96
	s_addc_u32 s97, s81, s97
	s_mov_b32 m0, s21
	v_lshl_add_u64 v[62:63], s[96:97], 0, v[36:37]
	global_load_lds_dwordx4 v[62:63], off
	v_lshl_add_u64 v[62:63], s[96:97], 0, v[40:41]
	s_mov_b32 m0, s65
	s_nop 0
	global_load_lds_dwordx4 v[62:63], off
	v_lshl_add_u64 v[62:63], s[86:87], 0, v[36:37]
	s_mov_b32 m0, s66
	s_nop 0
	global_load_lds_dwordx4 v[62:63], off
	v_lshl_add_u64 v[62:63], s[86:87], 0, v[40:41]
	s_mov_b32 m0, s67
	s_nop 0
	global_load_lds_dwordx4 v[62:63], off
	v_lshl_add_u64 v[62:63], vcc, 0, v[36:37]
	s_mov_b32 m0, s68
	s_nop 0
	global_load_lds_dwordx4 v[62:63], off
	v_lshl_add_u64 v[62:63], vcc, 0, v[40:41]
	s_mov_b32 m0, s69
	s_nop 0
	global_load_lds_dwordx4 v[62:63], off
	s_mov_b32 m0, s70
	s_nop 0
	global_load_lds_dwordx4 v[2:3], off
	s_and_b64 vcc, exec, s[42:43]
	s_cbranch_vccz .LBB0_571

.LBB0_571:
	v_mov_b32_e32 v61, v58
	v_cvt_pk_bf16_f32 v62, v32, v33
	v_lshl_add_u32 v2, v61, 4, 0
	v_add_u32_e32 v170, 0xe000, v2
	ds_read_b128 v[78:81], v2 offset:57344
	ds_read_b128 v[82:85], v2 offset:61440
	ds_read_b128 v[86:89], v170 offset:16384
	ds_read_b128 v[90:93], v170 offset:20480
	ds_read_b128 v[94:97], v170 offset:8192
	ds_read_b128 v[98:101], v170 offset:12288
	ds_read_b128 v[102:105], v170 offset:24576
	ds_read_b128 v[106:109], v170 offset:28672
	v_cvt_pk_bf16_f32 v63, v34, v35
	v_cvt_pk_bf16_f32 v64, v28, v29
	v_cvt_pk_bf16_f32 v65, v30, v31
	v_cvt_pk_bf16_f32 v66, v24, v25
	v_cvt_pk_bf16_f32 v67, v26, v27
	v_cvt_pk_bf16_f32 v68, v20, v21
	v_cvt_pk_bf16_f32 v69, v22, v23
	v_cvt_pk_bf16_f32 v70, v16, v17
	v_cvt_pk_bf16_f32 v71, v18, v19
	v_cvt_pk_bf16_f32 v72, v12, v13
	v_cvt_pk_bf16_f32 v73, v14, v15
	v_cvt_pk_bf16_f32 v74, v8, v9
	v_cvt_pk_bf16_f32 v75, v10, v11
	v_cvt_pk_bf16_f32 v76, v4, v5
	v_cvt_pk_bf16_f32 v77, v6, v7
	v_and_b32_e32 v171, 15, v61
	ds_read_b128 v[110:113], v2 offset:58368
	ds_read_b128 v[114:117], v2 offset:62464
	ds_read_b128 v[118:121], v170 offset:17408
	ds_read_b128 v[122:125], v170 offset:21504
	ds_read_b128 v[126:129], v170 offset:9216
	ds_read_b128 v[130:133], v170 offset:13312
	ds_read_b128 v[134:137], v170 offset:25600
	ds_read_b128 v[138:141], v170 offset:29696
	s_waitcnt lgkmcnt(0)
	v_mfma_f32_16x16x32_bf16 v[78:81], v[78:81], v[62:65], 0
	v_mfma_f32_16x16x32_bf16 v[86:89], v[86:89], v[62:65], 0
	v_mfma_f32_16x16x32_bf16 v[82:85], v[82:85], v[62:65], 0
	v_mfma_f32_16x16x32_bf16 v[90:93], v[90:93], v[62:65], 0
	v_mfma_f32_16x16x32_bf16 v[94:97], v[94:97], v[62:65], 0
	v_mfma_f32_16x16x32_bf16 v[102:105], v[102:105], v[62:65], 0
	v_mfma_f32_16x16x32_bf16 v[98:101], v[98:101], v[62:65], 0
	v_mfma_f32_16x16x32_bf16 v[62:65], v[106:109], v[62:65], 0
	ds_read_b128 v[106:109], v2 offset:59392
	ds_read_b128 v[142:145], v2 offset:63488
	ds_read_b128 v[146:149], v170 offset:18432
	ds_read_b128 v[150:153], v170 offset:22528
	ds_read_b128 v[154:157], v170 offset:10240
	ds_read_b128 v[158:161], v170 offset:14336
	ds_read_b128 v[162:165], v170 offset:26624
	ds_read_b128 v[166:169], v170 offset:30720
	v_mfma_f32_16x16x32_bf16 v[78:81], v[110:113], v[66:69], v[78:81]
	v_mfma_f32_16x16x32_bf16 v[86:89], v[118:121], v[66:69], v[86:89]
	v_mfma_f32_16x16x32_bf16 v[82:85], v[114:117], v[66:69], v[82:85]
	v_mfma_f32_16x16x32_bf16 v[90:93], v[122:125], v[66:69], v[90:93]
	v_mfma_f32_16x16x32_bf16 v[94:97], v[126:129], v[66:69], v[94:97]
	v_mfma_f32_16x16x32_bf16 v[102:105], v[134:137], v[66:69], v[102:105]
	v_mfma_f32_16x16x32_bf16 v[98:101], v[130:133], v[66:69], v[98:101]
	v_mfma_f32_16x16x32_bf16 v[62:65], v[138:141], v[66:69], v[62:65]
	ds_read_b128 v[66:69], v2 offset:60416
	ds_read_b128 v[110:113], v2 offset:64512
	ds_read_b128 v[114:117], v170 offset:19456
	ds_read_b128 v[118:121], v170 offset:23552
	ds_read_b128 v[122:125], v170 offset:11264
	ds_read_b128 v[126:129], v170 offset:15360
	ds_read_b128 v[130:133], v170 offset:27648
	ds_read_b128 v[134:137], v170 offset:31744
	s_waitcnt lgkmcnt(0)
	v_mfma_f32_16x16x32_bf16 v[78:81], v[106:109], v[70:73], v[78:81]
	v_mfma_f32_16x16x32_bf16 v[86:89], v[146:149], v[70:73], v[86:89]
	v_mfma_f32_16x16x32_bf16 v[82:85], v[142:145], v[70:73], v[82:85]
	v_mfma_f32_16x16x32_bf16 v[90:93], v[150:153], v[70:73], v[90:93]
	v_mfma_f32_16x16x32_bf16 v[94:97], v[154:157], v[70:73], v[94:97]
	v_mfma_f32_16x16x32_bf16 v[102:105], v[162:165], v[70:73], v[102:105]
	v_mfma_f32_16x16x32_bf16 v[98:101], v[158:161], v[70:73], v[98:101]
	v_mfma_f32_16x16x32_bf16 v[62:65], v[166:169], v[70:73], v[62:65]
	ds_read_b128 v[70:73], v170 offset:32768
	ds_read_b128 v[106:109], v170 offset:34816
	ds_read_b128 v[138:141], v170 offset:36864
	ds_read_b128 v[142:145], v170 offset:38912
	ds_read_b128 v[146:149], v170 offset:40960
	ds_read_b128 v[150:153], v170 offset:43008
	ds_read_b128 v[154:157], v170 offset:45056
	ds_read_b128 v[158:161], v170 offset:47104
	v_mfma_f32_16x16x32_bf16 v[66:69], v[66:69], v[74:77], v[78:81]
	v_mfma_f32_16x16x32_bf16 v[78:81], v[114:117], v[74:77], v[86:89]
	v_mfma_f32_16x16x32_bf16 v[82:85], v[110:113], v[74:77], v[82:85]
	v_mfma_f32_16x16x32_bf16 v[86:89], v[118:121], v[74:77], v[90:93]
	v_mfma_f32_16x16x32_bf16 v[90:93], v[122:125], v[74:77], v[94:97]
	v_mfma_f32_16x16x32_bf16 v[94:97], v[130:133], v[74:77], v[102:105]
	v_mfma_f32_16x16x32_bf16 v[98:101], v[126:129], v[74:77], v[98:101]
	v_mfma_f32_16x16x32_bf16 v[62:65], v[134:137], v[74:77], v[62:65]
	v_lshlrev_b32_e32 v2, 16, v50
	v_and_b32_e32 v3, 0xffff0000, v50
	v_lshlrev_b32_e32 v74, 16, v51
	v_and_b32_e32 v75, 0xffff0000, v51
	v_sub_f32_e32 v3, v3, v67
	v_sub_f32_e32 v2, v2, v66
	v_lshlrev_b32_e32 v66, 16, v52
	v_and_b32_e32 v67, 0xffff0000, v52
	v_sub_f32_e32 v69, v75, v69
	v_sub_f32_e32 v68, v74, v68
	v_lshlrev_b32_e32 v74, 16, v53
	v_and_b32_e32 v75, 0xffff0000, v53
	v_sub_f32_e32 v76, v67, v83
	v_sub_f32_e32 v77, v66, v82
	v_lshlrev_b32_e32 v66, 16, v54
	v_and_b32_e32 v67, 0xffff0000, v54
	v_sub_f32_e32 v75, v75, v85
	v_sub_f32_e32 v74, v74, v84
	v_lshlrev_b32_e32 v82, 16, v55
	v_and_b32_e32 v83, 0xffff0000, v55
	v_sub_f32_e32 v84, v67, v91
	v_sub_f32_e32 v85, v66, v90
	v_lshlrev_b32_e32 v66, 16, v56
	v_and_b32_e32 v67, 0xffff0000, v56
	v_lshlrev_b32_e32 v90, 16, v57
	v_and_b32_e32 v91, 0xffff0000, v57
	v_sub_f32_e32 v83, v83, v93
	v_sub_f32_e32 v82, v82, v92
	v_sub_f32_e32 v91, v91, v101
	v_sub_f32_e32 v90, v90, v100
	v_sub_f32_e32 v92, v67, v99
	v_sub_f32_e32 v93, v66, v98
	s_cmp_lg_u64 s[48:49], 0
	s_cbranch_scc1 .Lg2_w7
	s_waitcnt vmcnt(0)
	s_branch .Lg2_wd
.Lg2_w7:
	s_waitcnt vmcnt(7)
.Lg2_wd:
	v_pk_mul_f32 v[34:35], v[34:35], v[0:1] op_sel_hi:[1,0]
	v_pk_mul_f32 v[32:33], v[32:33], v[0:1] op_sel_hi:[1,0]
	v_pk_mul_f32 v[30:31], v[30:31], v[0:1] op_sel_hi:[1,0]
	v_pk_mul_f32 v[28:29], v[28:29], v[0:1] op_sel_hi:[1,0]
	v_pk_mul_f32 v[26:27], v[26:27], v[0:1] op_sel_hi:[1,0]
	v_pk_mul_f32 v[24:25], v[24:25], v[0:1] op_sel_hi:[1,0]
	v_pk_mul_f32 v[22:23], v[22:23], v[0:1] op_sel_hi:[1,0]
	v_pk_mul_f32 v[20:21], v[20:21], v[0:1] op_sel_hi:[1,0]
	v_pk_mul_f32 v[18:19], v[18:19], v[0:1] op_sel_hi:[1,0]
	v_pk_mul_f32 v[16:17], v[16:17], v[0:1] op_sel_hi:[1,0]
	v_pk_mul_f32 v[14:15], v[14:15], v[0:1] op_sel_hi:[1,0]
	v_pk_mul_f32 v[12:13], v[12:13], v[0:1] op_sel_hi:[1,0]
	v_pk_mul_f32 v[10:11], v[10:11], v[0:1] op_sel_hi:[1,0]
	v_pk_mul_f32 v[8:9], v[8:9], v[0:1] op_sel_hi:[1,0]
	v_pk_mul_f32 v[6:7], v[6:7], v[0:1] op_sel_hi:[1,0]
	v_pk_mul_f32 v[4:5], v[4:5], v[0:1] op_sel_hi:[1,0]
	v_cvt_pk_bf16_f32 v66, v2, v3
	v_cvt_pk_bf16_f32 v67, v68, v69
	v_cvt_pk_bf16_f32 v68, v77, v76
	v_cvt_pk_bf16_f32 v69, v74, v75
	v_cvt_pk_bf16_f32 v74, v85, v84
	v_cvt_pk_bf16_f32 v75, v82, v83
	v_cvt_pk_bf16_f32 v76, v93, v92
	v_cvt_pk_bf16_f32 v77, v90, v91
	ds_read_b128 v[82:85], v170 offset:33792
	ds_read_b128 v[90:93], v170 offset:35840
	ds_read_b128 v[98:101], v170 offset:37888
	ds_read_b128 v[102:105], v170 offset:39936
	ds_read_b128 v[110:113], v170 offset:41984
	ds_read_b128 v[114:117], v170 offset:44032
	ds_read_b128 v[118:121], v170 offset:46080
	ds_read_b128 v[122:125], v170 offset:48128
	s_waitcnt lgkmcnt(14)
	v_mfma_f32_16x16x32_bf16 v[32:35], v[70:73], v[66:69], v[32:35]
	v_mfma_f32_16x16x32_bf16 v[28:31], v[106:109], v[66:69], v[28:31]
	s_waitcnt lgkmcnt(13)
	v_mfma_f32_16x16x32_bf16 v[24:27], v[138:141], v[66:69], v[24:27]
	s_waitcnt lgkmcnt(12)
	v_mfma_f32_16x16x32_bf16 v[20:23], v[142:145], v[66:69], v[20:23]
	s_waitcnt lgkmcnt(11)
	v_mfma_f32_16x16x32_bf16 v[16:19], v[146:149], v[66:69], v[16:19]
	s_waitcnt lgkmcnt(10)
	v_mfma_f32_16x16x32_bf16 v[12:15], v[150:153], v[66:69], v[12:15]
	s_waitcnt lgkmcnt(9)
	v_mfma_f32_16x16x32_bf16 v[8:11], v[154:157], v[66:69], v[8:11]
	s_waitcnt lgkmcnt(8)
	v_mfma_f32_16x16x32_bf16 v[2:5], v[158:161], v[66:69], v[4:7]
	ds_read_b128 v[70:73], v170 offset:49152
	ds_read_b128 v[106:109], v170 offset:50176
	ds_read_b128 v[126:129], v170 offset:51200
	ds_read_b128 v[130:133], v170 offset:52224
	ds_read_b128 v[134:137], v170 offset:53248
	ds_read_b128 v[138:141], v170 offset:54272
	ds_read_b128 v[142:145], v170 offset:55296
	ds_read_b128 v[146:149], v170 offset:56320
	s_waitcnt lgkmcnt(14)
	v_mfma_f32_16x16x32_bf16 v[32:35], v[82:85], v[74:77], v[32:35]
	v_mfma_f32_16x16x32_bf16 v[28:31], v[90:93], v[74:77], v[28:31]
	s_waitcnt lgkmcnt(13)
	v_mfma_f32_16x16x32_bf16 v[24:27], v[98:101], v[74:77], v[24:27]
	s_waitcnt lgkmcnt(12)
	v_mfma_f32_16x16x32_bf16 v[20:23], v[102:105], v[74:77], v[20:23]
	s_waitcnt lgkmcnt(11)
	v_mfma_f32_16x16x32_bf16 v[16:19], v[110:113], v[74:77], v[16:19]
	s_waitcnt lgkmcnt(10)
	v_mfma_f32_16x16x32_bf16 v[12:15], v[114:117], v[74:77], v[12:15]
	s_waitcnt lgkmcnt(9)
	v_mfma_f32_16x16x32_bf16 v[8:11], v[118:121], v[74:77], v[8:11]
	s_waitcnt lgkmcnt(8)
	v_mfma_f32_16x16x32_bf16 v[4:7], v[122:125], v[74:77], v[2:5]
	s_waitcnt lgkmcnt(7)
	v_mfma_f32_16x16x32_bf16 v[70:73], v[70:73], v[66:69], v[78:81]
	s_waitcnt lgkmcnt(5)
	v_mfma_f32_16x16x32_bf16 v[78:81], v[126:129], v[66:69], v[86:89]
	s_waitcnt lgkmcnt(3)
	v_mfma_f32_16x16x32_bf16 v[82:85], v[134:137], v[66:69], v[94:97]
	s_waitcnt lgkmcnt(1)
	v_mfma_f32_16x16x32_bf16 v[62:65], v[142:145], v[66:69], v[62:65]
	v_mfma_f32_16x16x32_bf16 v[66:69], v[106:109], v[74:77], v[70:73]
	v_mfma_f32_16x16x32_bf16 v[70:73], v[130:133], v[74:77], v[78:81]
	v_mfma_f32_16x16x32_bf16 v[78:81], v[138:141], v[74:77], v[82:85]
	s_waitcnt lgkmcnt(0)
	v_mfma_f32_16x16x32_bf16 v[62:65], v[146:149], v[74:77], v[62:65]
	v_ashrrev_i32_e32 v0, 2, v61
	v_and_b32_e32 v0, -4, v0
	v_add_u32_e32 v61, s83, v0
	v_add_u32_e32 v2, 64, v61
	v_lshlrev_b32_e32 v0, 1, v171
	v_ashrrev_i32_e32 v3, 31, v2
	v_lshl_add_u64 v[74:75], s[28:29], 0, v[0:1]
	v_lshlrev_b64 v[2:3], 11, v[2:3]
	v_cvt_pk_bf16_f32 v0, v66, v67
	v_lshl_add_u64 v[2:3], v[74:75], 0, v[2:3]
	global_store_short v[2:3], v0, off
	global_store_short_d16_hi v[2:3], v0, off offset:2048
	v_add_co_u32_e32 v2, vcc, s72, v2
	v_cvt_pk_bf16_f32 v66, v68, v69
	s_nop 0
	v_addc_co_u32_e32 v3, vcc, 0, v3, vcc
	global_store_short v[2:3], v66, off
	global_store_short_d16_hi v[2:3], v66, off offset:2048
	v_add_u32_e32 v2, 0x50, v61
	v_ashrrev_i32_e32 v3, 31, v2
	v_lshlrev_b64 v[2:3], 11, v[2:3]
	v_cvt_pk_bf16_f32 v0, v70, v71
	v_lshl_add_u64 v[2:3], v[74:75], 0, v[2:3]
	global_store_short v[2:3], v0, off
	global_store_short_d16_hi v[2:3], v0, off offset:2048
	v_add_co_u32_e32 v2, vcc, s72, v2
	v_cvt_pk_bf16_f32 v66, v72, v73
	s_nop 0
	v_addc_co_u32_e32 v3, vcc, 0, v3, vcc
	global_store_short v[2:3], v66, off
	global_store_short_d16_hi v[2:3], v66, off offset:2048
	v_add_u32_e32 v2, 0x60, v61
	v_ashrrev_i32_e32 v3, 31, v2
	v_lshlrev_b64 v[2:3], 11, v[2:3]
	v_cvt_pk_bf16_f32 v0, v78, v79
	v_lshl_add_u64 v[2:3], v[74:75], 0, v[2:3]
	global_store_short v[2:3], v0, off
	global_store_short_d16_hi v[2:3], v0, off offset:2048
	v_add_co_u32_e32 v2, vcc, s72, v2
	v_cvt_pk_bf16_f32 v66, v80, v81
	s_nop 0
	v_addc_co_u32_e32 v3, vcc, 0, v3, vcc
	global_store_short v[2:3], v66, off
	global_store_short_d16_hi v[2:3], v66, off offset:2048
	v_add_u32_e32 v2, 0x70, v61
	v_ashrrev_i32_e32 v3, 31, v2
	v_lshlrev_b64 v[2:3], 11, v[2:3]
	v_cvt_pk_bf16_f32 v0, v62, v63
	v_lshl_add_u64 v[2:3], v[74:75], 0, v[2:3]
	global_store_short v[2:3], v0, off
	global_store_short_d16_hi v[2:3], v0, off offset:2048
	v_add_co_u32_e32 v2, vcc, 0x1000, v2
	v_cvt_pk_bf16_f32 v62, v64, v65
	s_nop 0
	v_addc_co_u32_e32 v3, vcc, 0, v3, vcc
	global_store_short v[2:3], v62, off
	global_store_short_d16_hi v[2:3], v62, off offset:2048
	s_and_b64 s[42:43], s[6:7], s[48:49]
	s_andn2_b64 vcc, exec, s[42:43]
	s_cbranch_vccnz .LBB0_562

.Lattn_main:
	v_writelane_b32 v244, s79, 16
	v_mov_b32_e32 v203, v97
	v_mov_b32_e32 v248, v247
	v_mov_b32_e32 v249, v247
	v_mov_b32_e32 v250, v247
	v_mov_b32_e32 v251, v247
	v_mbcnt_hi_u32_b32 v204, -1, v192
	v_readlane_b32 s4, v245, 0
	v_readlane_b32 s0, v245, 7
	s_lshr_b32 s6, s4, 6
	s_mov_b32 s4, s62
	s_mov_b32 s5, s63
	s_cmp_eq_u32 s0, 0x100
	s_cselect_b32 s7, 1, 0
	s_mov_b32 s78, s0
	s_add_u32 s8, s92, 0x6d00000
	s_addc_u32 s9, s93, 0
	s_add_u32 s10, s92, 0x8d00000
	s_addc_u32 s11, s93, 0
	s_add_u32 s12, s92, 0xad00000
	s_addc_u32 s13, s93, 0
	s_add_u32 s14, s92, 0x4d00000
	s_addc_u32 s15, s93, 0
	s_add_u32 s16, s92, 0xcd00000
	s_addc_u32 s17, s93, 0
	s_add_u32 s18, s74, 0x2000000
	s_addc_u32 s19, s75, 0
	v_and_b32_e32 v205, 15, v204
	v_lshrrev_b32_e32 v206, 4, v204
	v_xor_b32_e32 v208, 16, v204
	v_lshlrev_b32_e32 v208, 2, v208
	v_xor_b32_e32 v209, 32, v204
	v_lshlrev_b32_e32 v209, 2, v209
	v_mov_b32_e32 v201, 0xf149f2ca
	v_lshlrev_b32_e32 v216, 4, v206
	v_and_b32_e32 v207, 3, v205
	v_xor_b32_e32 v207, v207, v206
	v_lshlrev_b32_e32 v207, 4, v207
	v_lshl_add_u32 v207, v205, 8, v207
	v_lshrrev_b32_e32 v217, 2, v205
	v_xor_b32_e32 v218, 0, v217
	v_lshl_add_u32 v195, v218, 6, v207
	v_xor_b32_e32 v218, 1, v217
	v_lshl_add_u32 v196, v218, 6, v207
	v_xor_b32_e32 v218, 2, v217
	v_lshl_add_u32 v231, v218, 6, v207
	v_xor_b32_e32 v218, 3, v217
	v_lshl_add_u32 v232, v218, 6, v207
	v_bfe_u32 v217, v205, 1, 3
	v_and_b32_e32 v207, 3, v217
	v_xor_b32_e32 v207, v207, v206
	v_lshlrev_b32_e32 v207, 4, v207
	v_lshl_add_u32 v207, v205, 7, v207
	v_lshrrev_b32_e32 v217, 2, v217
	v_xor_b32_e32 v218, 0, v217
	v_lshl_add_u32 v233, v218, 6, v207
	v_xor_b32_e32 v218, 1, v217
	v_lshl_add_u32 v234, v218, 6, v207
	s_and_b32 s1, s6, 3
	s_lshl_b32 s40, s1, 12
	s_cmp_lt_u32 s6, 4
	s_cbranch_scc0 .Lattn_roleV
	v_lshrrev_b32_e32 v207, 4, v204
	v_and_b32_e32 v217, 15, v204
	v_xor_b32_e32 v217, v217, v207
	v_xor_b32_e32 v218, 0, v217
	v_lshlrev_b32_e32 v218, 4, v218
	v_add_u32_e32 v219, 0, v207
	v_lshl_add_u32 v197, v219, 11, v218
	v_xor_b32_e32 v218, 4, v217
	v_lshlrev_b32_e32 v218, 4, v218
	v_add_u32_e32 v219, 8, v207
	v_lshl_add_u32 v198, v219, 11, v218
	v_xor_b32_e32 v218, 8, v217
	v_lshlrev_b32_e32 v218, 4, v218
	v_add_u32_e32 v219, 16, v207
	v_lshl_add_u32 v229, v219, 11, v218
	v_xor_b32_e32 v218, 12, v217
	v_lshlrev_b32_e32 v218, 4, v218
	v_add_u32_e32 v219, 24, v207
	v_lshl_add_u32 v230, v219, 11, v218
	s_mov_b32 s86, s10
	s_mov_b32 s87, s11
	s_mov_b32 s41, 0x20000
	s_branch .Lattn_roleDone
.Lattn_roleV:
	v_lshrrev_b32_e32 v207, 3, v204
	v_and_b32_e32 v217, 7, v204
	v_add_u32_e32 v219, 0, v207
	v_bfe_u32 v218, v219, 1, 3
	v_xor_b32_e32 v218, v218, v217
	v_lshlrev_b32_e32 v218, 4, v218
	v_add_u32_e32 v219, 0, v219
	v_lshl_add_u32 v197, v219, 15, v218
	v_add_u32_e32 v219, 8, v207
	v_bfe_u32 v218, v219, 1, 3
	v_xor_b32_e32 v218, v218, v217
	v_lshlrev_b32_e32 v218, 4, v218
	v_add_u32_e32 v219, 0, v219
	v_lshl_add_u32 v198, v219, 15, v218
	v_add_u32_e32 v219, 0, v207
	v_bfe_u32 v218, v219, 1, 3
	v_xor_b32_e32 v218, v218, v217
	v_lshlrev_b32_e32 v218, 4, v218
	v_add_u32_e32 v219, 16, v219
	v_lshl_add_u32 v229, v219, 15, v218
	v_add_u32_e32 v219, 8, v207
	v_bfe_u32 v218, v219, 1, 3
	v_xor_b32_e32 v218, v218, v217
	v_lshlrev_b32_e32 v218, 4, v218
	v_add_u32_e32 v219, 16, v219
	v_lshl_add_u32 v230, v219, 15, v218
	s_mov_b32 s86, s12
	s_mov_b32 s87, s13
	s_movk_i32 s41, 0x80
	s_or_b32 s40, s40, 0x4000
.Lattn_roleDone:
	s_mov_b32 s21, s2
	s_mov_b32 s22, 0
	s_mov_b32 s91, 0
	s_mov_b32 s32, 0
	s_mov_b32 s0, s21
	s_cmp_eq_u32 s7, 0
	s_cbranch_scc1 .Lat_noperm1
	s_lshl_b32 s0, s21, 3
	s_and_b32 s0, s0, 56
	s_bfe_u32 s1, s21, 0x20006
	s_or_b32 s0, s0, s1
	s_lshr_b32 s1, s21, 6
	s_and_b32 s1, s1, 0x1ffffffc
	s_add_i32 s0, s0, s1
	s_lshl_b32 s0, s0, 3
	s_bfe_u32 s1, s21, 0x30003
	s_or_b32 s0, s0, s1
.Lat_noperm1:
	s_and_b32 s36, s0, 7
	s_lshr_b32 s1, s0, 3
	s_lshr_b32 s23, s1, 3
	s_and_b32 s33, s1, 7
	s_sub_i32 s0, 15, s36
	s_cmp_eq_u32 s22, 0
	s_cselect_b32 s36, s0, s36
	s_lshl_b32 s37, s36, 7
	s_lshl_b32 s0, s6, 4
	s_add_i32 s37, s37, s0
	s_lshl_b32 s0, s23, 11
	s_add_i32 s0, s0, s37
	v_add_u32_e32 v207, s0, v205
	s_lshl_b32 s1, s33, 8
	v_lshl_add_u32 v217, v207, 11, s1
	v_lshl_add_u32 v214, v206, 4, v217
	v_lshl_add_u32 v202, v206, 3, v217
	global_load_dwordx4 v[64:67], v214, s[8:9]
	global_load_dwordx4 v[68:71], v214, s[8:9] offset:64
	global_load_dwordx4 v[72:75], v214, s[8:9] offset:128
	global_load_dwordx4 v[76:79], v214, s[8:9] offset:192
	v_lshlrev_b32_e32 v218, 3, v206
	v_add_u32_e32 v200, s37, v205
	v_sub_u32_e32 v200, v200, v218
	s_cmp_lt_u32 s6, 4
	s_cbranch_scc0 .Lat_ubV2
	s_and_b32 s0, s6, 3
	s_lshr_b32 s1, s0, 1
	s_lshl_b32 s1, s1, 5
	s_and_b32 s0, s0, 1
	s_lshl_b32 s0, s0, 2
	s_add_i32 s1, s1, s0
	s_lshl_b32 s0, s23, 11
	s_add_i32 s1, s1, s0
	s_lshl_b32 s1, s1, 11
	s_lshl_b32 s0, s33, 8
	s_add_i32 s79, s1, s0
	s_branch .Lat_ubD3

.Lat_ubD3:
	s_lshl_b32 s38, s36, 1
	s_add_i32 s38, s38, 2
	s_add_i32 s1, s91, 0
	s_and_b32 s1, s1, 3
	s_lshl_b32 s1, s1, 15
	s_add_i32 s1, s1, s40
	v_add_u32_e32 v210, s79, v197
	v_add_u32_e32 v211, s79, v198
	v_add_u32_e32 v212, s79, v229
	v_add_u32_e32 v213, s79, v230
	s_add_i32 m0, s1, 0x0
	s_nop 0
	global_load_lds_dwordx4 v210, s[86:87]
	s_add_i32 m0, s1, 0x400
	s_nop 0
	global_load_lds_dwordx4 v211, s[86:87]
	s_add_i32 m0, s1, 0x800
	s_nop 0
	global_load_lds_dwordx4 v212, s[86:87]
	s_add_i32 m0, s1, 0xc00
	s_nop 0
	global_load_lds_dwordx4 v213, s[86:87]
	s_add_i32 s79, s79, s41
	s_add_i32 s1, s91, 1
	s_and_b32 s1, s1, 3
	s_lshl_b32 s1, s1, 15
	s_add_i32 s1, s1, s40
	v_add_u32_e32 v210, s79, v197
	v_add_u32_e32 v211, s79, v198
	v_add_u32_e32 v212, s79, v229
	v_add_u32_e32 v213, s79, v230
	s_add_i32 m0, s1, 0x0
	s_nop 0
	global_load_lds_dwordx4 v210, s[86:87]
	s_add_i32 m0, s1, 0x400
	s_nop 0
	global_load_lds_dwordx4 v211, s[86:87]
	s_add_i32 m0, s1, 0x800
	s_nop 0
	global_load_lds_dwordx4 v212, s[86:87]
	s_add_i32 m0, s1, 0xc00
	s_nop 0
	global_load_lds_dwordx4 v213, s[86:87]
	s_add_i32 s79, s79, s41
	s_waitcnt vmcnt(0)
.Lattn_unit:
	v_mov_b32_e32 v215, v202
	v_mov_b32_e32 v0, 0
	v_mov_b32_e32 v1, 0
	v_mov_b32_e32 v2, 0
	v_mov_b32_e32 v3, 0
	v_mov_b32_e32 v4, 0
	v_mov_b32_e32 v5, 0
	v_mov_b32_e32 v6, 0
	v_mov_b32_e32 v7, 0
	v_mov_b32_e32 v8, 0
	v_mov_b32_e32 v9, 0
	v_mov_b32_e32 v10, 0
	v_mov_b32_e32 v11, 0
	v_mov_b32_e32 v12, 0
	v_mov_b32_e32 v13, 0
	v_mov_b32_e32 v14, 0
	v_mov_b32_e32 v15, 0
	v_mov_b32_e32 v16, 0
	v_mov_b32_e32 v17, 0
	v_mov_b32_e32 v18, 0
	v_mov_b32_e32 v19, 0
	v_mov_b32_e32 v20, 0
	v_mov_b32_e32 v21, 0
	v_mov_b32_e32 v22, 0
	v_mov_b32_e32 v23, 0
	v_mov_b32_e32 v24, 0
	v_mov_b32_e32 v25, 0
	v_mov_b32_e32 v26, 0
	v_mov_b32_e32 v27, 0
	v_mov_b32_e32 v28, 0
	v_mov_b32_e32 v29, 0
	v_mov_b32_e32 v30, 0
	v_mov_b32_e32 v31, 0
	v_mov_b32_e32 v32, 0
	v_mov_b32_e32 v33, 0
	v_mov_b32_e32 v34, 0
	v_mov_b32_e32 v35, 0
	v_mov_b32_e32 v36, 0
	v_mov_b32_e32 v37, 0
	v_mov_b32_e32 v38, 0
	v_mov_b32_e32 v39, 0
	v_mov_b32_e32 v40, 0
	v_mov_b32_e32 v41, 0
	v_mov_b32_e32 v42, 0
	v_mov_b32_e32 v43, 0
	v_mov_b32_e32 v44, 0
	v_mov_b32_e32 v45, 0
	v_mov_b32_e32 v46, 0
	v_mov_b32_e32 v47, 0
	v_mov_b32_e32 v48, 0
	v_mov_b32_e32 v49, 0
	v_mov_b32_e32 v50, 0
	v_mov_b32_e32 v51, 0
	v_mov_b32_e32 v52, 0
	v_mov_b32_e32 v53, 0
	v_mov_b32_e32 v54, 0
	v_mov_b32_e32 v55, 0
	v_mov_b32_e32 v56, 0
	v_mov_b32_e32 v57, 0
	v_mov_b32_e32 v58, 0
	v_mov_b32_e32 v59, 0
	v_mov_b32_e32 v60, 0
	v_mov_b32_e32 v61, 0
	v_mov_b32_e32 v62, 0
	v_mov_b32_e32 v63, 0
	v_mov_b32_e32 v193, 0
	v_mov_b32_e32 v194, 0
	s_mov_b32 s39, 0
	s_barrier
	s_cmp_lt_u32 s6, 4
	s_cbranch_scc0 .Lattn_halfB
.Lattn_tileA:
	s_add_i32 s0, s39, 2
	s_cmp_lt_i32 s0, s38
	s_cbranch_scc0 .Lat_nodma4
	s_add_i32 s1, s91, 2
	s_and_b32 s1, s1, 3
	s_lshl_b32 s1, s1, 15
	s_add_i32 s1, s1, s40
	v_add_u32_e32 v210, s79, v197
	v_add_u32_e32 v211, s79, v198
	v_add_u32_e32 v212, s79, v229
	v_add_u32_e32 v213, s79, v230
	s_add_i32 m0, s1, 0x0
	s_nop 0
	global_load_lds_dwordx4 v210, s[86:87]
	s_add_i32 m0, s1, 0x400
	s_nop 0
	global_load_lds_dwordx4 v211, s[86:87]
	s_add_i32 m0, s1, 0x800
	s_nop 0
	global_load_lds_dwordx4 v212, s[86:87]
	s_add_i32 m0, s1, 0xc00
	s_nop 0
	global_load_lds_dwordx4 v213, s[86:87]
	s_add_i32 s79, s79, s41
.Lat_nodma4:
	s_lshl_b32 s96, s39, 6
	s_add_i32 s0, s37, 15
	s_cmp_gt_i32 s96, s0
	s_cselect_b32 vcc_hi, 1, 0
	s_cbranch_scc1 .Lat_s1end5
	ds_read_b128 v[80:83], v195
	ds_read_b128 v[84:87], v196
	ds_read_b128 v[88:91], v195 offset:4096
	ds_read_b128 v[92:95], v196 offset:4096
	ds_read_b128 v[96:99], v195 offset:8192
	ds_read_b128 v[100:103], v196 offset:8192
	ds_read_b128 v[104:107], v195 offset:12288
	ds_read_b128 v[108:111], v196 offset:12288
	s_waitcnt lgkmcnt(7)
	v_mfma_f32_16x16x32_bf16 v[144:147], v[80:83], v[64:67], v[248:251]
	ds_read_b128 v[112:115], v231
	s_waitcnt lgkmcnt(7)
	v_mfma_f32_16x16x32_bf16 v[144:147], v[84:87], v[68:71], v[144:147]
	ds_read_b128 v[116:119], v232
	s_waitcnt lgkmcnt(7)
	v_mfma_f32_16x16x32_bf16 v[148:151], v[88:91], v[64:67], v[248:251]
	ds_read_b128 v[120:123], v231 offset:4096
	s_waitcnt lgkmcnt(7)
	v_mfma_f32_16x16x32_bf16 v[148:151], v[92:95], v[68:71], v[148:151]
	ds_read_b128 v[124:127], v232 offset:4096
	s_waitcnt lgkmcnt(7)
	v_mfma_f32_16x16x32_bf16 v[152:155], v[96:99], v[64:67], v[248:251]
	ds_read_b128 v[128:131], v231 offset:8192
	s_waitcnt lgkmcnt(7)
	v_mfma_f32_16x16x32_bf16 v[152:155], v[100:103], v[68:71], v[152:155]
	ds_read_b128 v[132:135], v232 offset:8192
	s_waitcnt lgkmcnt(7)
	v_mfma_f32_16x16x32_bf16 v[156:159], v[104:107], v[64:67], v[248:251]
	ds_read_b128 v[136:139], v231 offset:12288
	s_waitcnt lgkmcnt(7)
	v_mfma_f32_16x16x32_bf16 v[156:159], v[108:111], v[68:71], v[156:159]
	ds_read_b128 v[140:143], v232 offset:12288
	s_waitcnt lgkmcnt(0)
	v_mfma_f32_16x16x32_bf16 v[160:163], v[112:115], v[72:75], v[248:251]
	v_mfma_f32_16x16x32_bf16 v[160:163], v[116:119], v[76:79], v[160:163]
	s_add_i32 s0, s96, 63
	s_cmp_gt_i32 s0, s37
	s_cselect_b32 s97, 1, 0
	s_cbranch_scc0 .Lat_nomask6
	v_subrev_u32_e32 v207, s96, v200
	v_cmp_gt_i32_e64 s[42:43], 0, v207
	v_cmp_gt_i32_e64 s[44:45], 1, v207
	v_cmp_gt_i32_e64 s[46:47], 2, v207
	v_cmp_gt_i32_e64 s[48:49], 3, v207
	v_cmp_gt_i32_e64 s[50:51], 4, v207
	v_cmp_gt_i32_e64 s[52:53], 5, v207
	v_cmp_gt_i32_e64 s[54:55], 6, v207
	v_cmp_gt_i32_e64 s[56:57], 7, v207
	v_cmp_gt_i32_e64 s[58:59], 32, v207
	v_cmp_gt_i32_e64 s[60:61], 33, v207
	v_cmp_gt_i32_e64 s[62:63], 34, v207
	v_cmp_gt_i32_e64 s[64:65], 35, v207
	v_cmp_gt_i32_e64 s[66:67], 36, v207
	v_cmp_gt_i32_e64 s[68:69], 37, v207
	v_cmp_gt_i32_e64 s[70:71], 38, v207
	v_cmp_gt_i32_e64 s[72:73], 39, v207
	v_cndmask_b32_e64 v144, v144, v201, s[42:43]
	v_cndmask_b32_e64 v145, v145, v201, s[44:45]
	v_cndmask_b32_e64 v146, v146, v201, s[46:47]
	v_cndmask_b32_e64 v147, v147, v201, s[48:49]
	v_cndmask_b32_e64 v148, v148, v201, s[50:51]
	v_cndmask_b32_e64 v149, v149, v201, s[52:53]
	v_cndmask_b32_e64 v150, v150, v201, s[54:55]
	v_cndmask_b32_e64 v151, v151, v201, s[56:57]
	v_cndmask_b32_e64 v152, v152, v201, s[58:59]
	v_cndmask_b32_e64 v153, v153, v201, s[60:61]
	v_cndmask_b32_e64 v154, v154, v201, s[62:63]
	v_cndmask_b32_e64 v155, v155, v201, s[64:65]
	v_cndmask_b32_e64 v156, v156, v201, s[66:67]
	v_cndmask_b32_e64 v157, v157, v201, s[68:69]
	v_cndmask_b32_e64 v158, v158, v201, s[70:71]
	v_cndmask_b32_e64 v159, v159, v201, s[72:73]
.Lat_nomask6:
	v_exp_f32_e32 v144, v144
	v_exp_f32_e32 v145, v145
	v_add_f32_e32 v193, v193, v144
	v_exp_f32_e32 v146, v146
	v_mov_b32_e32 v199, v145
	v_exp_f32_e32 v147, v147
	v_mfma_f32_16x16x32_bf16 v[164:167], v[120:123], v[72:75], v[248:251]
	v_add_f32_e32 v193, v193, v146
	v_cvt_pk_bf16_f32 v176, v144, v145
	ds_read_b128 v[80:83], v233 offset:16384
	v_exp_f32_e32 v148, v148
	v_add_f32_e32 v199, v199, v147
	v_exp_f32_e32 v149, v149
	v_add_f32_e32 v193, v193, v148
	v_mfma_f32_16x16x32_bf16 v[164:167], v[124:127], v[76:79], v[164:167]
	ds_read_b128 v[84:87], v234 offset:16384
	v_cvt_pk_bf16_f32 v177, v146, v147
	v_exp_f32_e32 v150, v150
	v_add_f32_e32 v199, v199, v149
	v_exp_f32_e32 v151, v151
	ds_read_b128 v[88:91], v233 offset:18432
	v_add_f32_e32 v193, v193, v150
	v_cvt_pk_bf16_f32 v178, v148, v149
	v_mfma_f32_16x16x32_bf16 v[168:171], v[128:131], v[72:75], v[248:251]
	v_exp_f32_e32 v152, v152
	v_add_f32_e32 v199, v199, v151
	ds_read_b128 v[92:95], v234 offset:18432
	v_exp_f32_e32 v153, v153
	v_add_f32_e32 v193, v193, v152
	v_cvt_pk_bf16_f32 v179, v150, v151
	v_mfma_f32_16x16x32_bf16 v[168:171], v[132:135], v[76:79], v[168:171]
	v_exp_f32_e32 v154, v154
	ds_read_b128 v[96:99], v233 offset:20480
	v_add_f32_e32 v199, v199, v153
	v_exp_f32_e32 v155, v155
	v_add_f32_e32 v193, v193, v154
	v_cvt_pk_bf16_f32 v180, v152, v153
	v_exp_f32_e32 v156, v156
	ds_read_b128 v[100:103], v234 offset:20480
	v_mfma_f32_16x16x32_bf16 v[172:175], v[136:139], v[72:75], v[248:251]
	v_add_f32_e32 v199, v199, v155
	v_exp_f32_e32 v157, v157
	v_add_f32_e32 v193, v193, v156
	ds_read_b128 v[104:107], v233 offset:22528
	v_cvt_pk_bf16_f32 v181, v154, v155
	v_exp_f32_e32 v158, v158
	v_add_f32_e32 v199, v199, v157
	v_mfma_f32_16x16x32_bf16 v[172:175], v[140:143], v[76:79], v[172:175]
	v_exp_f32_e32 v159, v159
	ds_read_b128 v[108:111], v234 offset:22528
	v_add_f32_e32 v193, v193, v158
	v_cvt_pk_bf16_f32 v182, v156, v157
	v_add_f32_e32 v199, v199, v159
	v_add_f32_e32 v193, v193, v199
	v_cvt_pk_bf16_f32 v183, v158, v159
	s_waitcnt lgkmcnt(7)
	ds_read_b128 v[112:115], v233 offset:24576
	ds_read_b128 v[116:119], v234 offset:24576
	ds_read_b128 v[120:123], v233 offset:26624
	ds_read_b128 v[124:127], v234 offset:26624
	ds_read_b128 v[128:131], v233 offset:28672
	ds_read_b128 v[132:135], v234 offset:28672
	ds_read_b128 v[136:139], v233 offset:30720
	ds_read_b128 v[140:143], v234 offset:30720
.Lat_s1end5:
	s_cmp_lg_u32 vcc_hi, 0
	s_cbranch_scc1 .Lat_s2end7
	s_cmp_lg_u32 s97, 0
	s_cbranch_scc0 .Lat_nomask8
	v_cndmask_b32_e64 v160, v160, v201, s[42:43]
	v_cndmask_b32_e64 v161, v161, v201, s[44:45]
	v_cndmask_b32_e64 v162, v162, v201, s[46:47]
	v_cndmask_b32_e64 v163, v163, v201, s[48:49]
	v_cndmask_b32_e64 v164, v164, v201, s[50:51]
	v_cndmask_b32_e64 v165, v165, v201, s[52:53]
	v_cndmask_b32_e64 v166, v166, v201, s[54:55]
	v_cndmask_b32_e64 v167, v167, v201, s[56:57]
	v_cndmask_b32_e64 v168, v168, v201, s[58:59]
	v_cndmask_b32_e64 v169, v169, v201, s[60:61]
	v_cndmask_b32_e64 v170, v170, v201, s[62:63]
	v_cndmask_b32_e64 v171, v171, v201, s[64:65]
	v_cndmask_b32_e64 v172, v172, v201, s[66:67]
	v_cndmask_b32_e64 v173, v173, v201, s[68:69]
	v_cndmask_b32_e64 v174, v174, v201, s[70:71]
	v_cndmask_b32_e64 v175, v175, v201, s[72:73]
.Lat_nomask8:
	v_exp_f32_e32 v160, v160
	v_exp_f32_e32 v161, v161
	v_add_f32_e32 v194, v194, v160
	v_exp_f32_e32 v162, v162
	s_waitcnt lgkmcnt(15)
	v_mfma_f32_16x16x32_bf16 v[0:3], v[80:83], v[176:179], v[0:3]
	v_mov_b32_e32 v199, v161
	v_exp_f32_e32 v163, v163
	v_add_f32_e32 v194, v194, v162
	s_waitcnt lgkmcnt(14)
	v_mfma_f32_16x16x32_bf16 v[0:3], v[84:87], v[180:183], v[0:3]
	v_cvt_pk_bf16_f32 v184, v160, v161
	v_exp_f32_e32 v164, v164
	s_waitcnt lgkmcnt(13)
	v_mfma_f32_16x16x32_bf16 v[4:7], v[88:91], v[176:179], v[4:7]
	v_add_f32_e32 v199, v199, v163
	v_exp_f32_e32 v165, v165
	s_waitcnt lgkmcnt(12)
	v_mfma_f32_16x16x32_bf16 v[4:7], v[92:95], v[180:183], v[4:7]
	v_add_f32_e32 v194, v194, v164
	v_cvt_pk_bf16_f32 v185, v162, v163
	s_waitcnt lgkmcnt(11)
	v_mfma_f32_16x16x32_bf16 v[8:11], v[96:99], v[176:179], v[8:11]
	v_exp_f32_e32 v166, v166
	v_add_f32_e32 v199, v199, v165
	v_exp_f32_e32 v167, v167
	s_waitcnt lgkmcnt(10)
	v_mfma_f32_16x16x32_bf16 v[8:11], v[100:103], v[180:183], v[8:11]
	v_add_f32_e32 v194, v194, v166
	v_cvt_pk_bf16_f32 v186, v164, v165
	s_waitcnt lgkmcnt(9)
	v_mfma_f32_16x16x32_bf16 v[12:15], v[104:107], v[176:179], v[12:15]
	v_exp_f32_e32 v168, v168
	v_add_f32_e32 v199, v199, v167
	s_waitcnt lgkmcnt(8)
	v_mfma_f32_16x16x32_bf16 v[12:15], v[108:111], v[180:183], v[12:15]
	v_exp_f32_e32 v169, v169
	v_add_f32_e32 v194, v194, v168
	v_cvt_pk_bf16_f32 v187, v166, v167
	s_waitcnt lgkmcnt(7)
	v_mfma_f32_16x16x32_bf16 v[16:19], v[112:115], v[176:179], v[16:19]
	v_exp_f32_e32 v170, v170
	v_add_f32_e32 v199, v199, v169
	s_waitcnt lgkmcnt(6)
	v_mfma_f32_16x16x32_bf16 v[16:19], v[116:119], v[180:183], v[16:19]
	v_exp_f32_e32 v171, v171
	v_add_f32_e32 v194, v194, v170
	s_waitcnt lgkmcnt(5)
	v_mfma_f32_16x16x32_bf16 v[20:23], v[120:123], v[176:179], v[20:23]
	v_cvt_pk_bf16_f32 v188, v168, v169
	v_exp_f32_e32 v172, v172
	v_add_f32_e32 v199, v199, v171
	s_waitcnt lgkmcnt(4)
	v_mfma_f32_16x16x32_bf16 v[20:23], v[124:127], v[180:183], v[20:23]
	v_exp_f32_e32 v173, v173
	v_add_f32_e32 v194, v194, v172
	s_waitcnt lgkmcnt(3)
	v_mfma_f32_16x16x32_bf16 v[24:27], v[128:131], v[176:179], v[24:27]
	v_cvt_pk_bf16_f32 v189, v170, v171
	v_exp_f32_e32 v174, v174
	s_waitcnt lgkmcnt(2)
	v_mfma_f32_16x16x32_bf16 v[24:27], v[132:135], v[180:183], v[24:27]
	v_add_f32_e32 v199, v199, v173
	v_exp_f32_e32 v175, v175
	s_waitcnt lgkmcnt(1)
	v_mfma_f32_16x16x32_bf16 v[28:31], v[136:139], v[176:179], v[28:31]
	v_add_f32_e32 v194, v194, v174
	v_cvt_pk_bf16_f32 v190, v172, v173
	v_add_f32_e32 v199, v199, v175
	s_waitcnt lgkmcnt(0)
	v_mfma_f32_16x16x32_bf16 v[28:31], v[140:143], v[180:183], v[28:31]
	v_add_f32_e32 v194, v194, v199
	v_cvt_pk_bf16_f32 v191, v174, v175
	s_nop 1
	v_mfma_f32_16x16x32_bf16 v[32:35], v[80:83], v[184:187], v[32:35]
	v_mfma_f32_16x16x32_bf16 v[32:35], v[84:87], v[188:191], v[32:35]
	v_mfma_f32_16x16x32_bf16 v[36:39], v[88:91], v[184:187], v[36:39]
	v_mfma_f32_16x16x32_bf16 v[36:39], v[92:95], v[188:191], v[36:39]
	v_mfma_f32_16x16x32_bf16 v[40:43], v[96:99], v[184:187], v[40:43]
	v_mfma_f32_16x16x32_bf16 v[40:43], v[100:103], v[188:191], v[40:43]
	v_mfma_f32_16x16x32_bf16 v[44:47], v[104:107], v[184:187], v[44:47]
	v_mfma_f32_16x16x32_bf16 v[44:47], v[108:111], v[188:191], v[44:47]
	v_mfma_f32_16x16x32_bf16 v[48:51], v[112:115], v[184:187], v[48:51]
	v_mfma_f32_16x16x32_bf16 v[48:51], v[116:119], v[188:191], v[48:51]
	v_mfma_f32_16x16x32_bf16 v[52:55], v[120:123], v[184:187], v[52:55]
	v_mfma_f32_16x16x32_bf16 v[52:55], v[124:127], v[188:191], v[52:55]
	v_mfma_f32_16x16x32_bf16 v[56:59], v[128:131], v[184:187], v[56:59]
	v_mfma_f32_16x16x32_bf16 v[56:59], v[132:135], v[188:191], v[56:59]
	v_mfma_f32_16x16x32_bf16 v[60:63], v[136:139], v[184:187], v[60:63]
	v_mfma_f32_16x16x32_bf16 v[60:63], v[140:143], v[188:191], v[60:63]
.Lat_s2end7:
	s_add_i32 s0, s39, 2
	s_cmp_lt_i32 s0, s38
	s_cbranch_scc1 .Lat_w49
	s_waitcnt vmcnt(0)
	s_branch .Lat_wd10
.Lat_w49:
	s_waitcnt vmcnt(4)
.Lat_wd10:
	s_barrier
	v_add_u32_e32 v195, 0x8000, v195
	v_add_u32_e32 v196, 0x8000, v196
	v_add_u32_e32 v231, 0x8000, v231
	v_add_u32_e32 v232, 0x8000, v232
	v_add_u32_e32 v233, 0x8000, v233
	v_add_u32_e32 v234, 0x8000, v234
	v_and_b32_e32 v195, 0x1ffff, v195
	v_and_b32_e32 v196, 0x1ffff, v196
	v_and_b32_e32 v231, 0x1ffff, v231
	v_and_b32_e32 v232, 0x1ffff, v232
	v_and_b32_e32 v233, 0x1ffff, v233
	v_and_b32_e32 v234, 0x1ffff, v234
	s_add_i32 s91, s91, 1
	s_add_i32 s39, s39, 1
	s_cmp_lt_i32 s39, s38
	s_cbranch_scc1 .Lattn_tileA
	s_branch .Lattn_loopdone

.Lat_wd15:
	s_barrier
.Lattn_tileB:
	s_add_i32 s0, s39, 3
	s_cmp_lt_i32 s0, s38
	s_cbranch_scc0 .Lat_nodmaB16
	s_add_i32 s1, s91, 3
	s_and_b32 s1, s1, 3
	s_lshl_b32 s1, s1, 15
	s_add_i32 s1, s1, s40
	v_add_u32_e32 v210, s79, v197
	v_add_u32_e32 v211, s79, v198
	v_add_u32_e32 v212, s79, v229
	v_add_u32_e32 v213, s79, v230
	s_add_i32 m0, s1, 0x0
	s_nop 0
	global_load_lds_dwordx4 v210, s[86:87]
	s_add_i32 m0, s1, 0x400
	s_nop 0
	global_load_lds_dwordx4 v211, s[86:87]
	s_add_i32 m0, s1, 0x800
	s_nop 0
	global_load_lds_dwordx4 v212, s[86:87]
	s_add_i32 m0, s1, 0xc00
	s_nop 0
	global_load_lds_dwordx4 v213, s[86:87]
	s_add_i32 s79, s79, s41

.Lat_s2end17:
	v_add_u32_e32 v195, 0x8000, v195
	v_add_u32_e32 v196, 0x8000, v196
	v_add_u32_e32 v231, 0x8000, v231
	v_add_u32_e32 v232, 0x8000, v232
	v_add_u32_e32 v233, 0x8000, v233
	v_add_u32_e32 v234, 0x8000, v234
	v_and_b32_e32 v195, 0x1ffff, v195
	v_and_b32_e32 v196, 0x1ffff, v196
	v_and_b32_e32 v231, 0x1ffff, v231
	v_and_b32_e32 v232, 0x1ffff, v232
	v_and_b32_e32 v233, 0x1ffff, v233
	v_and_b32_e32 v234, 0x1ffff, v234
	s_add_i32 s91, s91, 1
	s_add_i32 s39, s39, 1
	s_cmp_lt_i32 s39, s38
	s_cbranch_scc0 .Lattn_loopdone
	s_lshl_b32 s96, s39, 6
	s_add_i32 s0, s37, 15
	s_cmp_gt_i32 s96, s0
	s_cselect_b32 vcc_hi, 1, 0
	s_cbranch_scc1 .Lat_s1end19
	ds_read_b128 v[80:83], v195
	ds_read_b128 v[84:87], v196
	ds_read_b128 v[88:91], v195 offset:4096
	ds_read_b128 v[92:95], v196 offset:4096
	ds_read_b128 v[96:99], v195 offset:8192
	ds_read_b128 v[100:103], v196 offset:8192
	ds_read_b128 v[104:107], v195 offset:12288
	ds_read_b128 v[108:111], v196 offset:12288
	s_waitcnt lgkmcnt(7)
	v_mfma_f32_16x16x32_bf16 v[144:147], v[80:83], v[64:67], v[248:251]
	ds_read_b128 v[112:115], v231
	s_waitcnt lgkmcnt(7)
	v_mfma_f32_16x16x32_bf16 v[144:147], v[84:87], v[68:71], v[144:147]
	ds_read_b128 v[116:119], v232
	s_waitcnt lgkmcnt(7)
	v_mfma_f32_16x16x32_bf16 v[148:151], v[88:91], v[64:67], v[248:251]
	ds_read_b128 v[120:123], v231 offset:4096
	s_waitcnt lgkmcnt(7)
	v_mfma_f32_16x16x32_bf16 v[148:151], v[92:95], v[68:71], v[148:151]
	ds_read_b128 v[124:127], v232 offset:4096
	s_waitcnt lgkmcnt(7)
	v_mfma_f32_16x16x32_bf16 v[152:155], v[96:99], v[64:67], v[248:251]
	ds_read_b128 v[128:131], v231 offset:8192
	s_waitcnt lgkmcnt(7)
	v_mfma_f32_16x16x32_bf16 v[152:155], v[100:103], v[68:71], v[152:155]
	ds_read_b128 v[132:135], v232 offset:8192
	s_waitcnt lgkmcnt(7)
	v_mfma_f32_16x16x32_bf16 v[156:159], v[104:107], v[64:67], v[248:251]
	ds_read_b128 v[136:139], v231 offset:12288
	s_waitcnt lgkmcnt(7)
	v_mfma_f32_16x16x32_bf16 v[156:159], v[108:111], v[68:71], v[156:159]
	ds_read_b128 v[140:143], v232 offset:12288
	s_waitcnt lgkmcnt(0)
	v_mfma_f32_16x16x32_bf16 v[160:163], v[112:115], v[72:75], v[248:251]
	v_mfma_f32_16x16x32_bf16 v[160:163], v[116:119], v[76:79], v[160:163]
	s_add_i32 s0, s96, 63
	s_cmp_gt_i32 s0, s37
	s_cselect_b32 s97, 1, 0
	s_cbranch_scc0 .Lat_nomask20
	v_subrev_u32_e32 v207, s96, v200
	v_cmp_gt_i32_e64 s[42:43], 0, v207
	v_cmp_gt_i32_e64 s[44:45], 1, v207
	v_cmp_gt_i32_e64 s[46:47], 2, v207
	v_cmp_gt_i32_e64 s[48:49], 3, v207
	v_cmp_gt_i32_e64 s[50:51], 4, v207
	v_cmp_gt_i32_e64 s[52:53], 5, v207
	v_cmp_gt_i32_e64 s[54:55], 6, v207
	v_cmp_gt_i32_e64 s[56:57], 7, v207
	v_cmp_gt_i32_e64 s[58:59], 32, v207
	v_cmp_gt_i32_e64 s[60:61], 33, v207
	v_cmp_gt_i32_e64 s[62:63], 34, v207
	v_cmp_gt_i32_e64 s[64:65], 35, v207
	v_cmp_gt_i32_e64 s[66:67], 36, v207
	v_cmp_gt_i32_e64 s[68:69], 37, v207
	v_cmp_gt_i32_e64 s[70:71], 38, v207
	v_cmp_gt_i32_e64 s[72:73], 39, v207
	v_cndmask_b32_e64 v144, v144, v201, s[42:43]
	v_cndmask_b32_e64 v145, v145, v201, s[44:45]
	v_cndmask_b32_e64 v146, v146, v201, s[46:47]
	v_cndmask_b32_e64 v147, v147, v201, s[48:49]
	v_cndmask_b32_e64 v148, v148, v201, s[50:51]
	v_cndmask_b32_e64 v149, v149, v201, s[52:53]
	v_cndmask_b32_e64 v150, v150, v201, s[54:55]
	v_cndmask_b32_e64 v151, v151, v201, s[56:57]
	v_cndmask_b32_e64 v152, v152, v201, s[58:59]
	v_cndmask_b32_e64 v153, v153, v201, s[60:61]
	v_cndmask_b32_e64 v154, v154, v201, s[62:63]
	v_cndmask_b32_e64 v155, v155, v201, s[64:65]
	v_cndmask_b32_e64 v156, v156, v201, s[66:67]
	v_cndmask_b32_e64 v157, v157, v201, s[68:69]
	v_cndmask_b32_e64 v158, v158, v201, s[70:71]
	v_cndmask_b32_e64 v159, v159, v201, s[72:73]

.Lat_wd22:
	s_barrier
	s_branch .Lattn_tileB
.Lattn_loopdone:
	s_add_i32 s22, s22, 1
	s_cmp_lt_u32 s22, 2
	s_cbranch_scc1 .Lattn_adv
	s_mov_b32 s22, 0
	s_add_i32 s21, s21, s78
.Lattn_adv:
	s_cmpk_lt_i32 s21, 0x200
	s_cselect_b32 s90, 1, 0
	s_cbranch_scc0 .Lattn_noNext
	s_mov_b32 s0, s21
	s_cmp_eq_u32 s7, 0
	s_cbranch_scc1 .Lat_noperm23
	s_lshl_b32 s0, s21, 3
	s_and_b32 s0, s0, 56
	s_bfe_u32 s1, s21, 0x20006
	s_or_b32 s0, s0, s1
	s_lshr_b32 s1, s21, 6
	s_and_b32 s1, s1, 0x1ffffffc
	s_add_i32 s0, s0, s1
	s_lshl_b32 s0, s0, 3
	s_bfe_u32 s1, s21, 0x30003
	s_or_b32 s0, s0, s1

.Lat_ubD25:
	s_lshl_b32 s38, s36, 1
	s_add_i32 s38, s38, 2
	s_add_i32 s1, s91, 0
	s_and_b32 s1, s1, 3
	s_lshl_b32 s1, s1, 15
	s_add_i32 s1, s1, s40
	v_add_u32_e32 v210, s79, v197
	v_add_u32_e32 v211, s79, v198
	v_add_u32_e32 v212, s79, v229
	v_add_u32_e32 v213, s79, v230
	s_add_i32 m0, s1, 0x0
	s_nop 0
	global_load_lds_dwordx4 v210, s[86:87]
	s_add_i32 m0, s1, 0x400
	s_nop 0
	global_load_lds_dwordx4 v211, s[86:87]
	s_add_i32 m0, s1, 0x800
	s_nop 0
	global_load_lds_dwordx4 v212, s[86:87]
	s_add_i32 m0, s1, 0xc00
	s_nop 0
	global_load_lds_dwordx4 v213, s[86:87]
	s_add_i32 s79, s79, s41
	s_add_i32 s1, s91, 1
	s_and_b32 s1, s1, 3
	s_lshl_b32 s1, s1, 15
	s_add_i32 s1, s1, s40
	v_add_u32_e32 v210, s79, v197
	v_add_u32_e32 v211, s79, v198
	v_add_u32_e32 v212, s79, v229
	v_add_u32_e32 v213, s79, v230
	s_add_i32 m0, s1, 0x0
	s_nop 0
	global_load_lds_dwordx4 v210, s[86:87]
	s_add_i32 m0, s1, 0x400
	s_nop 0
	global_load_lds_dwordx4 v211, s[86:87]
	s_add_i32 m0, s1, 0x800
	s_nop 0
	global_load_lds_dwordx4 v212, s[86:87]
	s_add_i32 m0, s1, 0xc00
	s_nop 0
	global_load_lds_dwordx4 v213, s[86:87]
	s_add_i32 s79, s79, s41
.Lattn_noNext:
	global_load_dwordx2 v[80:81], v215, s[18:19]
	global_load_dwordx2 v[82:83], v215, s[18:19] offset:32
	global_load_dwordx2 v[84:85], v215, s[18:19] offset:64
	global_load_dwordx2 v[86:87], v215, s[18:19] offset:96
	global_load_dwordx2 v[88:89], v215, s[18:19] offset:128
	global_load_dwordx2 v[90:91], v215, s[18:19] offset:160
	global_load_dwordx2 v[92:93], v215, s[18:19] offset:192
	global_load_dwordx2 v[94:95], v215, s[18:19] offset:224
	global_load_dwordx2 v[96:97], v215, s[28:29]
	global_load_dwordx2 v[112:113], v215, s[14:15]
	global_load_dwordx2 v[128:129], v215, s[16:17]
	global_load_dwordx2 v[98:99], v215, s[28:29] offset:32
	global_load_dwordx2 v[114:115], v215, s[14:15] offset:32
	global_load_dwordx2 v[130:131], v215, s[16:17] offset:32
	global_load_dwordx2 v[100:101], v215, s[28:29] offset:64
	global_load_dwordx2 v[116:117], v215, s[14:15] offset:64
	global_load_dwordx2 v[132:133], v215, s[16:17] offset:64
	global_load_dwordx2 v[102:103], v215, s[28:29] offset:96
	global_load_dwordx2 v[118:119], v215, s[14:15] offset:96
	global_load_dwordx2 v[134:135], v215, s[16:17] offset:96
	global_load_dwordx2 v[104:105], v215, s[28:29] offset:128
	global_load_dwordx2 v[120:121], v215, s[14:15] offset:128
	global_load_dwordx2 v[136:137], v215, s[16:17] offset:128
	global_load_dwordx2 v[106:107], v215, s[28:29] offset:160
	global_load_dwordx2 v[122:123], v215, s[14:15] offset:160
	global_load_dwordx2 v[138:139], v215, s[16:17] offset:160
	global_load_dwordx2 v[108:109], v215, s[28:29] offset:192
	global_load_dwordx2 v[124:125], v215, s[14:15] offset:192
	global_load_dwordx2 v[140:141], v215, s[16:17] offset:192
	global_load_dwordx2 v[110:111], v215, s[28:29] offset:224
	global_load_dwordx2 v[126:127], v215, s[14:15] offset:224
	global_load_dwordx2 v[142:143], v215, s[16:17] offset:224
	global_load_dwordx4 v[144:147], v216, s[4:5]
	global_load_dwordx4 v[148:151], v216, s[4:5] offset:64
	global_load_dwordx4 v[152:155], v216, s[4:5] offset:128
	global_load_dwordx4 v[156:159], v216, s[4:5] offset:192
	global_load_dwordx4 v[160:163], v216, s[4:5] offset:256
	global_load_dwordx4 v[164:167], v216, s[4:5] offset:320
	global_load_dwordx4 v[168:171], v216, s[4:5] offset:384
	global_load_dwordx4 v[172:175], v216, s[4:5] offset:448
	ds_bpermute_b32 v207, v208, v193
	ds_bpermute_b32 v217, v208, v194
	s_waitcnt lgkmcnt(0)
	v_add_f32_e32 v193, v193, v207
	v_add_f32_e32 v194, v194, v217
	ds_bpermute_b32 v207, v209, v193
	ds_bpermute_b32 v217, v209, v194
	s_waitcnt lgkmcnt(0)
	v_add_f32_e32 v193, v193, v207
	v_add_f32_e32 v194, v194, v217
	v_rcp_f32_e32 v222, v193
	v_rcp_f32_e32 v223, v194
	v_mov_b32_e32 v224, 0
	v_mul_f32_e32 v223, v223, v203
	v_mul_f32_e32 v32, v32, v223
	v_fma_f32 v0, v0, v222, -v32
	v_fmac_f32_e32 v224, v0, v0
	v_mul_f32_e32 v33, v33, v223
	v_fma_f32 v1, v1, v222, -v33
	v_fmac_f32_e32 v224, v1, v1
	v_mul_f32_e32 v34, v34, v223
	v_fma_f32 v2, v2, v222, -v34
	v_fmac_f32_e32 v224, v2, v2
	v_mul_f32_e32 v35, v35, v223
	v_fma_f32 v3, v3, v222, -v35
	v_fmac_f32_e32 v224, v3, v3
	v_mul_f32_e32 v36, v36, v223
	v_fma_f32 v4, v4, v222, -v36
	v_fmac_f32_e32 v224, v4, v4
	v_mul_f32_e32 v37, v37, v223
	v_fma_f32 v5, v5, v222, -v37
	v_fmac_f32_e32 v224, v5, v5
	v_mul_f32_e32 v38, v38, v223
	v_fma_f32 v6, v6, v222, -v38
	v_fmac_f32_e32 v224, v6, v6
	v_mul_f32_e32 v39, v39, v223
	v_fma_f32 v7, v7, v222, -v39
	v_fmac_f32_e32 v224, v7, v7
	v_mul_f32_e32 v40, v40, v223
	v_fma_f32 v8, v8, v222, -v40
	v_fmac_f32_e32 v224, v8, v8
	v_mul_f32_e32 v41, v41, v223
	v_fma_f32 v9, v9, v222, -v41
	v_fmac_f32_e32 v224, v9, v9
	v_mul_f32_e32 v42, v42, v223
	v_fma_f32 v10, v10, v222, -v42
	v_fmac_f32_e32 v224, v10, v10
	v_mul_f32_e32 v43, v43, v223
	v_fma_f32 v11, v11, v222, -v43
	v_fmac_f32_e32 v224, v11, v11
	v_mul_f32_e32 v44, v44, v223
	v_fma_f32 v12, v12, v222, -v44
	v_fmac_f32_e32 v224, v12, v12
	v_mul_f32_e32 v45, v45, v223
	v_fma_f32 v13, v13, v222, -v45
	v_fmac_f32_e32 v224, v13, v13
	v_mul_f32_e32 v46, v46, v223
	v_fma_f32 v14, v14, v222, -v46
	v_fmac_f32_e32 v224, v14, v14
	v_mul_f32_e32 v47, v47, v223
	v_fma_f32 v15, v15, v222, -v47
	v_fmac_f32_e32 v224, v15, v15
	v_mul_f32_e32 v48, v48, v223
	v_fma_f32 v16, v16, v222, -v48
	v_fmac_f32_e32 v224, v16, v16
	v_mul_f32_e32 v49, v49, v223
	v_fma_f32 v17, v17, v222, -v49
	v_fmac_f32_e32 v224, v17, v17
	v_mul_f32_e32 v50, v50, v223
	v_fma_f32 v18, v18, v222, -v50
	v_fmac_f32_e32 v224, v18, v18
	v_mul_f32_e32 v51, v51, v223
	v_fma_f32 v19, v19, v222, -v51
	v_fmac_f32_e32 v224, v19, v19
	v_mul_f32_e32 v52, v52, v223
	v_fma_f32 v20, v20, v222, -v52
	v_fmac_f32_e32 v224, v20, v20
	v_mul_f32_e32 v53, v53, v223
	v_fma_f32 v21, v21, v222, -v53
	v_fmac_f32_e32 v224, v21, v21
	v_mul_f32_e32 v54, v54, v223
	v_fma_f32 v22, v22, v222, -v54
	v_fmac_f32_e32 v224, v22, v22
	v_mul_f32_e32 v55, v55, v223
	v_fma_f32 v23, v23, v222, -v55
	v_fmac_f32_e32 v224, v23, v23
	v_mul_f32_e32 v56, v56, v223
	v_fma_f32 v24, v24, v222, -v56
	v_fmac_f32_e32 v224, v24, v24
	v_mul_f32_e32 v57, v57, v223
	v_fma_f32 v25, v25, v222, -v57
	v_fmac_f32_e32 v224, v25, v25
	v_mul_f32_e32 v58, v58, v223
	v_fma_f32 v26, v26, v222, -v58
	v_fmac_f32_e32 v224, v26, v26
	v_mul_f32_e32 v59, v59, v223
	v_fma_f32 v27, v27, v222, -v59
	v_fmac_f32_e32 v224, v27, v27
	v_mul_f32_e32 v60, v60, v223
	v_fma_f32 v28, v28, v222, -v60
	v_fmac_f32_e32 v224, v28, v28
	v_mul_f32_e32 v61, v61, v223
	v_fma_f32 v29, v29, v222, -v61
	v_fmac_f32_e32 v224, v29, v29
	v_mul_f32_e32 v62, v62, v223
	v_fma_f32 v30, v30, v222, -v62
	v_fmac_f32_e32 v224, v30, v30
	v_mul_f32_e32 v63, v63, v223
	v_fma_f32 v31, v31, v222, -v63
	v_fmac_f32_e32 v224, v31, v31
	global_load_dwordx4 v[32:35], v216, s[88:89]
	global_load_dwordx4 v[36:39], v216, s[88:89] offset:64
	global_load_dwordx4 v[40:43], v216, s[88:89] offset:128
	global_load_dwordx4 v[44:47], v216, s[88:89] offset:192
	global_load_dwordx4 v[48:51], v216, s[88:89] offset:256
	global_load_dwordx4 v[52:55], v216, s[88:89] offset:320
	global_load_dwordx4 v[56:59], v216, s[88:89] offset:384
	global_load_dwordx4 v[60:63], v216, s[88:89] offset:448
	s_waitcnt vmcnt(40)
	v_mov_b32_e32 v225, 0
	v_lshlrev_b32_e32 v207, 16, v80
	v_and_b32_e32 v217, 0xffff0000, v80
	v_fmac_f32_e32 v225, v207, v207
	v_fmac_f32_e32 v225, v217, v217
	v_lshlrev_b32_e32 v207, 16, v81
	v_and_b32_e32 v217, 0xffff0000, v81
	v_fmac_f32_e32 v225, v207, v207
	v_fmac_f32_e32 v225, v217, v217
	v_lshlrev_b32_e32 v207, 16, v82
	v_and_b32_e32 v217, 0xffff0000, v82
	v_fmac_f32_e32 v225, v207, v207
	v_fmac_f32_e32 v225, v217, v217
	v_lshlrev_b32_e32 v207, 16, v83
	v_and_b32_e32 v217, 0xffff0000, v83
	v_fmac_f32_e32 v225, v207, v207
	v_fmac_f32_e32 v225, v217, v217
	v_lshlrev_b32_e32 v207, 16, v84
	v_and_b32_e32 v217, 0xffff0000, v84
	v_fmac_f32_e32 v225, v207, v207
	v_fmac_f32_e32 v225, v217, v217
	v_lshlrev_b32_e32 v207, 16, v85
	v_and_b32_e32 v217, 0xffff0000, v85
	v_fmac_f32_e32 v225, v207, v207
	v_fmac_f32_e32 v225, v217, v217
	v_lshlrev_b32_e32 v207, 16, v86
	v_and_b32_e32 v217, 0xffff0000, v86
	v_fmac_f32_e32 v225, v207, v207
	v_fmac_f32_e32 v225, v217, v217
	v_lshlrev_b32_e32 v207, 16, v87
	v_and_b32_e32 v217, 0xffff0000, v87
	v_fmac_f32_e32 v225, v207, v207
	v_fmac_f32_e32 v225, v217, v217
	v_lshlrev_b32_e32 v207, 16, v88
	v_and_b32_e32 v217, 0xffff0000, v88
	v_fmac_f32_e32 v225, v207, v207
	v_fmac_f32_e32 v225, v217, v217
	v_lshlrev_b32_e32 v207, 16, v89
	v_and_b32_e32 v217, 0xffff0000, v89
	v_fmac_f32_e32 v225, v207, v207
	v_fmac_f32_e32 v225, v217, v217
	v_lshlrev_b32_e32 v207, 16, v90
	v_and_b32_e32 v217, 0xffff0000, v90
	v_fmac_f32_e32 v225, v207, v207
	v_fmac_f32_e32 v225, v217, v217
	v_lshlrev_b32_e32 v207, 16, v91
	v_and_b32_e32 v217, 0xffff0000, v91
	v_fmac_f32_e32 v225, v207, v207
	v_fmac_f32_e32 v225, v217, v217
	v_lshlrev_b32_e32 v207, 16, v92
	v_and_b32_e32 v217, 0xffff0000, v92
	v_fmac_f32_e32 v225, v207, v207
	v_fmac_f32_e32 v225, v217, v217
	v_lshlrev_b32_e32 v207, 16, v93
	v_and_b32_e32 v217, 0xffff0000, v93
	v_fmac_f32_e32 v225, v207, v207
	v_fmac_f32_e32 v225, v217, v217
	v_lshlrev_b32_e32 v207, 16, v94
	v_and_b32_e32 v217, 0xffff0000, v94
	v_fmac_f32_e32 v225, v207, v207
	v_fmac_f32_e32 v225, v217, v217
	v_lshlrev_b32_e32 v207, 16, v95
	v_and_b32_e32 v217, 0xffff0000, v95
	v_fmac_f32_e32 v225, v207, v207
	v_fmac_f32_e32 v225, v217, v217
	ds_bpermute_b32 v207, v208, v224
	ds_bpermute_b32 v217, v208, v225
	s_waitcnt lgkmcnt(0)
	v_add_f32_e32 v224, v224, v207
	v_add_f32_e32 v225, v225, v217
	ds_bpermute_b32 v207, v209, v224
	ds_bpermute_b32 v217, v209, v225
	s_waitcnt lgkmcnt(0)
	v_add_f32_e32 v224, v224, v207
	v_add_f32_e32 v225, v225, v217
	v_mov_b32_e32 v218, 0x358637bd
	v_fmac_f32_e32 v218, 0x3c000000, v224
	v_mov_b32_e32 v219, 0x358637bd
	v_fmac_f32_e32 v219, 0x3c000000, v225
	v_rsq_f32_e32 v226, v218
	v_rsq_f32_e32 v227, v219
	s_nop 0
	v_mul_f32_e32 v226, 0x3f4ccccd, v226
	s_waitcnt vmcnt(0)
	v_lshlrev_b32_e32 v176, 16, v96
	v_lshlrev_b32_e32 v177, 16, v112
	v_lshlrev_b32_e32 v178, 16, v128
	v_lshlrev_b32_e32 v179, 16, v80
	v_mul_f32_e32 v184, 0xbfb8aa3b, v176
	v_mul_f32_e32 v185, 0xbfb8aa3b, v177
	v_mul_f32_e32 v186, 0xbfb8aa3b, v178
	v_exp_f32_e32 v184, v184
	v_exp_f32_e32 v185, v185
	v_exp_f32_e32 v186, v186
	v_mul_f32_e32 v179, v179, v227
	v_add_f32_e32 v184, 1.0, v184
	v_add_f32_e32 v185, 1.0, v185
	v_add_f32_e32 v186, 1.0, v186
	v_rcp_f32_e32 v184, v184
	v_rcp_f32_e32 v185, v185
	v_rcp_f32_e32 v186, v186
	v_mul_f32_e32 v179, v179, v32
	v_mul_f32_e32 v176, v176, v184
	v_mul_f32_e32 v178, v0, v226
	v_mul_f32_e32 v179, v179, v176
	v_mul_f32_e32 v178, v178, v144
	v_mul_f32_e32 v179, v179, v185
	v_fmac_f32_e32 v179, v186, v178
	v_and_b32_e32 v180, 0xffff0000, v96
	v_and_b32_e32 v181, 0xffff0000, v112
	v_and_b32_e32 v182, 0xffff0000, v128
	v_and_b32_e32 v183, 0xffff0000, v80
	v_mul_f32_e32 v187, 0xbfb8aa3b, v180
	v_mul_f32_e32 v188, 0xbfb8aa3b, v181
	v_mul_f32_e32 v189, 0xbfb8aa3b, v182
	v_exp_f32_e32 v187, v187
	v_exp_f32_e32 v188, v188
	v_exp_f32_e32 v189, v189
	v_mul_f32_e32 v183, v183, v227
	v_add_f32_e32 v187, 1.0, v187
	v_add_f32_e32 v188, 1.0, v188
	v_add_f32_e32 v189, 1.0, v189
	v_rcp_f32_e32 v187, v187
	v_rcp_f32_e32 v188, v188
	v_rcp_f32_e32 v189, v189
	v_mul_f32_e32 v183, v183, v33
	v_mul_f32_e32 v180, v180, v187
	v_mul_f32_e32 v182, v1, v226
	v_mul_f32_e32 v183, v183, v180
	v_mul_f32_e32 v182, v182, v145
	v_mul_f32_e32 v183, v183, v188
	v_fmac_f32_e32 v183, v189, v182
	v_cvt_pk_bf16_f32 v190, v179, v183
	v_lshlrev_b32_e32 v176, 16, v97
	v_lshlrev_b32_e32 v177, 16, v113
	v_lshlrev_b32_e32 v178, 16, v129
	v_lshlrev_b32_e32 v179, 16, v81
	v_mul_f32_e32 v184, 0xbfb8aa3b, v176
	v_mul_f32_e32 v185, 0xbfb8aa3b, v177
	v_mul_f32_e32 v186, 0xbfb8aa3b, v178
	v_exp_f32_e32 v184, v184
	v_exp_f32_e32 v185, v185
	v_exp_f32_e32 v186, v186
	v_mul_f32_e32 v179, v179, v227
	v_add_f32_e32 v184, 1.0, v184
	v_add_f32_e32 v185, 1.0, v185
	v_add_f32_e32 v186, 1.0, v186
	v_rcp_f32_e32 v184, v184
	v_rcp_f32_e32 v185, v185
	v_rcp_f32_e32 v186, v186
	v_mul_f32_e32 v179, v179, v34
	v_mul_f32_e32 v176, v176, v184
	v_mul_f32_e32 v178, v2, v226
	v_mul_f32_e32 v179, v179, v176
	v_mul_f32_e32 v178, v178, v146
	v_mul_f32_e32 v179, v179, v185
	v_fmac_f32_e32 v179, v186, v178
	v_and_b32_e32 v180, 0xffff0000, v97
	v_and_b32_e32 v181, 0xffff0000, v113
	v_and_b32_e32 v182, 0xffff0000, v129
	v_and_b32_e32 v183, 0xffff0000, v81
	v_mul_f32_e32 v187, 0xbfb8aa3b, v180
	v_mul_f32_e32 v188, 0xbfb8aa3b, v181
	v_mul_f32_e32 v189, 0xbfb8aa3b, v182
	v_exp_f32_e32 v187, v187
	v_exp_f32_e32 v188, v188
	v_exp_f32_e32 v189, v189
	v_mul_f32_e32 v183, v183, v227
	v_add_f32_e32 v187, 1.0, v187
	v_add_f32_e32 v188, 1.0, v188
	v_add_f32_e32 v189, 1.0, v189
	v_rcp_f32_e32 v187, v187
	v_rcp_f32_e32 v188, v188
	v_rcp_f32_e32 v189, v189
	v_mul_f32_e32 v183, v183, v35
	v_mul_f32_e32 v180, v180, v187
	v_mul_f32_e32 v182, v3, v226
	v_mul_f32_e32 v183, v183, v180
	v_mul_f32_e32 v182, v182, v147
	v_mul_f32_e32 v183, v183, v188
	v_fmac_f32_e32 v183, v189, v182
	v_cvt_pk_bf16_f32 v191, v179, v183
	global_store_dwordx2 v215, v[190:191], s[28:29]
	s_nop 1
	v_lshlrev_b32_e32 v176, 16, v98
	v_lshlrev_b32_e32 v177, 16, v114
	v_lshlrev_b32_e32 v178, 16, v130
	v_lshlrev_b32_e32 v179, 16, v82
	v_mul_f32_e32 v184, 0xbfb8aa3b, v176
	v_mul_f32_e32 v185, 0xbfb8aa3b, v177
	v_mul_f32_e32 v186, 0xbfb8aa3b, v178
	v_exp_f32_e32 v184, v184
	v_exp_f32_e32 v185, v185
	v_exp_f32_e32 v186, v186
	v_mul_f32_e32 v179, v179, v227
	v_add_f32_e32 v184, 1.0, v184
	v_add_f32_e32 v185, 1.0, v185
	v_add_f32_e32 v186, 1.0, v186
	v_rcp_f32_e32 v184, v184
	v_rcp_f32_e32 v185, v185
	v_rcp_f32_e32 v186, v186
	v_mul_f32_e32 v179, v179, v36
	v_mul_f32_e32 v176, v176, v184
	v_mul_f32_e32 v178, v4, v226
	v_mul_f32_e32 v179, v179, v176
	v_mul_f32_e32 v178, v178, v148
	v_mul_f32_e32 v179, v179, v185
	v_fmac_f32_e32 v179, v186, v178
	v_and_b32_e32 v180, 0xffff0000, v98
	v_and_b32_e32 v181, 0xffff0000, v114
	v_and_b32_e32 v182, 0xffff0000, v130
	v_and_b32_e32 v183, 0xffff0000, v82
	v_mul_f32_e32 v187, 0xbfb8aa3b, v180
	v_mul_f32_e32 v188, 0xbfb8aa3b, v181
	v_mul_f32_e32 v189, 0xbfb8aa3b, v182
	v_exp_f32_e32 v187, v187
	v_exp_f32_e32 v188, v188
	v_exp_f32_e32 v189, v189
	v_mul_f32_e32 v183, v183, v227
	v_add_f32_e32 v187, 1.0, v187
	v_add_f32_e32 v188, 1.0, v188
	v_add_f32_e32 v189, 1.0, v189
	v_rcp_f32_e32 v187, v187
	v_rcp_f32_e32 v188, v188
	v_rcp_f32_e32 v189, v189
	v_mul_f32_e32 v183, v183, v37
	v_mul_f32_e32 v180, v180, v187
	v_mul_f32_e32 v182, v5, v226
	v_mul_f32_e32 v183, v183, v180
	v_mul_f32_e32 v182, v182, v149
	v_mul_f32_e32 v183, v183, v188
	v_fmac_f32_e32 v183, v189, v182
	v_cvt_pk_bf16_f32 v190, v179, v183
	v_lshlrev_b32_e32 v176, 16, v99
	v_lshlrev_b32_e32 v177, 16, v115
	v_lshlrev_b32_e32 v178, 16, v131
	v_lshlrev_b32_e32 v179, 16, v83
	v_mul_f32_e32 v184, 0xbfb8aa3b, v176
	v_mul_f32_e32 v185, 0xbfb8aa3b, v177
	v_mul_f32_e32 v186, 0xbfb8aa3b, v178
	v_exp_f32_e32 v184, v184
	v_exp_f32_e32 v185, v185
	v_exp_f32_e32 v186, v186
	v_mul_f32_e32 v179, v179, v227
	v_add_f32_e32 v184, 1.0, v184
	v_add_f32_e32 v185, 1.0, v185
	v_add_f32_e32 v186, 1.0, v186
	v_rcp_f32_e32 v184, v184
	v_rcp_f32_e32 v185, v185
	v_rcp_f32_e32 v186, v186
	v_mul_f32_e32 v179, v179, v38
	v_mul_f32_e32 v176, v176, v184
	v_mul_f32_e32 v178, v6, v226
	v_mul_f32_e32 v179, v179, v176
	v_mul_f32_e32 v178, v178, v150
	v_mul_f32_e32 v179, v179, v185
	v_fmac_f32_e32 v179, v186, v178
	v_and_b32_e32 v180, 0xffff0000, v99
	v_and_b32_e32 v181, 0xffff0000, v115
	v_and_b32_e32 v182, 0xffff0000, v131
	v_and_b32_e32 v183, 0xffff0000, v83
	v_mul_f32_e32 v187, 0xbfb8aa3b, v180
	v_mul_f32_e32 v188, 0xbfb8aa3b, v181
	v_mul_f32_e32 v189, 0xbfb8aa3b, v182
	v_exp_f32_e32 v187, v187
	v_exp_f32_e32 v188, v188
	v_exp_f32_e32 v189, v189
	v_mul_f32_e32 v183, v183, v227
	v_add_f32_e32 v187, 1.0, v187
	v_add_f32_e32 v188, 1.0, v188
	v_add_f32_e32 v189, 1.0, v189
	v_rcp_f32_e32 v187, v187
	v_rcp_f32_e32 v188, v188
	v_rcp_f32_e32 v189, v189
	v_mul_f32_e32 v183, v183, v39
	v_mul_f32_e32 v180, v180, v187
	v_mul_f32_e32 v182, v7, v226
	v_mul_f32_e32 v183, v183, v180
	v_mul_f32_e32 v182, v182, v151
	v_mul_f32_e32 v183, v183, v188
	v_fmac_f32_e32 v183, v189, v182
	v_cvt_pk_bf16_f32 v191, v179, v183
	global_store_dwordx2 v215, v[190:191], s[28:29] offset:32
	s_nop 1
	v_lshlrev_b32_e32 v176, 16, v100
	v_lshlrev_b32_e32 v177, 16, v116
	v_lshlrev_b32_e32 v178, 16, v132
	v_lshlrev_b32_e32 v179, 16, v84
	v_mul_f32_e32 v184, 0xbfb8aa3b, v176
	v_mul_f32_e32 v185, 0xbfb8aa3b, v177
	v_mul_f32_e32 v186, 0xbfb8aa3b, v178
	v_exp_f32_e32 v184, v184
	v_exp_f32_e32 v185, v185
	v_exp_f32_e32 v186, v186
	v_mul_f32_e32 v179, v179, v227
	v_add_f32_e32 v184, 1.0, v184
	v_add_f32_e32 v185, 1.0, v185
	v_add_f32_e32 v186, 1.0, v186
	v_rcp_f32_e32 v184, v184
	v_rcp_f32_e32 v185, v185
	v_rcp_f32_e32 v186, v186
	v_mul_f32_e32 v179, v179, v40
	v_mul_f32_e32 v176, v176, v184
	v_mul_f32_e32 v178, v8, v226
	v_mul_f32_e32 v179, v179, v176
	v_mul_f32_e32 v178, v178, v152
	v_mul_f32_e32 v179, v179, v185
	v_fmac_f32_e32 v179, v186, v178
	v_and_b32_e32 v180, 0xffff0000, v100
	v_and_b32_e32 v181, 0xffff0000, v116
	v_and_b32_e32 v182, 0xffff0000, v132
	v_and_b32_e32 v183, 0xffff0000, v84
	v_mul_f32_e32 v187, 0xbfb8aa3b, v180
	v_mul_f32_e32 v188, 0xbfb8aa3b, v181
	v_mul_f32_e32 v189, 0xbfb8aa3b, v182
	v_exp_f32_e32 v187, v187
	v_exp_f32_e32 v188, v188
	v_exp_f32_e32 v189, v189
	v_mul_f32_e32 v183, v183, v227
	v_add_f32_e32 v187, 1.0, v187
	v_add_f32_e32 v188, 1.0, v188
	v_add_f32_e32 v189, 1.0, v189
	v_rcp_f32_e32 v187, v187
	v_rcp_f32_e32 v188, v188
	v_rcp_f32_e32 v189, v189
	v_mul_f32_e32 v183, v183, v41
	v_mul_f32_e32 v180, v180, v187
	v_mul_f32_e32 v182, v9, v226
	v_mul_f32_e32 v183, v183, v180
	v_mul_f32_e32 v182, v182, v153
	v_mul_f32_e32 v183, v183, v188
	v_fmac_f32_e32 v183, v189, v182
	v_cvt_pk_bf16_f32 v190, v179, v183
	v_lshlrev_b32_e32 v176, 16, v101
	v_lshlrev_b32_e32 v177, 16, v117
	v_lshlrev_b32_e32 v178, 16, v133
	v_lshlrev_b32_e32 v179, 16, v85
	v_mul_f32_e32 v184, 0xbfb8aa3b, v176
	v_mul_f32_e32 v185, 0xbfb8aa3b, v177
	v_mul_f32_e32 v186, 0xbfb8aa3b, v178
	v_exp_f32_e32 v184, v184
	v_exp_f32_e32 v185, v185
	v_exp_f32_e32 v186, v186
	v_mul_f32_e32 v179, v179, v227
	v_add_f32_e32 v184, 1.0, v184
	v_add_f32_e32 v185, 1.0, v185
	v_add_f32_e32 v186, 1.0, v186
	v_rcp_f32_e32 v184, v184
	v_rcp_f32_e32 v185, v185
	v_rcp_f32_e32 v186, v186
	v_mul_f32_e32 v179, v179, v42
	v_mul_f32_e32 v176, v176, v184
	v_mul_f32_e32 v178, v10, v226
	v_mul_f32_e32 v179, v179, v176
	v_mul_f32_e32 v178, v178, v154
	v_mul_f32_e32 v179, v179, v185
	v_fmac_f32_e32 v179, v186, v178
	v_and_b32_e32 v180, 0xffff0000, v101
	v_and_b32_e32 v181, 0xffff0000, v117
	v_and_b32_e32 v182, 0xffff0000, v133
	v_and_b32_e32 v183, 0xffff0000, v85
	v_mul_f32_e32 v187, 0xbfb8aa3b, v180
	v_mul_f32_e32 v188, 0xbfb8aa3b, v181
	v_mul_f32_e32 v189, 0xbfb8aa3b, v182
	v_exp_f32_e32 v187, v187
	v_exp_f32_e32 v188, v188
	v_exp_f32_e32 v189, v189
	v_mul_f32_e32 v183, v183, v227
	v_add_f32_e32 v187, 1.0, v187
	v_add_f32_e32 v188, 1.0, v188
	v_add_f32_e32 v189, 1.0, v189
	v_rcp_f32_e32 v187, v187
	v_rcp_f32_e32 v188, v188
	v_rcp_f32_e32 v189, v189
	v_mul_f32_e32 v183, v183, v43
	v_mul_f32_e32 v180, v180, v187
	v_mul_f32_e32 v182, v11, v226
	v_mul_f32_e32 v183, v183, v180
	v_mul_f32_e32 v182, v182, v155
	v_mul_f32_e32 v183, v183, v188
	v_fmac_f32_e32 v183, v189, v182
	v_cvt_pk_bf16_f32 v191, v179, v183
	global_store_dwordx2 v215, v[190:191], s[28:29] offset:64
	s_nop 1
	v_lshlrev_b32_e32 v176, 16, v102
	v_lshlrev_b32_e32 v177, 16, v118
	v_lshlrev_b32_e32 v178, 16, v134
	v_lshlrev_b32_e32 v179, 16, v86
	v_mul_f32_e32 v184, 0xbfb8aa3b, v176
	v_mul_f32_e32 v185, 0xbfb8aa3b, v177
	v_mul_f32_e32 v186, 0xbfb8aa3b, v178
	v_exp_f32_e32 v184, v184
	v_exp_f32_e32 v185, v185
	v_exp_f32_e32 v186, v186
	v_mul_f32_e32 v179, v179, v227
	v_add_f32_e32 v184, 1.0, v184
	v_add_f32_e32 v185, 1.0, v185
	v_add_f32_e32 v186, 1.0, v186
	v_rcp_f32_e32 v184, v184
	v_rcp_f32_e32 v185, v185
	v_rcp_f32_e32 v186, v186
	v_mul_f32_e32 v179, v179, v44
	v_mul_f32_e32 v176, v176, v184
	v_mul_f32_e32 v178, v12, v226
	v_mul_f32_e32 v179, v179, v176
	v_mul_f32_e32 v178, v178, v156
	v_mul_f32_e32 v179, v179, v185
	v_fmac_f32_e32 v179, v186, v178
	v_and_b32_e32 v180, 0xffff0000, v102
	v_and_b32_e32 v181, 0xffff0000, v118
	v_and_b32_e32 v182, 0xffff0000, v134
	v_and_b32_e32 v183, 0xffff0000, v86
	v_mul_f32_e32 v187, 0xbfb8aa3b, v180
	v_mul_f32_e32 v188, 0xbfb8aa3b, v181
	v_mul_f32_e32 v189, 0xbfb8aa3b, v182
	v_exp_f32_e32 v187, v187
	v_exp_f32_e32 v188, v188
	v_exp_f32_e32 v189, v189
	v_mul_f32_e32 v183, v183, v227
	v_add_f32_e32 v187, 1.0, v187
	v_add_f32_e32 v188, 1.0, v188
	v_add_f32_e32 v189, 1.0, v189
	v_rcp_f32_e32 v187, v187
	v_rcp_f32_e32 v188, v188
	v_rcp_f32_e32 v189, v189
	v_mul_f32_e32 v183, v183, v45
	v_mul_f32_e32 v180, v180, v187
	v_mul_f32_e32 v182, v13, v226
	v_mul_f32_e32 v183, v183, v180
	v_mul_f32_e32 v182, v182, v157
	v_mul_f32_e32 v183, v183, v188
	v_fmac_f32_e32 v183, v189, v182
	v_cvt_pk_bf16_f32 v190, v179, v183
	v_lshlrev_b32_e32 v176, 16, v103
	v_lshlrev_b32_e32 v177, 16, v119
	v_lshlrev_b32_e32 v178, 16, v135
	v_lshlrev_b32_e32 v179, 16, v87
	v_mul_f32_e32 v184, 0xbfb8aa3b, v176
	v_mul_f32_e32 v185, 0xbfb8aa3b, v177
	v_mul_f32_e32 v186, 0xbfb8aa3b, v178
	v_exp_f32_e32 v184, v184
	v_exp_f32_e32 v185, v185
	v_exp_f32_e32 v186, v186
	v_mul_f32_e32 v179, v179, v227
	v_add_f32_e32 v184, 1.0, v184
	v_add_f32_e32 v185, 1.0, v185
	v_add_f32_e32 v186, 1.0, v186
	v_rcp_f32_e32 v184, v184
	v_rcp_f32_e32 v185, v185
	v_rcp_f32_e32 v186, v186
	v_mul_f32_e32 v179, v179, v46
	v_mul_f32_e32 v176, v176, v184
	v_mul_f32_e32 v178, v14, v226
	v_mul_f32_e32 v179, v179, v176
	v_mul_f32_e32 v178, v178, v158
	v_mul_f32_e32 v179, v179, v185
	v_fmac_f32_e32 v179, v186, v178
	v_and_b32_e32 v180, 0xffff0000, v103
	v_and_b32_e32 v181, 0xffff0000, v119
	v_and_b32_e32 v182, 0xffff0000, v135
	v_and_b32_e32 v183, 0xffff0000, v87
	v_mul_f32_e32 v187, 0xbfb8aa3b, v180
	v_mul_f32_e32 v188, 0xbfb8aa3b, v181
	v_mul_f32_e32 v189, 0xbfb8aa3b, v182
	v_exp_f32_e32 v187, v187
	v_exp_f32_e32 v188, v188
	v_exp_f32_e32 v189, v189
	v_mul_f32_e32 v183, v183, v227
	v_add_f32_e32 v187, 1.0, v187
	v_add_f32_e32 v188, 1.0, v188
	v_add_f32_e32 v189, 1.0, v189
	v_rcp_f32_e32 v187, v187
	v_rcp_f32_e32 v188, v188
	v_rcp_f32_e32 v189, v189
	v_mul_f32_e32 v183, v183, v47
	v_mul_f32_e32 v180, v180, v187
	v_mul_f32_e32 v182, v15, v226
	v_mul_f32_e32 v183, v183, v180
	v_mul_f32_e32 v182, v182, v159
	v_mul_f32_e32 v183, v183, v188
	v_fmac_f32_e32 v183, v189, v182
	v_cvt_pk_bf16_f32 v191, v179, v183
	global_store_dwordx2 v215, v[190:191], s[28:29] offset:96
	s_nop 1
	v_lshlrev_b32_e32 v176, 16, v104
	v_lshlrev_b32_e32 v177, 16, v120
	v_lshlrev_b32_e32 v178, 16, v136
	v_lshlrev_b32_e32 v179, 16, v88
	v_mul_f32_e32 v184, 0xbfb8aa3b, v176
	v_mul_f32_e32 v185, 0xbfb8aa3b, v177
	v_mul_f32_e32 v186, 0xbfb8aa3b, v178
	v_exp_f32_e32 v184, v184
	v_exp_f32_e32 v185, v185
	v_exp_f32_e32 v186, v186
	v_mul_f32_e32 v179, v179, v227
	v_add_f32_e32 v184, 1.0, v184
	v_add_f32_e32 v185, 1.0, v185
	v_add_f32_e32 v186, 1.0, v186
	v_rcp_f32_e32 v184, v184
	v_rcp_f32_e32 v185, v185
	v_rcp_f32_e32 v186, v186
	v_mul_f32_e32 v179, v179, v48
	v_mul_f32_e32 v176, v176, v184
	v_mul_f32_e32 v178, v16, v226
	v_mul_f32_e32 v179, v179, v176
	v_mul_f32_e32 v178, v178, v160
	v_mul_f32_e32 v179, v179, v185
	v_fmac_f32_e32 v179, v186, v178
	v_and_b32_e32 v180, 0xffff0000, v104
	v_and_b32_e32 v181, 0xffff0000, v120
	v_and_b32_e32 v182, 0xffff0000, v136
	v_and_b32_e32 v183, 0xffff0000, v88
	v_mul_f32_e32 v187, 0xbfb8aa3b, v180
	v_mul_f32_e32 v188, 0xbfb8aa3b, v181
	v_mul_f32_e32 v189, 0xbfb8aa3b, v182
	v_exp_f32_e32 v187, v187
	v_exp_f32_e32 v188, v188
	v_exp_f32_e32 v189, v189
	v_mul_f32_e32 v183, v183, v227
	v_add_f32_e32 v187, 1.0, v187
	v_add_f32_e32 v188, 1.0, v188
	v_add_f32_e32 v189, 1.0, v189
	v_rcp_f32_e32 v187, v187
	v_rcp_f32_e32 v188, v188
	v_rcp_f32_e32 v189, v189
	v_mul_f32_e32 v183, v183, v49
	v_mul_f32_e32 v180, v180, v187
	v_mul_f32_e32 v182, v17, v226
	v_mul_f32_e32 v183, v183, v180
	v_mul_f32_e32 v182, v182, v161
	v_mul_f32_e32 v183, v183, v188
	v_fmac_f32_e32 v183, v189, v182
	v_cvt_pk_bf16_f32 v190, v179, v183
	v_lshlrev_b32_e32 v176, 16, v105
	v_lshlrev_b32_e32 v177, 16, v121
	v_lshlrev_b32_e32 v178, 16, v137
	v_lshlrev_b32_e32 v179, 16, v89
	v_mul_f32_e32 v184, 0xbfb8aa3b, v176
	v_mul_f32_e32 v185, 0xbfb8aa3b, v177
	v_mul_f32_e32 v186, 0xbfb8aa3b, v178
	v_exp_f32_e32 v184, v184
	v_exp_f32_e32 v185, v185
	v_exp_f32_e32 v186, v186
	v_mul_f32_e32 v179, v179, v227
	v_add_f32_e32 v184, 1.0, v184
	v_add_f32_e32 v185, 1.0, v185
	v_add_f32_e32 v186, 1.0, v186
	v_rcp_f32_e32 v184, v184
	v_rcp_f32_e32 v185, v185
	v_rcp_f32_e32 v186, v186
	v_mul_f32_e32 v179, v179, v50
	v_mul_f32_e32 v176, v176, v184
	v_mul_f32_e32 v178, v18, v226
	v_mul_f32_e32 v179, v179, v176
	v_mul_f32_e32 v178, v178, v162
	v_mul_f32_e32 v179, v179, v185
	v_fmac_f32_e32 v179, v186, v178
	v_and_b32_e32 v180, 0xffff0000, v105
	v_and_b32_e32 v181, 0xffff0000, v121
	v_and_b32_e32 v182, 0xffff0000, v137
	v_and_b32_e32 v183, 0xffff0000, v89
	v_mul_f32_e32 v187, 0xbfb8aa3b, v180
	v_mul_f32_e32 v188, 0xbfb8aa3b, v181
	v_mul_f32_e32 v189, 0xbfb8aa3b, v182
	v_exp_f32_e32 v187, v187
	v_exp_f32_e32 v188, v188
	v_exp_f32_e32 v189, v189
	v_mul_f32_e32 v183, v183, v227
	v_add_f32_e32 v187, 1.0, v187
	v_add_f32_e32 v188, 1.0, v188
	v_add_f32_e32 v189, 1.0, v189
	v_rcp_f32_e32 v187, v187
	v_rcp_f32_e32 v188, v188
	v_rcp_f32_e32 v189, v189
	v_mul_f32_e32 v183, v183, v51
	v_mul_f32_e32 v180, v180, v187
	v_mul_f32_e32 v182, v19, v226
	v_mul_f32_e32 v183, v183, v180
	v_mul_f32_e32 v182, v182, v163
	v_mul_f32_e32 v183, v183, v188
	v_fmac_f32_e32 v183, v189, v182
	v_cvt_pk_bf16_f32 v191, v179, v183
	global_store_dwordx2 v215, v[190:191], s[28:29] offset:128
	s_nop 1
	v_lshlrev_b32_e32 v176, 16, v106
	v_lshlrev_b32_e32 v177, 16, v122
	v_lshlrev_b32_e32 v178, 16, v138
	v_lshlrev_b32_e32 v179, 16, v90
	v_mul_f32_e32 v184, 0xbfb8aa3b, v176
	v_mul_f32_e32 v185, 0xbfb8aa3b, v177
	v_mul_f32_e32 v186, 0xbfb8aa3b, v178
	v_exp_f32_e32 v184, v184
	v_exp_f32_e32 v185, v185
	v_exp_f32_e32 v186, v186
	v_mul_f32_e32 v179, v179, v227
	v_add_f32_e32 v184, 1.0, v184
	v_add_f32_e32 v185, 1.0, v185
	v_add_f32_e32 v186, 1.0, v186
	v_rcp_f32_e32 v184, v184
	v_rcp_f32_e32 v185, v185
	v_rcp_f32_e32 v186, v186
	v_mul_f32_e32 v179, v179, v52
	v_mul_f32_e32 v176, v176, v184
	v_mul_f32_e32 v178, v20, v226
	v_mul_f32_e32 v179, v179, v176
	v_mul_f32_e32 v178, v178, v164
	v_mul_f32_e32 v179, v179, v185
	v_fmac_f32_e32 v179, v186, v178
	v_and_b32_e32 v180, 0xffff0000, v106
	v_and_b32_e32 v181, 0xffff0000, v122
	v_and_b32_e32 v182, 0xffff0000, v138
	v_and_b32_e32 v183, 0xffff0000, v90
	v_mul_f32_e32 v187, 0xbfb8aa3b, v180
	v_mul_f32_e32 v188, 0xbfb8aa3b, v181
	v_mul_f32_e32 v189, 0xbfb8aa3b, v182
	v_exp_f32_e32 v187, v187
	v_exp_f32_e32 v188, v188
	v_exp_f32_e32 v189, v189
	v_mul_f32_e32 v183, v183, v227
	v_add_f32_e32 v187, 1.0, v187
	v_add_f32_e32 v188, 1.0, v188
	v_add_f32_e32 v189, 1.0, v189
	v_rcp_f32_e32 v187, v187
	v_rcp_f32_e32 v188, v188
	v_rcp_f32_e32 v189, v189
	v_mul_f32_e32 v183, v183, v53
	v_mul_f32_e32 v180, v180, v187
	v_mul_f32_e32 v182, v21, v226
	v_mul_f32_e32 v183, v183, v180
	v_mul_f32_e32 v182, v182, v165
	v_mul_f32_e32 v183, v183, v188
	v_fmac_f32_e32 v183, v189, v182
	v_cvt_pk_bf16_f32 v190, v179, v183
	v_lshlrev_b32_e32 v176, 16, v107
	v_lshlrev_b32_e32 v177, 16, v123
	v_lshlrev_b32_e32 v178, 16, v139
	v_lshlrev_b32_e32 v179, 16, v91
	v_mul_f32_e32 v184, 0xbfb8aa3b, v176
	v_mul_f32_e32 v185, 0xbfb8aa3b, v177
	v_mul_f32_e32 v186, 0xbfb8aa3b, v178
	v_exp_f32_e32 v184, v184
	v_exp_f32_e32 v185, v185
	v_exp_f32_e32 v186, v186
	v_mul_f32_e32 v179, v179, v227
	v_add_f32_e32 v184, 1.0, v184
	v_add_f32_e32 v185, 1.0, v185
	v_add_f32_e32 v186, 1.0, v186
	v_rcp_f32_e32 v184, v184
	v_rcp_f32_e32 v185, v185
	v_rcp_f32_e32 v186, v186
	v_mul_f32_e32 v179, v179, v54
	v_mul_f32_e32 v176, v176, v184
	v_mul_f32_e32 v178, v22, v226
	v_mul_f32_e32 v179, v179, v176
	v_mul_f32_e32 v178, v178, v166
	v_mul_f32_e32 v179, v179, v185
	v_fmac_f32_e32 v179, v186, v178
	v_and_b32_e32 v180, 0xffff0000, v107
	v_and_b32_e32 v181, 0xffff0000, v123
	v_and_b32_e32 v182, 0xffff0000, v139
	v_and_b32_e32 v183, 0xffff0000, v91
	v_mul_f32_e32 v187, 0xbfb8aa3b, v180
	v_mul_f32_e32 v188, 0xbfb8aa3b, v181
	v_mul_f32_e32 v189, 0xbfb8aa3b, v182
	v_exp_f32_e32 v187, v187
	v_exp_f32_e32 v188, v188
	v_exp_f32_e32 v189, v189
	v_mul_f32_e32 v183, v183, v227
	v_add_f32_e32 v187, 1.0, v187
	v_add_f32_e32 v188, 1.0, v188
	v_add_f32_e32 v189, 1.0, v189
	v_rcp_f32_e32 v187, v187
	v_rcp_f32_e32 v188, v188
	v_rcp_f32_e32 v189, v189
	v_mul_f32_e32 v183, v183, v55
	v_mul_f32_e32 v180, v180, v187
	v_mul_f32_e32 v182, v23, v226
	v_mul_f32_e32 v183, v183, v180
	v_mul_f32_e32 v182, v182, v167
	v_mul_f32_e32 v183, v183, v188
	v_fmac_f32_e32 v183, v189, v182
	v_cvt_pk_bf16_f32 v191, v179, v183
	global_store_dwordx2 v215, v[190:191], s[28:29] offset:160
	s_nop 1
	v_lshlrev_b32_e32 v176, 16, v108
	v_lshlrev_b32_e32 v177, 16, v124
	v_lshlrev_b32_e32 v178, 16, v140
	v_lshlrev_b32_e32 v179, 16, v92
	v_mul_f32_e32 v184, 0xbfb8aa3b, v176
	v_mul_f32_e32 v185, 0xbfb8aa3b, v177
	v_mul_f32_e32 v186, 0xbfb8aa3b, v178
	v_exp_f32_e32 v184, v184
	v_exp_f32_e32 v185, v185
	v_exp_f32_e32 v186, v186
	v_mul_f32_e32 v179, v179, v227
	v_add_f32_e32 v184, 1.0, v184
	v_add_f32_e32 v185, 1.0, v185
	v_add_f32_e32 v186, 1.0, v186
	v_rcp_f32_e32 v184, v184
	v_rcp_f32_e32 v185, v185
	v_rcp_f32_e32 v186, v186
	v_mul_f32_e32 v179, v179, v56
	v_mul_f32_e32 v176, v176, v184
	v_mul_f32_e32 v178, v24, v226
	v_mul_f32_e32 v179, v179, v176
	v_mul_f32_e32 v178, v178, v168
	v_mul_f32_e32 v179, v179, v185
	v_fmac_f32_e32 v179, v186, v178
	v_and_b32_e32 v180, 0xffff0000, v108
	v_and_b32_e32 v181, 0xffff0000, v124
	v_and_b32_e32 v182, 0xffff0000, v140
	v_and_b32_e32 v183, 0xffff0000, v92
	v_mul_f32_e32 v187, 0xbfb8aa3b, v180
	v_mul_f32_e32 v188, 0xbfb8aa3b, v181
	v_mul_f32_e32 v189, 0xbfb8aa3b, v182
	v_exp_f32_e32 v187, v187
	v_exp_f32_e32 v188, v188
	v_exp_f32_e32 v189, v189
	v_mul_f32_e32 v183, v183, v227
	v_add_f32_e32 v187, 1.0, v187
	v_add_f32_e32 v188, 1.0, v188
	v_add_f32_e32 v189, 1.0, v189
	v_rcp_f32_e32 v187, v187
	v_rcp_f32_e32 v188, v188
	v_rcp_f32_e32 v189, v189
	v_mul_f32_e32 v183, v183, v57
	v_mul_f32_e32 v180, v180, v187
	v_mul_f32_e32 v182, v25, v226
	v_mul_f32_e32 v183, v183, v180
	v_mul_f32_e32 v182, v182, v169
	v_mul_f32_e32 v183, v183, v188
	v_fmac_f32_e32 v183, v189, v182
	v_cvt_pk_bf16_f32 v190, v179, v183
	v_lshlrev_b32_e32 v176, 16, v109
	v_lshlrev_b32_e32 v177, 16, v125
	v_lshlrev_b32_e32 v178, 16, v141
	v_lshlrev_b32_e32 v179, 16, v93
	v_mul_f32_e32 v184, 0xbfb8aa3b, v176
	v_mul_f32_e32 v185, 0xbfb8aa3b, v177
	v_mul_f32_e32 v186, 0xbfb8aa3b, v178
	v_exp_f32_e32 v184, v184
	v_exp_f32_e32 v185, v185
	v_exp_f32_e32 v186, v186
	v_mul_f32_e32 v179, v179, v227
	v_add_f32_e32 v184, 1.0, v184
	v_add_f32_e32 v185, 1.0, v185
	v_add_f32_e32 v186, 1.0, v186
	v_rcp_f32_e32 v184, v184
	v_rcp_f32_e32 v185, v185
	v_rcp_f32_e32 v186, v186
	v_mul_f32_e32 v179, v179, v58
	v_mul_f32_e32 v176, v176, v184
	v_mul_f32_e32 v178, v26, v226
	v_mul_f32_e32 v179, v179, v176
	v_mul_f32_e32 v178, v178, v170
	v_mul_f32_e32 v179, v179, v185
	v_fmac_f32_e32 v179, v186, v178
	v_and_b32_e32 v180, 0xffff0000, v109
	v_and_b32_e32 v181, 0xffff0000, v125
	v_and_b32_e32 v182, 0xffff0000, v141
	v_and_b32_e32 v183, 0xffff0000, v93
	v_mul_f32_e32 v187, 0xbfb8aa3b, v180
	v_mul_f32_e32 v188, 0xbfb8aa3b, v181
	v_mul_f32_e32 v189, 0xbfb8aa3b, v182
	v_exp_f32_e32 v187, v187
	v_exp_f32_e32 v188, v188
	v_exp_f32_e32 v189, v189
	v_mul_f32_e32 v183, v183, v227
	v_add_f32_e32 v187, 1.0, v187
	v_add_f32_e32 v188, 1.0, v188
	v_add_f32_e32 v189, 1.0, v189
	v_rcp_f32_e32 v187, v187
	v_rcp_f32_e32 v188, v188
	v_rcp_f32_e32 v189, v189
	v_mul_f32_e32 v183, v183, v59
	v_mul_f32_e32 v180, v180, v187
	v_mul_f32_e32 v182, v27, v226
	v_mul_f32_e32 v183, v183, v180
	v_mul_f32_e32 v182, v182, v171
	v_mul_f32_e32 v183, v183, v188
	v_fmac_f32_e32 v183, v189, v182
	v_cvt_pk_bf16_f32 v191, v179, v183
	global_store_dwordx2 v215, v[190:191], s[28:29] offset:192
	s_nop 1
	v_lshlrev_b32_e32 v176, 16, v110
	v_lshlrev_b32_e32 v177, 16, v126
	v_lshlrev_b32_e32 v178, 16, v142
	v_lshlrev_b32_e32 v179, 16, v94
	v_mul_f32_e32 v184, 0xbfb8aa3b, v176
	v_mul_f32_e32 v185, 0xbfb8aa3b, v177
	v_mul_f32_e32 v186, 0xbfb8aa3b, v178
	v_exp_f32_e32 v184, v184
	v_exp_f32_e32 v185, v185
	v_exp_f32_e32 v186, v186
	v_mul_f32_e32 v179, v179, v227
	v_add_f32_e32 v184, 1.0, v184
	v_add_f32_e32 v185, 1.0, v185
	v_add_f32_e32 v186, 1.0, v186
	v_rcp_f32_e32 v184, v184
	v_rcp_f32_e32 v185, v185
	v_rcp_f32_e32 v186, v186
	v_mul_f32_e32 v179, v179, v60
	v_mul_f32_e32 v176, v176, v184
	v_mul_f32_e32 v178, v28, v226
	v_mul_f32_e32 v179, v179, v176
	v_mul_f32_e32 v178, v178, v172
	v_mul_f32_e32 v179, v179, v185
	v_fmac_f32_e32 v179, v186, v178
	v_and_b32_e32 v180, 0xffff0000, v110
	v_and_b32_e32 v181, 0xffff0000, v126
	v_and_b32_e32 v182, 0xffff0000, v142
	v_and_b32_e32 v183, 0xffff0000, v94
	v_mul_f32_e32 v187, 0xbfb8aa3b, v180
	v_mul_f32_e32 v188, 0xbfb8aa3b, v181
	v_mul_f32_e32 v189, 0xbfb8aa3b, v182
	v_exp_f32_e32 v187, v187
	v_exp_f32_e32 v188, v188
	v_exp_f32_e32 v189, v189
	v_mul_f32_e32 v183, v183, v227
	v_add_f32_e32 v187, 1.0, v187
	v_add_f32_e32 v188, 1.0, v188
	v_add_f32_e32 v189, 1.0, v189
	v_rcp_f32_e32 v187, v187
	v_rcp_f32_e32 v188, v188
	v_rcp_f32_e32 v189, v189
	v_mul_f32_e32 v183, v183, v61
	v_mul_f32_e32 v180, v180, v187
	v_mul_f32_e32 v182, v29, v226
	v_mul_f32_e32 v183, v183, v180
	v_mul_f32_e32 v182, v182, v173
	v_mul_f32_e32 v183, v183, v188
	v_fmac_f32_e32 v183, v189, v182
	v_cvt_pk_bf16_f32 v190, v179, v183
	v_lshlrev_b32_e32 v176, 16, v111
	v_lshlrev_b32_e32 v177, 16, v127
	v_lshlrev_b32_e32 v178, 16, v143
	v_lshlrev_b32_e32 v179, 16, v95
	v_mul_f32_e32 v184, 0xbfb8aa3b, v176
	v_mul_f32_e32 v185, 0xbfb8aa3b, v177
	v_mul_f32_e32 v186, 0xbfb8aa3b, v178
	v_exp_f32_e32 v184, v184
	v_exp_f32_e32 v185, v185
	v_exp_f32_e32 v186, v186
	v_mul_f32_e32 v179, v179, v227
	v_add_f32_e32 v184, 1.0, v184
	v_add_f32_e32 v185, 1.0, v185
	v_add_f32_e32 v186, 1.0, v186
	v_rcp_f32_e32 v184, v184
	v_rcp_f32_e32 v185, v185
	v_rcp_f32_e32 v186, v186
	v_mul_f32_e32 v179, v179, v62
	v_mul_f32_e32 v176, v176, v184
	v_mul_f32_e32 v178, v30, v226
	v_mul_f32_e32 v179, v179, v176
	v_mul_f32_e32 v178, v178, v174
	v_mul_f32_e32 v179, v179, v185
	v_fmac_f32_e32 v179, v186, v178
	v_and_b32_e32 v180, 0xffff0000, v111
	v_and_b32_e32 v181, 0xffff0000, v127
	v_and_b32_e32 v182, 0xffff0000, v143
	v_and_b32_e32 v183, 0xffff0000, v95
	v_mul_f32_e32 v187, 0xbfb8aa3b, v180
	v_mul_f32_e32 v188, 0xbfb8aa3b, v181
	v_mul_f32_e32 v189, 0xbfb8aa3b, v182
	v_exp_f32_e32 v187, v187
	v_exp_f32_e32 v188, v188
	v_exp_f32_e32 v189, v189
	v_mul_f32_e32 v183, v183, v227
	v_add_f32_e32 v187, 1.0, v187
	v_add_f32_e32 v188, 1.0, v188
	v_add_f32_e32 v189, 1.0, v189
	v_rcp_f32_e32 v187, v187
	v_rcp_f32_e32 v188, v188
	v_rcp_f32_e32 v189, v189
	v_mul_f32_e32 v183, v183, v63
	v_mul_f32_e32 v180, v180, v187
	v_mul_f32_e32 v182, v31, v226
	v_mul_f32_e32 v183, v183, v180
	v_mul_f32_e32 v182, v182, v175
	v_mul_f32_e32 v183, v183, v188
	v_fmac_f32_e32 v183, v189, v182
	v_cvt_pk_bf16_f32 v191, v179, v183
	global_store_dwordx2 v215, v[190:191], s[28:29] offset:224
	s_nop 1
	s_cmp_lg_u32 s90, 0
	s_cbranch_scc1 .Lattn_unit
	s_branch .LBB0_812

.LBB0_977:
	v_lshl_add_u32 v146, s24, 8, v148
	v_mbcnt_hi_u32_b32 v170, -1, v192
	v_lshrrev_b32_e32 v171, 4, v170
	v_lshlrev_b32_e32 v171, 4, v171
	v_lshl_add_u32 v171, v146, 6, v171
	v_add_u32_e32 v172, 0x2000, v171
	v_xor_b32_e32 v210, 16, v170
	v_lshlrev_b32_e32 v210, 2, v210
	v_xor_b32_e32 v211, 32, v170
	v_lshlrev_b32_e32 v211, 2, v211
	global_load_dwordx4 v[174:177], v171, s[22:23]
	global_load_dwordx4 v[178:181], v171, s[22:23] offset:1024
	global_load_dwordx4 v[182:185], v171, s[22:23] offset:2048
	global_load_dwordx4 v[186:189], v171, s[22:23] offset:3072
	global_load_dwordx4 v[194:197], v172, s[22:23]
	global_load_dwordx4 v[198:201], v172, s[22:23] offset:1024
	global_load_dwordx4 v[202:205], v172, s[22:23] offset:2048
	global_load_dwordx4 v[206:209], v172, s[22:23] offset:3072
	s_waitcnt vmcnt(0)
	v_add_f32_e32 v174, v174, v175
	v_add_f32_e32 v176, v176, v177
	v_add_f32_e32 v178, v178, v179
	v_add_f32_e32 v180, v180, v181
	v_add_f32_e32 v182, v182, v183
	v_add_f32_e32 v184, v184, v185
	v_add_f32_e32 v186, v186, v187
	v_add_f32_e32 v188, v188, v189
	v_add_f32_e32 v194, v194, v195
	v_add_f32_e32 v196, v196, v197
	v_add_f32_e32 v198, v198, v199
	v_add_f32_e32 v200, v200, v201
	v_add_f32_e32 v202, v202, v203
	v_add_f32_e32 v204, v204, v205
	v_add_f32_e32 v206, v206, v207
	v_add_f32_e32 v208, v208, v209
	v_add_f32_e32 v174, v174, v176
	v_add_f32_e32 v178, v178, v180
	v_add_f32_e32 v182, v182, v184
	v_add_f32_e32 v186, v186, v188
	v_add_f32_e32 v194, v194, v196
	v_add_f32_e32 v198, v198, v200
	v_add_f32_e32 v202, v202, v204
	v_add_f32_e32 v206, v206, v208
	ds_bpermute_b32 v212, v210, v174
	ds_bpermute_b32 v213, v210, v178
	ds_bpermute_b32 v214, v210, v182
	ds_bpermute_b32 v215, v210, v186
	ds_bpermute_b32 v216, v210, v194
	ds_bpermute_b32 v217, v210, v198
	ds_bpermute_b32 v218, v210, v202
	ds_bpermute_b32 v219, v210, v206
	s_waitcnt lgkmcnt(0)
	v_add_f32_e32 v174, v174, v212
	v_add_f32_e32 v178, v178, v213
	v_add_f32_e32 v182, v182, v214
	v_add_f32_e32 v186, v186, v215
	v_add_f32_e32 v194, v194, v216
	v_add_f32_e32 v198, v198, v217
	v_add_f32_e32 v202, v202, v218
	v_add_f32_e32 v206, v206, v219
	ds_bpermute_b32 v212, v211, v174
	ds_bpermute_b32 v213, v211, v178
	ds_bpermute_b32 v214, v211, v182
	ds_bpermute_b32 v215, v211, v186
	ds_bpermute_b32 v216, v211, v194
	ds_bpermute_b32 v217, v211, v198
	ds_bpermute_b32 v218, v211, v202
	ds_bpermute_b32 v219, v211, v206
	s_waitcnt lgkmcnt(0)
	v_add_f32_e32 v174, v174, v212
	v_add_f32_e32 v178, v178, v213
	v_add_f32_e32 v182, v182, v214
	v_add_f32_e32 v186, v186, v215
	v_add_f32_e32 v194, v194, v216
	v_add_f32_e32 v198, v198, v217
	v_add_f32_e32 v202, v202, v218
	v_add_f32_e32 v206, v206, v219
	v_fmamk_f32 v220, v174, 0x3a800000, v153
	v_fmamk_f32 v221, v178, 0x3a800000, v153
	v_fmamk_f32 v222, v182, 0x3a800000, v153
	v_fmamk_f32 v223, v186, 0x3a800000, v153
	v_fmamk_f32 v224, v194, 0x3a800000, v153
	v_fmamk_f32 v225, v198, 0x3a800000, v153
	v_fmamk_f32 v226, v202, 0x3a800000, v153
	v_fmamk_f32 v227, v206, 0x3a800000, v153
	v_rsq_f32_e32 v220, v220
	v_rsq_f32_e32 v221, v221
	v_rsq_f32_e32 v222, v222
	v_rsq_f32_e32 v223, v223
	v_rsq_f32_e32 v224, v224
	v_rsq_f32_e32 v225, v225
	v_rsq_f32_e32 v226, v226
	v_rsq_f32_e32 v227, v227
	s_nop 0
	s_lshl_b32 s24, s25, 7
	s_ashr_i32 s25, s24, 31
	s_lshl_b64 s[24:25], s[24:25], 1
	s_andn2_b64 vcc, exec, s[40:41]
	v_mov_b32_e32 v154, v220
	s_nop 0
	v_pk_mul_f32 v[124:125], v[124:125], v[154:155] op_sel_hi:[1,0]
	s_nop 0
	v_mul_f32_e32 v147, 0xbfb8aa3b, v124
	v_exp_f32_e32 v147, v147
	v_pk_mul_f32 v[116:117], v[116:117], v[154:155] op_sel_hi:[1,0]
	v_pk_mul_f32 v[118:119], v[118:119], v[154:155] op_sel_hi:[1,0]
	v_pk_mul_f32 v[120:121], v[120:121], v[154:155] op_sel_hi:[1,0]
	v_add_f32_e32 v147, 1.0, v147
	v_rcp_f32_e32 v156, v147
	v_mul_f32_e32 v147, 0xbfb8aa3b, v125
	v_exp_f32_e32 v147, v147
	v_pk_mul_f32 v[112:113], v[112:113], v[154:155] op_sel_hi:[1,0]
	v_pk_mul_f32 v[114:115], v[114:115], v[154:155] op_sel_hi:[1,0]
	v_add_f32_e32 v147, 1.0, v147
	v_rcp_f32_e32 v157, v147
	s_nop 0
	v_pk_mul_f32 v[124:125], v[124:125], v[156:157]
	s_nop 0
	v_pk_mul_f32 v[116:117], v[116:117], v[124:125]
	v_pk_mul_f32 v[124:125], v[126:127], v[154:155] op_sel_hi:[1,0]
	s_nop 0
	v_mul_f32_e32 v126, 0xbfb8aa3b, v124
	v_mul_f32_e32 v127, 0xbfb8aa3b, v125
	v_exp_f32_e32 v126, v126
	v_exp_f32_e32 v127, v127
	v_add_f32_e32 v126, 1.0, v126
	v_add_f32_e32 v127, 1.0, v127
	v_rcp_f32_e32 v126, v126
	v_rcp_f32_e32 v127, v127
	s_nop 0
	v_pk_mul_f32 v[124:125], v[124:125], v[126:127]
	s_nop 0
	v_pk_mul_f32 v[118:119], v[118:119], v[124:125]
	v_mul_f32_e32 v124, 0xbfb8aa3b, v120
	v_mul_f32_e32 v125, 0xbfb8aa3b, v121
	v_exp_f32_e32 v124, v124
	v_exp_f32_e32 v125, v125
	v_add_f32_e32 v124, 1.0, v124
	v_add_f32_e32 v125, 1.0, v125
	v_rcp_f32_e32 v124, v124
	v_rcp_f32_e32 v125, v125
	s_nop 0
	v_pk_mul_f32 v[120:121], v[120:121], v[124:125]
	s_nop 0
	v_pk_mul_f32 v[112:113], v[112:113], v[120:121]
	v_pk_mul_f32 v[120:121], v[122:123], v[154:155] op_sel_hi:[1,0]
	s_nop 0
	v_mul_f32_e32 v122, 0xbfb8aa3b, v120
	v_mul_f32_e32 v123, 0xbfb8aa3b, v121
	v_exp_f32_e32 v122, v122
	v_exp_f32_e32 v123, v123
	v_add_f32_e32 v122, 1.0, v122
	v_add_f32_e32 v123, 1.0, v123
	v_rcp_f32_e32 v122, v122
	v_rcp_f32_e32 v123, v123
	s_nop 0
	v_pk_mul_f32 v[120:121], v[120:121], v[122:123]
	s_nop 0
	v_pk_mul_f32 v[120:121], v[114:115], v[120:121]
	v_cvt_pk_bf16_f32 v114, v116, v117
	v_cvt_pk_bf16_f32 v116, v112, v113
	v_mov_b64_e32 v[112:113], s[80:81]
	v_cvt_pk_bf16_f32 v115, v118, v119
	v_mad_i64_i32 v[118:119], s[26:27], v146, s45, v[112:113]
	v_lshl_add_u64 v[118:119], v[118:119], 0, s[24:25]
	v_lshl_add_u64 v[118:119], v[118:119], 0, s[8:9]
	v_cvt_pk_bf16_f32 v117, v120, v121
	v_lshl_add_u64 v[118:119], v[118:119], 0, v[136:137]
	global_store_dwordx4 v[118:119], v[114:117], off
	s_nop 1
	v_or_b32_e32 v114, 16, v146
	v_mov_b32_e32 v116, v221
	s_nop 0
	v_pk_mul_f32 v[108:109], v[108:109], v[116:117] op_sel_hi:[1,0]
	s_nop 0
	v_mul_f32_e32 v115, 0xbfb8aa3b, v108
	v_exp_f32_e32 v115, v115
	v_pk_mul_f32 v[100:101], v[100:101], v[116:117] op_sel_hi:[1,0]
	v_pk_mul_f32 v[102:103], v[102:103], v[116:117] op_sel_hi:[1,0]
	v_pk_mul_f32 v[104:105], v[104:105], v[116:117] op_sel_hi:[1,0]
	v_add_f32_e32 v115, 1.0, v115
	v_rcp_f32_e32 v118, v115
	v_mul_f32_e32 v115, 0xbfb8aa3b, v109
	v_exp_f32_e32 v115, v115
	v_pk_mul_f32 v[96:97], v[96:97], v[116:117] op_sel_hi:[1,0]
	v_pk_mul_f32 v[98:99], v[98:99], v[116:117] op_sel_hi:[1,0]
	v_add_f32_e32 v115, 1.0, v115
	v_rcp_f32_e32 v119, v115
	s_nop 0
	v_pk_mul_f32 v[108:109], v[108:109], v[118:119]
	s_nop 0
	v_pk_mul_f32 v[100:101], v[100:101], v[108:109]
	v_pk_mul_f32 v[108:109], v[110:111], v[116:117] op_sel_hi:[1,0]
	s_nop 0
	v_mul_f32_e32 v110, 0xbfb8aa3b, v108
	v_mul_f32_e32 v111, 0xbfb8aa3b, v109
	v_exp_f32_e32 v110, v110
	v_exp_f32_e32 v111, v111
	v_add_f32_e32 v110, 1.0, v110
	v_add_f32_e32 v111, 1.0, v111
	v_rcp_f32_e32 v110, v110
	v_rcp_f32_e32 v111, v111
	s_nop 0
	v_pk_mul_f32 v[108:109], v[108:109], v[110:111]
	s_nop 0
	v_pk_mul_f32 v[102:103], v[102:103], v[108:109]
	v_mul_f32_e32 v108, 0xbfb8aa3b, v104
	v_mul_f32_e32 v109, 0xbfb8aa3b, v105
	v_exp_f32_e32 v108, v108
	v_exp_f32_e32 v109, v109
	v_add_f32_e32 v108, 1.0, v108
	v_add_f32_e32 v109, 1.0, v109
	v_rcp_f32_e32 v108, v108
	v_rcp_f32_e32 v109, v109
	s_nop 0
	v_pk_mul_f32 v[104:105], v[104:105], v[108:109]
	s_nop 0
	v_pk_mul_f32 v[104:105], v[96:97], v[104:105]
	v_pk_mul_f32 v[96:97], v[106:107], v[116:117] op_sel_hi:[1,0]
	s_nop 0
	v_mul_f32_e32 v106, 0xbfb8aa3b, v96
	v_mul_f32_e32 v107, 0xbfb8aa3b, v97
	v_exp_f32_e32 v106, v106
	v_exp_f32_e32 v107, v107
	v_add_f32_e32 v106, 1.0, v106
	v_add_f32_e32 v107, 1.0, v107
	v_rcp_f32_e32 v106, v106
	v_rcp_f32_e32 v107, v107
	s_nop 0
	v_pk_mul_f32 v[96:97], v[96:97], v[106:107]
	s_nop 0
	v_pk_mul_f32 v[106:107], v[98:99], v[96:97]
	v_cvt_pk_bf16_f32 v96, v100, v101
	v_mad_i64_i32 v[100:101], s[26:27], v114, s45, v[112:113]
	v_lshl_add_u64 v[100:101], v[100:101], 0, s[24:25]
	v_lshl_add_u64 v[100:101], v[100:101], 0, s[8:9]
	v_cvt_pk_bf16_f32 v97, v102, v103
	v_cvt_pk_bf16_f32 v98, v104, v105
	v_cvt_pk_bf16_f32 v99, v106, v107
	v_lshl_add_u64 v[100:101], v[100:101], 0, v[136:137]
	global_store_dwordx4 v[100:101], v[96:99], off
	s_nop 1
	v_or_b32_e32 v96, 32, v146
	v_mov_b32_e32 v98, v222
	s_nop 0
	v_pk_mul_f32 v[92:93], v[92:93], v[98:99] op_sel_hi:[1,0]
	s_nop 0
	v_mul_f32_e32 v97, 0xbfb8aa3b, v92
	v_exp_f32_e32 v97, v97
	v_pk_mul_f32 v[84:85], v[84:85], v[98:99] op_sel_hi:[1,0]
	v_pk_mul_f32 v[86:87], v[86:87], v[98:99] op_sel_hi:[1,0]
	v_pk_mul_f32 v[88:89], v[88:89], v[98:99] op_sel_hi:[1,0]
	v_add_f32_e32 v97, 1.0, v97
	v_rcp_f32_e32 v100, v97
	v_mul_f32_e32 v97, 0xbfb8aa3b, v93
	v_exp_f32_e32 v97, v97
	v_pk_mul_f32 v[80:81], v[80:81], v[98:99] op_sel_hi:[1,0]
	v_pk_mul_f32 v[82:83], v[82:83], v[98:99] op_sel_hi:[1,0]
	v_add_f32_e32 v97, 1.0, v97
	v_rcp_f32_e32 v101, v97
	s_nop 0
	v_pk_mul_f32 v[92:93], v[92:93], v[100:101]
	s_nop 0
	v_pk_mul_f32 v[84:85], v[84:85], v[92:93]
	v_pk_mul_f32 v[92:93], v[94:95], v[98:99] op_sel_hi:[1,0]
	s_nop 0
	v_mul_f32_e32 v94, 0xbfb8aa3b, v92
	v_mul_f32_e32 v95, 0xbfb8aa3b, v93
	v_exp_f32_e32 v94, v94
	v_exp_f32_e32 v95, v95
	v_add_f32_e32 v94, 1.0, v94
	v_add_f32_e32 v95, 1.0, v95
	v_rcp_f32_e32 v94, v94
	v_rcp_f32_e32 v95, v95
	s_nop 0
	v_pk_mul_f32 v[92:93], v[92:93], v[94:95]
	s_nop 0
	v_pk_mul_f32 v[86:87], v[86:87], v[92:93]
	v_mul_f32_e32 v92, 0xbfb8aa3b, v88
	v_mul_f32_e32 v93, 0xbfb8aa3b, v89
	v_exp_f32_e32 v92, v92
	v_exp_f32_e32 v93, v93
	v_add_f32_e32 v92, 1.0, v92
	v_add_f32_e32 v93, 1.0, v93
	v_rcp_f32_e32 v92, v92
	v_rcp_f32_e32 v93, v93
	s_nop 0
	v_pk_mul_f32 v[88:89], v[88:89], v[92:93]
	s_nop 0
	v_pk_mul_f32 v[88:89], v[80:81], v[88:89]
	v_pk_mul_f32 v[80:81], v[90:91], v[98:99] op_sel_hi:[1,0]
	s_nop 0
	v_mul_f32_e32 v90, 0xbfb8aa3b, v80
	v_mul_f32_e32 v91, 0xbfb8aa3b, v81
	v_exp_f32_e32 v90, v90
	v_exp_f32_e32 v91, v91
	v_add_f32_e32 v90, 1.0, v90
	v_add_f32_e32 v91, 1.0, v91
	v_rcp_f32_e32 v90, v90
	v_rcp_f32_e32 v91, v91
	s_nop 0
	v_pk_mul_f32 v[80:81], v[80:81], v[90:91]
	s_nop 0
	v_pk_mul_f32 v[90:91], v[82:83], v[80:81]
	v_cvt_pk_bf16_f32 v80, v84, v85
	v_mad_i64_i32 v[84:85], s[26:27], v96, s45, v[112:113]
	v_lshl_add_u64 v[84:85], v[84:85], 0, s[24:25]
	v_lshl_add_u64 v[84:85], v[84:85], 0, s[8:9]
	v_cvt_pk_bf16_f32 v81, v86, v87
	v_cvt_pk_bf16_f32 v82, v88, v89
	v_cvt_pk_bf16_f32 v83, v90, v91
	v_lshl_add_u64 v[84:85], v[84:85], 0, v[136:137]
	global_store_dwordx4 v[84:85], v[80:83], off
	s_nop 1
	v_or_b32_e32 v80, 48, v146
	v_mov_b32_e32 v82, v223
	s_nop 0
	v_pk_mul_f32 v[76:77], v[76:77], v[82:83] op_sel_hi:[1,0]
	s_nop 0
	v_mul_f32_e32 v81, 0xbfb8aa3b, v76
	v_exp_f32_e32 v81, v81
	v_pk_mul_f32 v[68:69], v[68:69], v[82:83] op_sel_hi:[1,0]
	v_pk_mul_f32 v[70:71], v[70:71], v[82:83] op_sel_hi:[1,0]
	v_pk_mul_f32 v[72:73], v[72:73], v[82:83] op_sel_hi:[1,0]
	v_add_f32_e32 v81, 1.0, v81
	v_rcp_f32_e32 v84, v81
	v_mul_f32_e32 v81, 0xbfb8aa3b, v77
	v_exp_f32_e32 v81, v81
	v_pk_mul_f32 v[64:65], v[64:65], v[82:83] op_sel_hi:[1,0]
	v_pk_mul_f32 v[66:67], v[66:67], v[82:83] op_sel_hi:[1,0]
	v_add_f32_e32 v81, 1.0, v81
	v_rcp_f32_e32 v85, v81
	s_nop 0
	v_pk_mul_f32 v[76:77], v[76:77], v[84:85]
	s_nop 0
	v_pk_mul_f32 v[68:69], v[68:69], v[76:77]
	v_pk_mul_f32 v[76:77], v[78:79], v[82:83] op_sel_hi:[1,0]
	s_nop 0
	v_mul_f32_e32 v78, 0xbfb8aa3b, v76
	v_mul_f32_e32 v79, 0xbfb8aa3b, v77
	v_exp_f32_e32 v78, v78
	v_exp_f32_e32 v79, v79
	v_add_f32_e32 v78, 1.0, v78
	v_add_f32_e32 v79, 1.0, v79
	v_rcp_f32_e32 v78, v78
	v_rcp_f32_e32 v79, v79
	s_nop 0
	v_pk_mul_f32 v[76:77], v[76:77], v[78:79]
	s_nop 0
	v_pk_mul_f32 v[70:71], v[70:71], v[76:77]
	v_mul_f32_e32 v76, 0xbfb8aa3b, v72
	v_mul_f32_e32 v77, 0xbfb8aa3b, v73
	v_exp_f32_e32 v76, v76
	v_exp_f32_e32 v77, v77
	v_add_f32_e32 v76, 1.0, v76
	v_add_f32_e32 v77, 1.0, v77
	v_rcp_f32_e32 v76, v76
	v_rcp_f32_e32 v77, v77
	s_nop 0
	v_pk_mul_f32 v[72:73], v[72:73], v[76:77]
	s_nop 0
	v_pk_mul_f32 v[72:73], v[64:65], v[72:73]
	v_pk_mul_f32 v[64:65], v[74:75], v[82:83] op_sel_hi:[1,0]
	s_nop 0
	v_mul_f32_e32 v74, 0xbfb8aa3b, v64
	v_mul_f32_e32 v75, 0xbfb8aa3b, v65
	v_exp_f32_e32 v74, v74
	v_exp_f32_e32 v75, v75
	v_add_f32_e32 v74, 1.0, v74
	v_add_f32_e32 v75, 1.0, v75
	v_rcp_f32_e32 v74, v74
	v_rcp_f32_e32 v75, v75
	s_nop 0
	v_pk_mul_f32 v[64:65], v[64:65], v[74:75]
	s_nop 0
	v_pk_mul_f32 v[74:75], v[66:67], v[64:65]
	v_cvt_pk_bf16_f32 v64, v68, v69
	v_mad_i64_i32 v[68:69], s[26:27], v80, s45, v[112:113]
	v_lshl_add_u64 v[68:69], v[68:69], 0, s[24:25]
	v_lshl_add_u64 v[68:69], v[68:69], 0, s[8:9]
	v_cvt_pk_bf16_f32 v65, v70, v71
	v_cvt_pk_bf16_f32 v66, v72, v73
	v_cvt_pk_bf16_f32 v67, v74, v75
	v_lshl_add_u64 v[68:69], v[68:69], 0, v[136:137]
	global_store_dwordx4 v[68:69], v[64:67], off
	s_nop 1
	v_add_u32_e32 v64, 0x80, v146
	v_mov_b32_e32 v66, v224
	s_nop 0
	v_pk_mul_f32 v[60:61], v[60:61], v[66:67] op_sel_hi:[1,0]
	s_nop 0
	v_mul_f32_e32 v65, 0xbfb8aa3b, v60
	v_exp_f32_e32 v65, v65
	v_pk_mul_f32 v[52:53], v[52:53], v[66:67] op_sel_hi:[1,0]
	v_pk_mul_f32 v[54:55], v[54:55], v[66:67] op_sel_hi:[1,0]
	v_pk_mul_f32 v[56:57], v[56:57], v[66:67] op_sel_hi:[1,0]
	v_add_f32_e32 v65, 1.0, v65
	v_rcp_f32_e32 v68, v65
	v_mul_f32_e32 v65, 0xbfb8aa3b, v61
	v_exp_f32_e32 v65, v65
	v_pk_mul_f32 v[48:49], v[48:49], v[66:67] op_sel_hi:[1,0]
	v_pk_mul_f32 v[50:51], v[50:51], v[66:67] op_sel_hi:[1,0]
	v_add_f32_e32 v65, 1.0, v65
	v_rcp_f32_e32 v69, v65
	s_nop 0
	v_pk_mul_f32 v[60:61], v[60:61], v[68:69]
	s_nop 0
	v_pk_mul_f32 v[52:53], v[52:53], v[60:61]
	v_pk_mul_f32 v[60:61], v[62:63], v[66:67] op_sel_hi:[1,0]
	s_nop 0
	v_mul_f32_e32 v62, 0xbfb8aa3b, v60
	v_mul_f32_e32 v63, 0xbfb8aa3b, v61
	v_exp_f32_e32 v62, v62
	v_exp_f32_e32 v63, v63
	v_add_f32_e32 v62, 1.0, v62
	v_add_f32_e32 v63, 1.0, v63
	v_rcp_f32_e32 v62, v62
	v_rcp_f32_e32 v63, v63
	s_nop 0
	v_pk_mul_f32 v[60:61], v[60:61], v[62:63]
	s_nop 0
	v_pk_mul_f32 v[54:55], v[54:55], v[60:61]
	v_mul_f32_e32 v60, 0xbfb8aa3b, v56
	v_mul_f32_e32 v61, 0xbfb8aa3b, v57
	v_exp_f32_e32 v60, v60
	v_exp_f32_e32 v61, v61
	v_add_f32_e32 v60, 1.0, v60
	v_add_f32_e32 v61, 1.0, v61
	v_rcp_f32_e32 v60, v60
	v_rcp_f32_e32 v61, v61
	s_nop 0
	v_pk_mul_f32 v[56:57], v[56:57], v[60:61]
	s_nop 0
	v_pk_mul_f32 v[56:57], v[48:49], v[56:57]
	v_pk_mul_f32 v[48:49], v[58:59], v[66:67] op_sel_hi:[1,0]
	s_nop 0
	v_mul_f32_e32 v58, 0xbfb8aa3b, v48
	v_mul_f32_e32 v59, 0xbfb8aa3b, v49
	v_exp_f32_e32 v58, v58
	v_exp_f32_e32 v59, v59
	v_add_f32_e32 v58, 1.0, v58
	v_add_f32_e32 v59, 1.0, v59
	v_rcp_f32_e32 v58, v58
	v_rcp_f32_e32 v59, v59
	s_nop 0
	v_pk_mul_f32 v[48:49], v[48:49], v[58:59]
	s_nop 0
	v_pk_mul_f32 v[58:59], v[50:51], v[48:49]
	v_cvt_pk_bf16_f32 v48, v52, v53
	v_mad_i64_i32 v[52:53], s[26:27], v64, s45, v[112:113]
	v_lshl_add_u64 v[52:53], v[52:53], 0, s[24:25]
	v_lshl_add_u64 v[52:53], v[52:53], 0, s[8:9]
	v_cvt_pk_bf16_f32 v49, v54, v55
	v_cvt_pk_bf16_f32 v50, v56, v57
	v_cvt_pk_bf16_f32 v51, v58, v59
	v_lshl_add_u64 v[52:53], v[52:53], 0, v[136:137]
	global_store_dwordx4 v[52:53], v[48:51], off
	s_nop 1
	v_add_u32_e32 v48, 0x90, v146
	v_mov_b32_e32 v50, v225
	s_nop 0
	v_pk_mul_f32 v[44:45], v[44:45], v[50:51] op_sel_hi:[1,0]
	s_nop 0
	v_mul_f32_e32 v49, 0xbfb8aa3b, v44
	v_exp_f32_e32 v49, v49
	v_pk_mul_f32 v[36:37], v[36:37], v[50:51] op_sel_hi:[1,0]
	v_pk_mul_f32 v[38:39], v[38:39], v[50:51] op_sel_hi:[1,0]
	v_pk_mul_f32 v[40:41], v[40:41], v[50:51] op_sel_hi:[1,0]
	v_add_f32_e32 v49, 1.0, v49
	v_rcp_f32_e32 v52, v49
	v_mul_f32_e32 v49, 0xbfb8aa3b, v45
	v_exp_f32_e32 v49, v49
	v_pk_mul_f32 v[32:33], v[32:33], v[50:51] op_sel_hi:[1,0]
	v_pk_mul_f32 v[34:35], v[34:35], v[50:51] op_sel_hi:[1,0]
	v_add_f32_e32 v49, 1.0, v49
	v_rcp_f32_e32 v53, v49
	s_nop 0
	v_pk_mul_f32 v[44:45], v[44:45], v[52:53]
	s_nop 0
	v_pk_mul_f32 v[36:37], v[36:37], v[44:45]
	v_pk_mul_f32 v[44:45], v[46:47], v[50:51] op_sel_hi:[1,0]
	s_nop 0
	v_mul_f32_e32 v46, 0xbfb8aa3b, v44
	v_mul_f32_e32 v47, 0xbfb8aa3b, v45
	v_exp_f32_e32 v46, v46
	v_exp_f32_e32 v47, v47
	v_add_f32_e32 v46, 1.0, v46
	v_add_f32_e32 v47, 1.0, v47
	v_rcp_f32_e32 v46, v46
	v_rcp_f32_e32 v47, v47
	s_nop 0
	v_pk_mul_f32 v[44:45], v[44:45], v[46:47]
	s_nop 0
	v_pk_mul_f32 v[38:39], v[38:39], v[44:45]
	v_mul_f32_e32 v44, 0xbfb8aa3b, v40
	v_mul_f32_e32 v45, 0xbfb8aa3b, v41
	v_exp_f32_e32 v44, v44
	v_exp_f32_e32 v45, v45
	v_add_f32_e32 v44, 1.0, v44
	v_add_f32_e32 v45, 1.0, v45
	v_rcp_f32_e32 v44, v44
	v_rcp_f32_e32 v45, v45
	s_nop 0
	v_pk_mul_f32 v[40:41], v[40:41], v[44:45]
	s_nop 0
	v_pk_mul_f32 v[40:41], v[32:33], v[40:41]
	v_pk_mul_f32 v[32:33], v[42:43], v[50:51] op_sel_hi:[1,0]
	s_nop 0
	v_mul_f32_e32 v42, 0xbfb8aa3b, v32
	v_mul_f32_e32 v43, 0xbfb8aa3b, v33
	v_exp_f32_e32 v42, v42
	v_exp_f32_e32 v43, v43
	v_add_f32_e32 v42, 1.0, v42
	v_add_f32_e32 v43, 1.0, v43
	v_rcp_f32_e32 v42, v42
	v_rcp_f32_e32 v43, v43
	s_nop 0
	v_pk_mul_f32 v[32:33], v[32:33], v[42:43]
	s_nop 0
	v_pk_mul_f32 v[42:43], v[34:35], v[32:33]
	v_cvt_pk_bf16_f32 v32, v36, v37
	v_mad_i64_i32 v[36:37], s[26:27], v48, s45, v[112:113]
	v_lshl_add_u64 v[36:37], v[36:37], 0, s[24:25]
	v_lshl_add_u64 v[36:37], v[36:37], 0, s[8:9]
	v_cvt_pk_bf16_f32 v33, v38, v39
	v_cvt_pk_bf16_f32 v34, v40, v41
	v_cvt_pk_bf16_f32 v35, v42, v43
	v_lshl_add_u64 v[36:37], v[36:37], 0, v[136:137]
	global_store_dwordx4 v[36:37], v[32:35], off
	s_nop 1
	v_add_u32_e32 v32, 0xa0, v146
	v_mov_b32_e32 v34, v226
	s_nop 0
	v_pk_mul_f32 v[28:29], v[28:29], v[34:35] op_sel_hi:[1,0]
	s_nop 0
	v_mul_f32_e32 v33, 0xbfb8aa3b, v28
	v_exp_f32_e32 v33, v33
	v_pk_mul_f32 v[20:21], v[20:21], v[34:35] op_sel_hi:[1,0]
	v_pk_mul_f32 v[22:23], v[22:23], v[34:35] op_sel_hi:[1,0]
	v_pk_mul_f32 v[24:25], v[24:25], v[34:35] op_sel_hi:[1,0]
	v_add_f32_e32 v33, 1.0, v33
	v_rcp_f32_e32 v36, v33
	v_mul_f32_e32 v33, 0xbfb8aa3b, v29
	v_exp_f32_e32 v33, v33
	v_pk_mul_f32 v[16:17], v[16:17], v[34:35] op_sel_hi:[1,0]
	v_pk_mul_f32 v[18:19], v[18:19], v[34:35] op_sel_hi:[1,0]
	v_add_f32_e32 v33, 1.0, v33
	v_rcp_f32_e32 v37, v33
	s_nop 0
	v_pk_mul_f32 v[28:29], v[28:29], v[36:37]
	s_nop 0
	v_pk_mul_f32 v[20:21], v[20:21], v[28:29]
	v_pk_mul_f32 v[28:29], v[30:31], v[34:35] op_sel_hi:[1,0]
	s_nop 0
	v_mul_f32_e32 v30, 0xbfb8aa3b, v28
	v_mul_f32_e32 v31, 0xbfb8aa3b, v29
	v_exp_f32_e32 v30, v30
	v_exp_f32_e32 v31, v31
	v_add_f32_e32 v30, 1.0, v30
	v_add_f32_e32 v31, 1.0, v31
	v_rcp_f32_e32 v30, v30
	v_rcp_f32_e32 v31, v31
	s_nop 0
	v_pk_mul_f32 v[28:29], v[28:29], v[30:31]
	s_nop 0
	v_pk_mul_f32 v[22:23], v[22:23], v[28:29]
	v_mul_f32_e32 v28, 0xbfb8aa3b, v24
	v_mul_f32_e32 v29, 0xbfb8aa3b, v25
	v_exp_f32_e32 v28, v28
	v_exp_f32_e32 v29, v29
	v_add_f32_e32 v28, 1.0, v28
	v_add_f32_e32 v29, 1.0, v29
	v_rcp_f32_e32 v28, v28
	v_rcp_f32_e32 v29, v29
	s_nop 0
	v_pk_mul_f32 v[24:25], v[24:25], v[28:29]
	s_nop 0
	v_pk_mul_f32 v[24:25], v[16:17], v[24:25]
	v_pk_mul_f32 v[16:17], v[26:27], v[34:35] op_sel_hi:[1,0]
	s_nop 0
	v_mul_f32_e32 v26, 0xbfb8aa3b, v16
	v_mul_f32_e32 v27, 0xbfb8aa3b, v17
	v_exp_f32_e32 v26, v26
	v_exp_f32_e32 v27, v27
	v_add_f32_e32 v26, 1.0, v26
	v_add_f32_e32 v27, 1.0, v27
	v_rcp_f32_e32 v26, v26
	v_rcp_f32_e32 v27, v27
	s_nop 0
	v_pk_mul_f32 v[16:17], v[16:17], v[26:27]
	s_nop 0
	v_pk_mul_f32 v[26:27], v[18:19], v[16:17]
	v_cvt_pk_bf16_f32 v16, v20, v21
	v_mad_i64_i32 v[20:21], s[26:27], v32, s45, v[112:113]
	v_lshl_add_u64 v[20:21], v[20:21], 0, s[24:25]
	v_lshl_add_u64 v[20:21], v[20:21], 0, s[8:9]
	v_cvt_pk_bf16_f32 v17, v22, v23
	v_cvt_pk_bf16_f32 v18, v24, v25
	v_cvt_pk_bf16_f32 v19, v26, v27
	v_lshl_add_u64 v[20:21], v[20:21], 0, v[136:137]
	global_store_dwordx4 v[20:21], v[16:19], off
	s_nop 1
	v_add_u32_e32 v16, 0xb0, v146
	v_mov_b32_e32 v18, v227
	s_nop 0
	v_pk_mul_f32 v[12:13], v[12:13], v[18:19] op_sel_hi:[1,0]
	s_nop 0
	v_mul_f32_e32 v17, 0xbfb8aa3b, v12
	v_exp_f32_e32 v17, v17
	v_pk_mul_f32 v[4:5], v[4:5], v[18:19] op_sel_hi:[1,0]
	v_pk_mul_f32 v[6:7], v[6:7], v[18:19] op_sel_hi:[1,0]
	v_pk_mul_f32 v[8:9], v[8:9], v[18:19] op_sel_hi:[1,0]
	v_add_f32_e32 v17, 1.0, v17
	v_rcp_f32_e32 v20, v17
	v_mul_f32_e32 v17, 0xbfb8aa3b, v13
	v_exp_f32_e32 v17, v17
	v_pk_mul_f32 v[0:1], v[0:1], v[18:19] op_sel_hi:[1,0]
	v_pk_mul_f32 v[2:3], v[2:3], v[18:19] op_sel_hi:[1,0]
	v_add_f32_e32 v17, 1.0, v17
	v_rcp_f32_e32 v21, v17
	s_nop 0
	v_pk_mul_f32 v[12:13], v[12:13], v[20:21]
	s_nop 0
	v_pk_mul_f32 v[4:5], v[4:5], v[12:13]
	v_pk_mul_f32 v[12:13], v[14:15], v[18:19] op_sel_hi:[1,0]
	s_nop 0
	v_mul_f32_e32 v14, 0xbfb8aa3b, v12
	v_mul_f32_e32 v15, 0xbfb8aa3b, v13
	v_exp_f32_e32 v14, v14
	v_exp_f32_e32 v15, v15
	v_add_f32_e32 v14, 1.0, v14
	v_add_f32_e32 v15, 1.0, v15
	v_rcp_f32_e32 v14, v14
	v_rcp_f32_e32 v15, v15
	s_nop 0
	v_pk_mul_f32 v[12:13], v[12:13], v[14:15]
	s_nop 0
	v_pk_mul_f32 v[6:7], v[6:7], v[12:13]
	v_mul_f32_e32 v12, 0xbfb8aa3b, v8
	v_mul_f32_e32 v13, 0xbfb8aa3b, v9
	v_exp_f32_e32 v12, v12
	v_exp_f32_e32 v13, v13
	v_add_f32_e32 v12, 1.0, v12
	v_add_f32_e32 v13, 1.0, v13
	v_rcp_f32_e32 v12, v12
	v_rcp_f32_e32 v13, v13
	s_nop 0
	v_pk_mul_f32 v[8:9], v[8:9], v[12:13]
	s_nop 0
	v_pk_mul_f32 v[8:9], v[0:1], v[8:9]
	v_pk_mul_f32 v[0:1], v[10:11], v[18:19] op_sel_hi:[1,0]
	s_nop 0
	v_mul_f32_e32 v10, 0xbfb8aa3b, v0
	v_mul_f32_e32 v11, 0xbfb8aa3b, v1
	v_exp_f32_e32 v10, v10
	v_exp_f32_e32 v11, v11
	v_add_f32_e32 v10, 1.0, v10
	v_add_f32_e32 v11, 1.0, v11
	v_rcp_f32_e32 v10, v10
	v_rcp_f32_e32 v11, v11
	s_nop 0
	v_pk_mul_f32 v[0:1], v[0:1], v[10:11]
	s_nop 0
	v_pk_mul_f32 v[10:11], v[2:3], v[0:1]
	v_cvt_pk_bf16_f32 v0, v4, v5
	v_mad_i64_i32 v[4:5], s[26:27], v16, s45, v[112:113]
	v_lshl_add_u64 v[4:5], v[4:5], 0, s[24:25]
	v_lshl_add_u64 v[4:5], v[4:5], 0, s[8:9]
	v_cvt_pk_bf16_f32 v1, v6, v7
	v_cvt_pk_bf16_f32 v2, v8, v9
	v_cvt_pk_bf16_f32 v3, v10, v11
	v_lshl_add_u64 v[4:5], v[4:5], 0, v[136:137]
	s_mov_b64 s[24:25], -1
	global_store_dwordx4 v[4:5], v[0:3], off
	s_cbranch_vccnz .LBB0_970
	s_andn2_b64 vcc, exec, s[4:5]
	s_cbranch_vccnz .LBB0_969
	s_barrier
	s_branch .LBB0_969
